# v21
# speedup vs baseline: 1.0173x; 1.0049x over previous
; #define LDA(dst, b, h)                                                                                               \
;   _Pragma("unroll") for (int m = 0; m < 4; ++m) _Pragma("unroll") for (int k = 0; k < 2; ++k) dst[m][k] =            \
;       *reinterpret_cast<const bf16x8*>(SA(b, h) + lds_byte(wr * 64 + m * 16 + fr, k * 32 + fq * 8))
; #define LDB(dst, b, h)                                                                                               \
;   _Pragma("unroll") for (int n = 0; n < 2; ++n) _Pragma("unroll") for (int k = 0; k < 2; ++k) dst[n][k] =            \
;       *reinterpret_cast<const bf16x8*>(SB(b, h) + lds_byte(wc * 32 + n * 16 + fr, k * 32 + fq * 8))
; #define WAIT_V(n) asm volatile("s_waitcnt vmcnt(" #n ")" ::: "memory")
; #define WAIT_L(n) asm volatile("s_waitcnt lgkmcnt(" #n ")" ::: "memory")
; #define BAR __builtin_amdgcn_s_barrier()
; #define SCHED __builtin_amdgcn_sched_barrier(0)
; template <int EPI>
; __device__ __forceinline__ void gemm_phase(const u16* __restrict__ A, const u16* __restrict__ Bt, const int K,
;                                            const int nN, char* shm, const EpiArgs& ea) {
;     ...
;     for (int t = 0; t < nt - 2; t += 2) {
;       LDB(B0, 0, 0); SCHED; LDA(At, 0, 0); STAGE(SA(1, 1), rA, brow + HALF, t + 1);
;       WAIT_V(10); WAIT_L(8); BAR; WAIT_L(0); MMA(0, 0, At, B0); BAR; SCHED;
;       LDB(B1, 0, 1); STAGE(SB(0, 0), rB, bcol, t + 2);
;       WAIT_V(10); BAR; WAIT_L(0); MMA(0, 1, At, B1); BAR;
;       LDA(At, 0, 1); STAGE(SA(0, 0), rA, brow, t + 2);
;       BAR; WAIT_L(0); MMA(1, 0, At, B0); BAR; SCHED;
;       STAGE(SB(0, 1), rB, bcol + HALF, t + 2);
;       WAIT_V(10); BAR; MMA(1, 1, At, B1); BAR;
;       LDB(B0, 1, 0); SCHED; LDA(At, 1, 0); STAGE(SA(0, 1), rA, brow + HALF, t + 2);
;       WAIT_V(10); WAIT_L(8); BAR; WAIT_L(0); MMA(0, 0, At, B0); BAR; SCHED;
;       LDB(B1, 1, 1); STAGE(SB(1, 0), rB, bcol, t + 3);
;       WAIT_V(10); BAR; WAIT_L(0); MMA(0, 1, At, B1); BAR;
;       LDA(At, 1, 1); STAGE(SA(1, 0), rA, brow, t + 3);
;       BAR; WAIT_L(0); MMA(1, 0, At, B0); BAR; SCHED;
;       STAGE(SB(1, 1), rB, bcol + HALF, t + 3);
;       WAIT_V(10); BAR; MMA(1, 1, At, B1); BAR;
;     }
.LBB0_172:
	ds_read_b128 v[142:145], v133
	ds_read_b128 v[146:149], v133 offset:1024
	ds_read_b128 v[150:153], v133 offset:2048
	ds_read_b128 v[154:157], v133 offset:3072
	s_add_i32 s73, s67, s72
	s_mov_b32 m0, s57
	s_add_i32 s6, s73, 0x4000
	ds_read_b128 v[162:165], v134
	ds_read_b128 v[166:169], v134 offset:1024
	ds_read_b128 v[170:173], v135
	ds_read_b128 v[176:179], v135 offset:1024
	ds_read_b128 v[180:183], v136
	ds_read_b128 v[184:187], v136 offset:1024
	ds_read_b128 v[188:191], v137
	ds_read_b128 v[192:195], v137 offset:1024
	buffer_load_dwordx4 v130, s[0:3], s6 offen lds
	s_add_i32 s6, s73, 0x6000
	s_mov_b32 m0, s58
	s_nop 0
	buffer_load_dwordx4 v130, s[0:3], s6 offen lds
	s_waitcnt vmcnt(10)
	s_waitcnt lgkmcnt(8)
	s_barrier
	s_setprio 1
	s_waitcnt lgkmcnt(7)
	v_mfma_f32_16x16x32_bf16 v[124:127], v[142:145], v[162:165], v[124:127]
	v_mfma_f32_16x16x32_bf16 v[120:123], v[150:153], v[162:165], v[120:123]
	s_waitcnt lgkmcnt(5)
	v_mfma_f32_16x16x32_bf16 v[116:119], v[142:145], v[170:173], v[116:119]
	v_mfma_f32_16x16x32_bf16 v[112:115], v[150:153], v[170:173], v[112:115]
	s_waitcnt lgkmcnt(3)
	v_mfma_f32_16x16x32_bf16 v[108:111], v[142:145], v[180:183], v[108:111]
	v_mfma_f32_16x16x32_bf16 v[104:107], v[150:153], v[180:183], v[104:107]
	s_waitcnt lgkmcnt(1)
	v_mfma_f32_16x16x32_bf16 v[100:103], v[142:145], v[188:191], v[100:103]
	v_mfma_f32_16x16x32_bf16 v[96:99], v[150:153], v[188:191], v[96:99]
	v_mfma_f32_16x16x32_bf16 v[124:127], v[146:149], v[166:169], v[124:127]
	v_mfma_f32_16x16x32_bf16 v[120:123], v[154:157], v[166:169], v[120:123]
	v_mfma_f32_16x16x32_bf16 v[116:119], v[146:149], v[176:179], v[116:119]
	v_mfma_f32_16x16x32_bf16 v[112:115], v[154:157], v[176:179], v[112:115]
	v_mfma_f32_16x16x32_bf16 v[108:111], v[146:149], v[184:187], v[108:111]
	v_mfma_f32_16x16x32_bf16 v[104:107], v[154:157], v[184:187], v[104:107]
	s_waitcnt lgkmcnt(0)
	v_mfma_f32_16x16x32_bf16 v[100:103], v[146:149], v[192:195], v[100:103]
	v_mfma_f32_16x16x32_bf16 v[96:99], v[154:157], v[192:195], v[96:99]
	s_setprio 0
	s_barrier
	s_add_i32 s74, s70, s72
	s_mov_b32 m0, s34
	s_add_i32 s75, s74, 0x8000
	s_mov_b32 s6, s2
	s_mov_b32 s7, s3
	ds_read_b128 v[196:199], v138
	ds_read_b128 v[200:203], v138 offset:1024
	ds_read_b128 v[204:207], v138 offset:2048
	ds_read_b128 v[208:211], v138 offset:3072
	buffer_load_dwordx4 v130, s[4:7], s75 offen lds
	s_add_i32 s75, s74, 0xa000
	s_mov_b32 m0, s35
	s_nop 0
	buffer_load_dwordx4 v130, s[4:7], s75 offen lds
	s_waitcnt vmcnt(10)
	s_barrier
	s_setprio 1
	s_waitcnt lgkmcnt(3)
	v_mfma_f32_16x16x32_bf16 v[92:95], v[196:199], v[162:165], v[92:95]
	s_waitcnt lgkmcnt(1)
	v_mfma_f32_16x16x32_bf16 v[88:91], v[204:207], v[162:165], v[88:91]
	v_mfma_f32_16x16x32_bf16 v[84:87], v[196:199], v[170:173], v[84:87]
	v_mfma_f32_16x16x32_bf16 v[80:83], v[204:207], v[170:173], v[80:83]
	v_mfma_f32_16x16x32_bf16 v[76:79], v[196:199], v[180:183], v[76:79]
	v_mfma_f32_16x16x32_bf16 v[72:75], v[204:207], v[180:183], v[72:75]
	v_mfma_f32_16x16x32_bf16 v[68:71], v[196:199], v[188:191], v[68:71]
	v_mfma_f32_16x16x32_bf16 v[64:67], v[204:207], v[188:191], v[64:67]
	v_mfma_f32_16x16x32_bf16 v[92:95], v[200:203], v[166:169], v[92:95]
	s_waitcnt lgkmcnt(0)
	v_mfma_f32_16x16x32_bf16 v[88:91], v[208:211], v[166:169], v[88:91]
	v_mfma_f32_16x16x32_bf16 v[84:87], v[200:203], v[176:179], v[84:87]
	v_mfma_f32_16x16x32_bf16 v[80:83], v[208:211], v[176:179], v[80:83]
	v_mfma_f32_16x16x32_bf16 v[76:79], v[200:203], v[184:187], v[76:79]
	v_mfma_f32_16x16x32_bf16 v[72:75], v[208:211], v[184:187], v[72:75]
	v_mfma_f32_16x16x32_bf16 v[68:71], v[200:203], v[192:195], v[68:71]
	v_mfma_f32_16x16x32_bf16 v[64:67], v[208:211], v[192:195], v[64:67]
	s_setprio 0
	s_add_i32 s75, s69, s72
	s_mov_b32 m0, s38
	s_add_i32 s78, s75, 0x8000
	s_barrier
	ds_read_b128 v[162:165], v134 offset:16384
	ds_read_b128 v[166:169], v134 offset:17408
	ds_read_b128 v[170:173], v135 offset:16384
	ds_read_b128 v[176:179], v135 offset:17408
	ds_read_b128 v[180:183], v136 offset:16384
	ds_read_b128 v[184:187], v136 offset:17408
	ds_read_b128 v[188:191], v137 offset:16384
	ds_read_b128 v[192:195], v137 offset:17408
	buffer_load_dwordx4 v130, s[0:3], s78 offen lds
	s_add_i32 s78, s75, 0xa000
	s_mov_b32 m0, s39
	s_nop 0
	buffer_load_dwordx4 v130, s[0:3], s78 offen lds
	s_barrier
	s_setprio 1
	s_waitcnt lgkmcnt(7)
	v_mfma_f32_16x16x32_bf16 v[60:63], v[142:145], v[162:165], v[60:63]
	v_mfma_f32_16x16x32_bf16 v[56:59], v[150:153], v[162:165], v[56:59]
	s_waitcnt lgkmcnt(5)
	v_mfma_f32_16x16x32_bf16 v[52:55], v[142:145], v[170:173], v[52:55]
	v_mfma_f32_16x16x32_bf16 v[48:51], v[150:153], v[170:173], v[48:51]
	s_waitcnt lgkmcnt(3)
	v_mfma_f32_16x16x32_bf16 v[44:47], v[142:145], v[180:183], v[44:47]
	v_mfma_f32_16x16x32_bf16 v[40:43], v[150:153], v[180:183], v[40:43]
	s_waitcnt lgkmcnt(1)
	v_mfma_f32_16x16x32_bf16 v[36:39], v[142:145], v[188:191], v[36:39]
	v_mfma_f32_16x16x32_bf16 v[32:35], v[150:153], v[188:191], v[32:35]
	v_mfma_f32_16x16x32_bf16 v[60:63], v[146:149], v[166:169], v[60:63]
	v_mfma_f32_16x16x32_bf16 v[56:59], v[154:157], v[166:169], v[56:59]
	v_mfma_f32_16x16x32_bf16 v[52:55], v[146:149], v[176:179], v[52:55]
	v_mfma_f32_16x16x32_bf16 v[48:51], v[154:157], v[176:179], v[48:51]
	v_mfma_f32_16x16x32_bf16 v[44:47], v[146:149], v[184:187], v[44:47]
	v_mfma_f32_16x16x32_bf16 v[40:43], v[154:157], v[184:187], v[40:43]
	s_waitcnt lgkmcnt(0)
	v_mfma_f32_16x16x32_bf16 v[36:39], v[146:149], v[192:195], v[36:39]
	v_mfma_f32_16x16x32_bf16 v[32:35], v[154:157], v[192:195], v[32:35]
	s_setprio 0
	s_barrier
; #define LDA(dst, b, h)                                                                                               \
;   _Pragma("unroll") for (int m = 0; m < 4; ++m) _Pragma("unroll") for (int k = 0; k < 2; ++k) dst[m][k] =            \
;       *reinterpret_cast<const bf16x8*>(SA(b, h) + lds_byte(wr * 64 + m * 16 + fr, k * 32 + fq * 8))
; #define LDB(dst, b, h)                                                                                               \
;   _Pragma("unroll") for (int n = 0; n < 2; ++n) _Pragma("unroll") for (int k = 0; k < 2; ++k) dst[n][k] =            \
;       *reinterpret_cast<const bf16x8*>(SB(b, h) + lds_byte(wc * 32 + n * 16 + fr, k * 32 + fq * 8))
; #define WAIT_V(n) asm volatile("s_waitcnt vmcnt(" #n ")" ::: "memory")
; #define WAIT_L(n) asm volatile("s_waitcnt lgkmcnt(" #n ")" ::: "memory")
; #define BAR __builtin_amdgcn_s_barrier()
; #define SCHED __builtin_amdgcn_sched_barrier(0)
; template <int EPI>
; __device__ __forceinline__ void gemm_phase(const u16* __restrict__ A, const u16* __restrict__ Bt, const int K,
;                                            const int nN, char* shm, const EpiArgs& ea) {
;     ...
;     for (int t = 0; t < nt - 2; t += 2) {
;       LDB(B0, 0, 0); SCHED; LDA(At, 0, 0); STAGE(SA(1, 1), rA, brow + HALF, t + 1);
;       WAIT_V(10); WAIT_L(8); BAR; WAIT_L(0); MMA(0, 0, At, B0); BAR; SCHED;
;       LDB(B1, 0, 1); STAGE(SB(0, 0), rB, bcol, t + 2);
;       WAIT_V(10); BAR; WAIT_L(0); MMA(0, 1, At, B1); BAR;
;       LDA(At, 0, 1); STAGE(SA(0, 0), rA, brow, t + 2);
;       BAR; WAIT_L(0); MMA(1, 0, At, B0); BAR; SCHED;
;       STAGE(SB(0, 1), rB, bcol + HALF, t + 2);
;       WAIT_V(10); BAR; MMA(1, 1, At, B1); BAR;
;       LDB(B0, 1, 0); SCHED; LDA(At, 1, 0); STAGE(SA(0, 1), rA, brow + HALF, t + 2);
;       WAIT_V(10); WAIT_L(8); BAR; WAIT_L(0); MMA(0, 0, At, B0); BAR; SCHED;
;       LDB(B1, 1, 1); STAGE(SB(1, 0), rB, bcol, t + 3);
;       WAIT_V(10); BAR; WAIT_L(0); MMA(0, 1, At, B1); BAR;
;       LDA(At, 1, 1); STAGE(SA(1, 0), rA, brow, t + 3);
;       BAR; WAIT_L(0); MMA(1, 0, At, B0); BAR; SCHED;
;       STAGE(SB(1, 1), rB, bcol + HALF, t + 3);
;       WAIT_V(10); BAR; MMA(1, 1, At, B1); BAR;
;     }
	s_add_i32 s78, s68, s72
	s_mov_b32 m0, s40
	s_add_i32 s79, s78, 0x8000
	buffer_load_dwordx4 v130, s[4:7], s79 offen lds
	s_add_i32 s79, s78, 0xa000
	s_mov_b32 m0, s41
	s_nop 0
	buffer_load_dwordx4 v130, s[4:7], s79 offen lds
	s_waitcnt vmcnt(10)
	s_barrier
	s_setprio 1
	v_mfma_f32_16x16x32_bf16 v[28:31], v[196:199], v[162:165], v[28:31]
	v_mfma_f32_16x16x32_bf16 v[24:27], v[204:207], v[162:165], v[24:27]
	v_mfma_f32_16x16x32_bf16 v[20:23], v[196:199], v[170:173], v[20:23]
	v_mfma_f32_16x16x32_bf16 v[16:19], v[204:207], v[170:173], v[16:19]
	v_mfma_f32_16x16x32_bf16 v[12:15], v[196:199], v[180:183], v[12:15]
	v_mfma_f32_16x16x32_bf16 v[8:11], v[204:207], v[180:183], v[8:11]
	v_mfma_f32_16x16x32_bf16 v[4:7], v[196:199], v[188:191], v[4:7]
	v_mfma_f32_16x16x32_bf16 v[0:3], v[204:207], v[188:191], v[0:3]
	v_mfma_f32_16x16x32_bf16 v[28:31], v[200:203], v[166:169], v[28:31]
	v_mfma_f32_16x16x32_bf16 v[24:27], v[208:211], v[166:169], v[24:27]
	v_mfma_f32_16x16x32_bf16 v[20:23], v[200:203], v[176:179], v[20:23]
	v_mfma_f32_16x16x32_bf16 v[16:19], v[208:211], v[176:179], v[16:19]
	v_mfma_f32_16x16x32_bf16 v[12:15], v[200:203], v[184:187], v[12:15]
	v_mfma_f32_16x16x32_bf16 v[8:11], v[208:211], v[184:187], v[8:11]
	v_mfma_f32_16x16x32_bf16 v[4:7], v[200:203], v[192:195], v[4:7]
	v_mfma_f32_16x16x32_bf16 v[0:3], v[208:211], v[192:195], v[0:3]
	s_setprio 0
	s_barrier
	ds_read_b128 v[142:145], v139
	ds_read_b128 v[146:149], v139 offset:1024
	ds_read_b128 v[150:153], v139 offset:2048
	ds_read_b128 v[154:157], v139 offset:3072
	s_mov_b32 m0, s42
	s_add_i32 s79, s73, 0x8000
	ds_read_b128 v[162:165], v134 offset:32768
	ds_read_b128 v[166:169], v134 offset:33792
	ds_read_b128 v[170:173], v135 offset:32768
	ds_read_b128 v[176:179], v135 offset:33792
	ds_read_b128 v[180:183], v136 offset:32768
	ds_read_b128 v[184:187], v136 offset:33792
	ds_read_b128 v[188:191], v137 offset:32768
	ds_read_b128 v[192:195], v137 offset:33792
	buffer_load_dwordx4 v130, s[0:3], s79 offen lds
	s_add_i32 s73, s73, 0xa000
	s_mov_b32 m0, s43
	s_nop 0
	buffer_load_dwordx4 v130, s[0:3], s73 offen lds
	s_waitcnt vmcnt(10)
	s_waitcnt lgkmcnt(8)
	s_barrier
	s_setprio 1
	s_waitcnt lgkmcnt(7)
	v_mfma_f32_16x16x32_bf16 v[124:127], v[142:145], v[162:165], v[124:127]
	v_mfma_f32_16x16x32_bf16 v[120:123], v[150:153], v[162:165], v[120:123]
	s_waitcnt lgkmcnt(5)
	v_mfma_f32_16x16x32_bf16 v[116:119], v[142:145], v[170:173], v[116:119]
	v_mfma_f32_16x16x32_bf16 v[112:115], v[150:153], v[170:173], v[112:115]
	s_waitcnt lgkmcnt(3)
	v_mfma_f32_16x16x32_bf16 v[108:111], v[142:145], v[180:183], v[108:111]
	v_mfma_f32_16x16x32_bf16 v[104:107], v[150:153], v[180:183], v[104:107]
	s_waitcnt lgkmcnt(1)
	v_mfma_f32_16x16x32_bf16 v[100:103], v[142:145], v[188:191], v[100:103]
	v_mfma_f32_16x16x32_bf16 v[96:99], v[150:153], v[188:191], v[96:99]
	v_mfma_f32_16x16x32_bf16 v[124:127], v[146:149], v[166:169], v[124:127]
	v_mfma_f32_16x16x32_bf16 v[120:123], v[154:157], v[166:169], v[120:123]
	v_mfma_f32_16x16x32_bf16 v[116:119], v[146:149], v[176:179], v[116:119]
	v_mfma_f32_16x16x32_bf16 v[112:115], v[154:157], v[176:179], v[112:115]
	v_mfma_f32_16x16x32_bf16 v[108:111], v[146:149], v[184:187], v[108:111]
	v_mfma_f32_16x16x32_bf16 v[104:107], v[154:157], v[184:187], v[104:107]
	s_waitcnt lgkmcnt(0)
	v_mfma_f32_16x16x32_bf16 v[100:103], v[146:149], v[192:195], v[100:103]
	v_mfma_f32_16x16x32_bf16 v[96:99], v[154:157], v[192:195], v[96:99]
	s_setprio 0
	s_barrier
	s_mov_b32 m0, s48
	s_add_i32 s73, s74, 0xc000
	ds_read_b128 v[196:199], v140
	ds_read_b128 v[200:203], v140 offset:1024
	ds_read_b128 v[204:207], v140 offset:2048
	ds_read_b128 v[208:211], v140 offset:3072
	buffer_load_dwordx4 v130, s[4:7], s73 offen lds
	s_add_i32 s74, s74, 0xe000
	s_mov_b32 m0, s49
	s_nop 0
	buffer_load_dwordx4 v130, s[4:7], s74 offen lds
	s_waitcnt vmcnt(10)
	s_barrier
	s_setprio 1
	s_waitcnt lgkmcnt(3)
	v_mfma_f32_16x16x32_bf16 v[92:95], v[196:199], v[162:165], v[92:95]
	s_waitcnt lgkmcnt(1)
	v_mfma_f32_16x16x32_bf16 v[88:91], v[204:207], v[162:165], v[88:91]
	v_mfma_f32_16x16x32_bf16 v[84:87], v[196:199], v[170:173], v[84:87]
	v_mfma_f32_16x16x32_bf16 v[80:83], v[204:207], v[170:173], v[80:83]
	v_mfma_f32_16x16x32_bf16 v[76:79], v[196:199], v[180:183], v[76:79]
	v_mfma_f32_16x16x32_bf16 v[72:75], v[204:207], v[180:183], v[72:75]
	v_mfma_f32_16x16x32_bf16 v[68:71], v[196:199], v[188:191], v[68:71]
	v_mfma_f32_16x16x32_bf16 v[64:67], v[204:207], v[188:191], v[64:67]
	v_mfma_f32_16x16x32_bf16 v[92:95], v[200:203], v[166:169], v[92:95]
	s_waitcnt lgkmcnt(0)
	v_mfma_f32_16x16x32_bf16 v[88:91], v[208:211], v[166:169], v[88:91]
	v_mfma_f32_16x16x32_bf16 v[84:87], v[200:203], v[176:179], v[84:87]
	v_mfma_f32_16x16x32_bf16 v[80:83], v[208:211], v[176:179], v[80:83]
	v_mfma_f32_16x16x32_bf16 v[76:79], v[200:203], v[184:187], v[76:79]
	v_mfma_f32_16x16x32_bf16 v[72:75], v[208:211], v[184:187], v[72:75]
	v_mfma_f32_16x16x32_bf16 v[68:71], v[200:203], v[192:195], v[68:71]
	v_mfma_f32_16x16x32_bf16 v[64:67], v[208:211], v[192:195], v[64:67]
	s_setprio 0
	s_mov_b32 m0, s52
	s_add_i32 s73, s75, 0xc000
	s_barrier
	ds_read_b128 v[162:165], v134 offset:49152
	ds_read_b128 v[166:169], v134 offset:50176
	ds_read_b128 v[170:173], v135 offset:49152
	ds_read_b128 v[176:179], v135 offset:50176
	ds_read_b128 v[180:183], v136 offset:49152
	ds_read_b128 v[184:187], v136 offset:50176
	ds_read_b128 v[188:191], v137 offset:49152
	ds_read_b128 v[192:195], v137 offset:50176
	buffer_load_dwordx4 v130, s[0:3], s73 offen lds
	s_add_i32 s75, s75, 0xe000
	s_mov_b32 m0, s53
	s_nop 0
	buffer_load_dwordx4 v130, s[0:3], s75 offen lds
	s_barrier
; #define LDA(dst, b, h)                                                                                               \
;   _Pragma("unroll") for (int m = 0; m < 4; ++m) _Pragma("unroll") for (int k = 0; k < 2; ++k) dst[m][k] =            \
;       *reinterpret_cast<const bf16x8*>(SA(b, h) + lds_byte(wr * 64 + m * 16 + fr, k * 32 + fq * 8))
; #define LDB(dst, b, h)                                                                                               \
;   _Pragma("unroll") for (int n = 0; n < 2; ++n) _Pragma("unroll") for (int k = 0; k < 2; ++k) dst[n][k] =            \
;       *reinterpret_cast<const bf16x8*>(SB(b, h) + lds_byte(wc * 32 + n * 16 + fr, k * 32 + fq * 8))
; #define WAIT_V(n) asm volatile("s_waitcnt vmcnt(" #n ")" ::: "memory")
; #define BAR __builtin_amdgcn_s_barrier()
; template <int EPI>
; __device__ __forceinline__ void gemm_phase(const u16* __restrict__ A, const u16* __restrict__ Bt, const int K,
;                                            const int nN, char* shm, const EpiArgs& ea) {
;     ...
;     for (int t = 0; t < nt - 2; t += 2) {
;       LDB(B0, 0, 0); SCHED; LDA(At, 0, 0); STAGE(SA(1, 1), rA, brow + HALF, t + 1);
;       WAIT_V(10); WAIT_L(8); BAR; WAIT_L(0); MMA(0, 0, At, B0); BAR; SCHED;
;       LDB(B1, 0, 1); STAGE(SB(0, 0), rB, bcol, t + 2);
;       WAIT_V(10); BAR; WAIT_L(0); MMA(0, 1, At, B1); BAR;
;       LDA(At, 0, 1); STAGE(SA(0, 0), rA, brow, t + 2);
;       BAR; WAIT_L(0); MMA(1, 0, At, B0); BAR; SCHED;
;       STAGE(SB(0, 1), rB, bcol + HALF, t + 2);
;       WAIT_V(10); BAR; MMA(1, 1, At, B1); BAR;
;       LDB(B0, 1, 0); SCHED; LDA(At, 1, 0); STAGE(SA(0, 1), rA, brow + HALF, t + 2);
;       WAIT_V(10); WAIT_L(8); BAR; WAIT_L(0); MMA(0, 0, At, B0); BAR; SCHED;
;       LDB(B1, 1, 1); STAGE(SB(1, 0), rB, bcol, t + 3);
;       WAIT_V(10); BAR; WAIT_L(0); MMA(0, 1, At, B1); BAR;
;       LDA(At, 1, 1); STAGE(SA(1, 0), rA, brow, t + 3);
;       BAR; WAIT_L(0); MMA(1, 0, At, B0); BAR; SCHED;
;       STAGE(SB(1, 1), rB, bcol + HALF, t + 3);
;       WAIT_V(10); BAR; MMA(1, 1, At, B1); BAR;
;     }
;     ...
;     {
;       LDB(B0, 0, 0); LDA(At, 0, 0); STAGE(SA(1, 1), rA, brow + HALF, nt - 1);
;       WAIT_V(10); BAR; WAIT_L(0); MMA(0, 0, At, B0); BAR;
;       LDB(B1, 0, 1); WAIT_V(8); BAR; WAIT_L(0); MMA(0, 1, At, B1); BAR;
;       LDA(At, 0, 1); WAIT_V(4); BAR; WAIT_L(0); MMA(1, 0, At, B0); MMA(1, 1, At, B1); BAR;
	s_setprio 1
	s_waitcnt lgkmcnt(7)
	v_mfma_f32_16x16x32_bf16 v[60:63], v[142:145], v[162:165], v[60:63]
	v_mfma_f32_16x16x32_bf16 v[56:59], v[150:153], v[162:165], v[56:59]
	s_waitcnt lgkmcnt(5)
	v_mfma_f32_16x16x32_bf16 v[52:55], v[142:145], v[170:173], v[52:55]
	v_mfma_f32_16x16x32_bf16 v[48:51], v[150:153], v[170:173], v[48:51]
	s_waitcnt lgkmcnt(3)
	v_mfma_f32_16x16x32_bf16 v[44:47], v[142:145], v[180:183], v[44:47]
	v_mfma_f32_16x16x32_bf16 v[40:43], v[150:153], v[180:183], v[40:43]
	s_waitcnt lgkmcnt(1)
	v_mfma_f32_16x16x32_bf16 v[36:39], v[142:145], v[188:191], v[36:39]
	v_mfma_f32_16x16x32_bf16 v[32:35], v[150:153], v[188:191], v[32:35]
	v_mfma_f32_16x16x32_bf16 v[60:63], v[146:149], v[166:169], v[60:63]
	v_mfma_f32_16x16x32_bf16 v[56:59], v[154:157], v[166:169], v[56:59]
	v_mfma_f32_16x16x32_bf16 v[52:55], v[146:149], v[176:179], v[52:55]
	v_mfma_f32_16x16x32_bf16 v[48:51], v[154:157], v[176:179], v[48:51]
	v_mfma_f32_16x16x32_bf16 v[44:47], v[146:149], v[184:187], v[44:47]
	v_mfma_f32_16x16x32_bf16 v[40:43], v[154:157], v[184:187], v[40:43]
	s_waitcnt lgkmcnt(0)
	v_mfma_f32_16x16x32_bf16 v[36:39], v[146:149], v[192:195], v[36:39]
	v_mfma_f32_16x16x32_bf16 v[32:35], v[154:157], v[192:195], v[32:35]
	s_setprio 0
	s_barrier
	s_mov_b32 m0, s54
	s_add_i32 s73, s78, 0xc000
	buffer_load_dwordx4 v130, s[4:7], s73 offen lds
	s_add_i32 s78, s78, 0xe000
	s_mov_b32 m0, s55
	s_nop 0
	buffer_load_dwordx4 v130, s[4:7], s78 offen lds
	s_waitcnt vmcnt(10)
	s_barrier
	s_setprio 1
	v_mfma_f32_16x16x32_bf16 v[28:31], v[196:199], v[162:165], v[28:31]
	v_mfma_f32_16x16x32_bf16 v[24:27], v[204:207], v[162:165], v[24:27]
	v_mfma_f32_16x16x32_bf16 v[20:23], v[196:199], v[170:173], v[20:23]
	v_mfma_f32_16x16x32_bf16 v[16:19], v[204:207], v[170:173], v[16:19]
	v_mfma_f32_16x16x32_bf16 v[12:15], v[196:199], v[180:183], v[12:15]
	v_mfma_f32_16x16x32_bf16 v[8:11], v[204:207], v[180:183], v[8:11]
	v_mfma_f32_16x16x32_bf16 v[4:7], v[196:199], v[188:191], v[4:7]
	v_mfma_f32_16x16x32_bf16 v[0:3], v[204:207], v[188:191], v[0:3]
	v_mfma_f32_16x16x32_bf16 v[28:31], v[200:203], v[166:169], v[28:31]
	v_mfma_f32_16x16x32_bf16 v[24:27], v[208:211], v[166:169], v[24:27]
	v_mfma_f32_16x16x32_bf16 v[20:23], v[200:203], v[176:179], v[20:23]
	v_mfma_f32_16x16x32_bf16 v[16:19], v[208:211], v[176:179], v[16:19]
	v_mfma_f32_16x16x32_bf16 v[12:15], v[200:203], v[184:187], v[12:15]
	v_mfma_f32_16x16x32_bf16 v[8:11], v[208:211], v[184:187], v[8:11]
	v_mfma_f32_16x16x32_bf16 v[4:7], v[200:203], v[192:195], v[4:7]
	v_mfma_f32_16x16x32_bf16 v[0:3], v[208:211], v[192:195], v[0:3]
	s_setprio 0
	s_add_i32 s71, s71, 2
	s_add_i32 s72, s72, 0x8000
	s_cmp_lt_u32 s71, 28
	s_barrier
	s_cbranch_scc1 .LBB0_172
	s_mov_b32 m0, s57
	s_add_i32 s6, s67, 0x7c000
	ds_read_b128 v[142:145], v133
	ds_read_b128 v[146:149], v133 offset:1024
	ds_read_b128 v[150:153], v133 offset:2048
	ds_read_b128 v[154:157], v133 offset:3072
	ds_read_b128 v[162:165], v134
	ds_read_b128 v[166:169], v134 offset:1024
	ds_read_b128 v[170:173], v135
	ds_read_b128 v[176:179], v135 offset:1024
	ds_read_b128 v[180:183], v136
	ds_read_b128 v[184:187], v136 offset:1024
	ds_read_b128 v[188:191], v137
	ds_read_b128 v[192:195], v137 offset:1024
	buffer_load_dwordx4 v130, s[0:3], s6 offen lds
	s_add_i32 s67, s67, 0x7e000
	s_mov_b32 m0, s58
	s_nop 0
	buffer_load_dwordx4 v130, s[0:3], s67 offen lds
	s_waitcnt vmcnt(10)
	s_barrier
	s_setprio 1
	s_waitcnt lgkmcnt(7)
	v_mfma_f32_16x16x32_bf16 v[124:127], v[142:145], v[162:165], v[124:127]
	v_mfma_f32_16x16x32_bf16 v[120:123], v[150:153], v[162:165], v[120:123]
	s_waitcnt lgkmcnt(5)
	v_mfma_f32_16x16x32_bf16 v[116:119], v[142:145], v[170:173], v[116:119]
	v_mfma_f32_16x16x32_bf16 v[112:115], v[150:153], v[170:173], v[112:115]
	s_waitcnt lgkmcnt(3)
	v_mfma_f32_16x16x32_bf16 v[108:111], v[142:145], v[180:183], v[108:111]
	v_mfma_f32_16x16x32_bf16 v[104:107], v[150:153], v[180:183], v[104:107]
	s_waitcnt lgkmcnt(1)
	v_mfma_f32_16x16x32_bf16 v[100:103], v[142:145], v[188:191], v[100:103]
	v_mfma_f32_16x16x32_bf16 v[96:99], v[150:153], v[188:191], v[96:99]
	v_mfma_f32_16x16x32_bf16 v[124:127], v[146:149], v[166:169], v[124:127]
	v_mfma_f32_16x16x32_bf16 v[120:123], v[154:157], v[166:169], v[120:123]
	v_mfma_f32_16x16x32_bf16 v[116:119], v[146:149], v[176:179], v[116:119]
	v_mfma_f32_16x16x32_bf16 v[112:115], v[154:157], v[176:179], v[112:115]
	v_mfma_f32_16x16x32_bf16 v[108:111], v[146:149], v[184:187], v[108:111]
	v_mfma_f32_16x16x32_bf16 v[104:107], v[154:157], v[184:187], v[104:107]
	s_waitcnt lgkmcnt(0)
	v_mfma_f32_16x16x32_bf16 v[100:103], v[146:149], v[192:195], v[100:103]
	v_mfma_f32_16x16x32_bf16 v[96:99], v[154:157], v[192:195], v[96:99]
	s_setprio 0
	s_barrier
	ds_read_b128 v[196:199], v138
	ds_read_b128 v[200:203], v138 offset:1024
	ds_read_b128 v[204:207], v138 offset:2048
	ds_read_b128 v[208:211], v138 offset:3072
	s_waitcnt vmcnt(8)
	s_barrier
	s_setprio 1
	s_waitcnt lgkmcnt(3)
	v_mfma_f32_16x16x32_bf16 v[76:79], v[196:199], v[180:183], v[76:79]
	s_waitcnt lgkmcnt(1)
	v_mfma_f32_16x16x32_bf16 v[72:75], v[204:207], v[180:183], v[72:75]
	v_mfma_f32_16x16x32_bf16 v[68:71], v[196:199], v[188:191], v[68:71]
	v_mfma_f32_16x16x32_bf16 v[64:67], v[204:207], v[188:191], v[64:67]
	v_mfma_f32_16x16x32_bf16 v[92:95], v[196:199], v[162:165], v[92:95]
	v_mfma_f32_16x16x32_bf16 v[88:91], v[204:207], v[162:165], v[88:91]
	v_mfma_f32_16x16x32_bf16 v[84:87], v[196:199], v[170:173], v[84:87]
	v_mfma_f32_16x16x32_bf16 v[80:83], v[204:207], v[170:173], v[80:83]
	v_mfma_f32_16x16x32_bf16 v[76:79], v[200:203], v[184:187], v[76:79]
	s_waitcnt lgkmcnt(0)
	v_mfma_f32_16x16x32_bf16 v[72:75], v[208:211], v[184:187], v[72:75]
	v_mfma_f32_16x16x32_bf16 v[68:71], v[200:203], v[192:195], v[68:71]
	v_mfma_f32_16x16x32_bf16 v[64:67], v[208:211], v[192:195], v[64:67]
	v_mfma_f32_16x16x32_bf16 v[212:215], v[200:203], v[166:169], v[92:95]
	v_mfma_f32_16x16x32_bf16 v[162:165], v[208:211], v[166:169], v[88:91]
	v_mfma_f32_16x16x32_bf16 v[166:169], v[200:203], v[176:179], v[84:87]
	v_mfma_f32_16x16x32_bf16 v[170:173], v[208:211], v[176:179], v[80:83]
	s_setprio 0
	s_barrier
; #define LDA(dst, b, h)                                                                                               \
;   _Pragma("unroll") for (int m = 0; m < 4; ++m) _Pragma("unroll") for (int k = 0; k < 2; ++k) dst[m][k] =            \
;       *reinterpret_cast<const bf16x8*>(SA(b, h) + lds_byte(wr * 64 + m * 16 + fr, k * 32 + fq * 8))
; #define LDB(dst, b, h)                                                                                               \
;   _Pragma("unroll") for (int n = 0; n < 2; ++n) _Pragma("unroll") for (int k = 0; k < 2; ++k) dst[n][k] =            \
;       *reinterpret_cast<const bf16x8*>(SB(b, h) + lds_byte(wc * 32 + n * 16 + fr, k * 32 + fq * 8))
; #define WAIT_V(n) asm volatile("s_waitcnt vmcnt(" #n ")" ::: "memory")
; #define WAIT_L(n) asm volatile("s_waitcnt lgkmcnt(" #n ")" ::: "memory")
; #define BAR __builtin_amdgcn_s_barrier()
; template <int EPI>
; __device__ __forceinline__ void gemm_phase(const u16* __restrict__ A, const u16* __restrict__ Bt, const int K,
;                                            const int nN, char* shm, const EpiArgs& ea) {
;     ...
;     {
;       LDB(B0, 0, 0); LDA(At, 0, 0); STAGE(SA(1, 1), rA, brow + HALF, nt - 1);
;       WAIT_V(10); BAR; WAIT_L(0); MMA(0, 0, At, B0); BAR;
;       LDB(B1, 0, 1); WAIT_V(8); BAR; WAIT_L(0); MMA(0, 1, At, B1); BAR;
;       LDA(At, 0, 1); WAIT_V(4); BAR; WAIT_L(0); MMA(1, 0, At, B0); MMA(1, 1, At, B1); BAR;
;     }
;     {
;       LDB(B0, 1, 0); LDA(At, 1, 0); WAIT_V(2); BAR; WAIT_L(0); MMA(0, 0, At, B0); BAR;
;       LDB(B1, 1, 1); WAIT_V(0); BAR; WAIT_L(0); MMA(0, 1, At, B1); BAR;
;       LDA(At, 1, 1); BAR; WAIT_L(0); MMA(1, 0, At, B0); MMA(1, 1, At, B1); BAR;
	s_nop 0
	ds_read_b128 v[80:83], v134 offset:16384
	ds_read_b128 v[84:87], v134 offset:17408
	ds_read_b128 v[88:91], v135 offset:16384
	ds_read_b128 v[92:95], v135 offset:17408
	ds_read_b128 v[176:179], v136 offset:16384
	ds_read_b128 v[180:183], v136 offset:17408
	ds_read_b128 v[184:187], v137 offset:16384
	ds_read_b128 v[188:191], v137 offset:17408
	s_waitcnt vmcnt(4)
	s_barrier
	s_setprio 1
	s_waitcnt lgkmcnt(7)
	v_mfma_f32_16x16x32_bf16 v[60:63], v[142:145], v[80:83], v[60:63]
	v_mfma_f32_16x16x32_bf16 v[56:59], v[150:153], v[80:83], v[56:59]
	s_waitcnt lgkmcnt(5)
	v_mfma_f32_16x16x32_bf16 v[52:55], v[142:145], v[88:91], v[52:55]
	v_mfma_f32_16x16x32_bf16 v[48:51], v[150:153], v[88:91], v[48:51]
	s_waitcnt lgkmcnt(3)
	v_mfma_f32_16x16x32_bf16 v[44:47], v[142:145], v[176:179], v[44:47]
	v_mfma_f32_16x16x32_bf16 v[40:43], v[150:153], v[176:179], v[40:43]
	s_waitcnt lgkmcnt(1)
	v_mfma_f32_16x16x32_bf16 v[36:39], v[142:145], v[184:187], v[36:39]
	v_mfma_f32_16x16x32_bf16 v[32:35], v[150:153], v[184:187], v[32:35]
	v_mfma_f32_16x16x32_bf16 v[60:63], v[146:149], v[84:87], v[60:63]
	v_mfma_f32_16x16x32_bf16 v[56:59], v[154:157], v[84:87], v[56:59]
	v_mfma_f32_16x16x32_bf16 v[52:55], v[146:149], v[92:95], v[52:55]
	v_mfma_f32_16x16x32_bf16 v[48:51], v[154:157], v[92:95], v[48:51]
	v_mfma_f32_16x16x32_bf16 v[44:47], v[146:149], v[180:183], v[44:47]
	v_mfma_f32_16x16x32_bf16 v[40:43], v[154:157], v[180:183], v[40:43]
	s_waitcnt lgkmcnt(0)
	v_mfma_f32_16x16x32_bf16 v[36:39], v[146:149], v[188:191], v[36:39]
	v_mfma_f32_16x16x32_bf16 v[32:35], v[154:157], v[188:191], v[32:35]
	s_setprio 0
	s_setprio 1
	v_mfma_f32_16x16x32_bf16 v[12:15], v[196:199], v[176:179], v[12:15]
	v_mfma_f32_16x16x32_bf16 v[8:11], v[204:207], v[176:179], v[8:11]
	v_mfma_f32_16x16x32_bf16 v[4:7], v[196:199], v[184:187], v[4:7]
	v_mfma_f32_16x16x32_bf16 v[0:3], v[204:207], v[184:187], v[0:3]
	v_mfma_f32_16x16x32_bf16 v[28:31], v[196:199], v[80:83], v[28:31]
	v_mfma_f32_16x16x32_bf16 v[24:27], v[204:207], v[80:83], v[24:27]
	v_mfma_f32_16x16x32_bf16 v[20:23], v[196:199], v[88:91], v[20:23]
	v_mfma_f32_16x16x32_bf16 v[16:19], v[204:207], v[88:91], v[16:19]
	v_mfma_f32_16x16x32_bf16 v[12:15], v[200:203], v[180:183], v[12:15]
	v_mfma_f32_16x16x32_bf16 v[8:11], v[208:211], v[180:183], v[8:11]
	v_mfma_f32_16x16x32_bf16 v[4:7], v[200:203], v[188:191], v[4:7]
	v_mfma_f32_16x16x32_bf16 v[0:3], v[208:211], v[188:191], v[0:3]
	v_mfma_f32_16x16x32_bf16 v[142:145], v[200:203], v[84:87], v[28:31]
	v_mfma_f32_16x16x32_bf16 v[146:149], v[208:211], v[84:87], v[24:27]
	v_mfma_f32_16x16x32_bf16 v[150:153], v[200:203], v[92:95], v[20:23]
	v_mfma_f32_16x16x32_bf16 v[154:157], v[208:211], v[92:95], v[16:19]
	s_setprio 0
	s_barrier
	s_nop 0
	ds_read_b128 v[16:19], v139
	ds_read_b128 v[20:23], v139 offset:1024
	ds_read_b128 v[176:179], v139 offset:2048
	ds_read_b128 v[180:183], v139 offset:3072
	ds_read_b128 v[24:27], v134 offset:32768
	ds_read_b128 v[28:31], v134 offset:33792
	ds_read_b128 v[184:187], v135 offset:32768
	ds_read_b128 v[188:191], v135 offset:33792
	ds_read_b128 v[192:195], v136 offset:32768
	ds_read_b128 v[196:199], v136 offset:33792
	ds_read_b128 v[200:203], v137 offset:32768
	ds_read_b128 v[204:207], v137 offset:33792
	s_waitcnt vmcnt(2)
	s_barrier
	s_setprio 1
	s_waitcnt lgkmcnt(7)
	v_mfma_f32_16x16x32_bf16 v[80:83], v[16:19], v[24:27], v[124:127]
	s_waitcnt lgkmcnt(6)
	v_mfma_f32_16x16x32_bf16 v[124:127], v[20:23], v[28:31], v[80:83]
	v_mfma_f32_16x16x32_bf16 v[80:83], v[176:179], v[24:27], v[120:123]
	v_mfma_f32_16x16x32_bf16 v[120:123], v[180:183], v[28:31], v[80:83]
	s_waitcnt lgkmcnt(5)
	v_mfma_f32_16x16x32_bf16 v[80:83], v[16:19], v[184:187], v[116:119]
	s_waitcnt lgkmcnt(4)
	v_mfma_f32_16x16x32_bf16 v[116:119], v[20:23], v[188:191], v[80:83]
	v_mfma_f32_16x16x32_bf16 v[80:83], v[176:179], v[184:187], v[112:115]
	v_mfma_f32_16x16x32_bf16 v[112:115], v[180:183], v[188:191], v[80:83]
	s_waitcnt lgkmcnt(3)
	v_mfma_f32_16x16x32_bf16 v[80:83], v[16:19], v[192:195], v[108:111]
	s_waitcnt lgkmcnt(2)
	v_mfma_f32_16x16x32_bf16 v[92:95], v[20:23], v[196:199], v[80:83]
	v_mfma_f32_16x16x32_bf16 v[80:83], v[176:179], v[192:195], v[104:107]
	v_mfma_f32_16x16x32_bf16 v[88:91], v[180:183], v[196:199], v[80:83]
	s_waitcnt lgkmcnt(1)
	v_mfma_f32_16x16x32_bf16 v[80:83], v[16:19], v[200:203], v[100:103]
	s_waitcnt lgkmcnt(0)
	v_mfma_f32_16x16x32_bf16 v[84:87], v[20:23], v[204:207], v[80:83]
	v_mfma_f32_16x16x32_bf16 v[80:83], v[176:179], v[200:203], v[96:99]
	v_mfma_f32_16x16x32_bf16 v[80:83], v[180:183], v[204:207], v[80:83]
	s_setprio 0
	s_barrier
; #define LDA(dst, b, h)                                                                                               \
;   _Pragma("unroll") for (int m = 0; m < 4; ++m) _Pragma("unroll") for (int k = 0; k < 2; ++k) dst[m][k] =            \
;       *reinterpret_cast<const bf16x8*>(SA(b, h) + lds_byte(wr * 64 + m * 16 + fr, k * 32 + fq * 8))
; #define LDB(dst, b, h)                                                                                               \
;   _Pragma("unroll") for (int n = 0; n < 2; ++n) _Pragma("unroll") for (int k = 0; k < 2; ++k) dst[n][k] =            \
;       *reinterpret_cast<const bf16x8*>(SB(b, h) + lds_byte(wc * 32 + n * 16 + fr, k * 32 + fq * 8))
; #define WAIT_V(n) asm volatile("s_waitcnt vmcnt(" #n ")" ::: "memory")
; #define WAIT_L(n) asm volatile("s_waitcnt lgkmcnt(" #n ")" ::: "memory")
; #define BAR __builtin_amdgcn_s_barrier()
; template <int EPI>
; __device__ __forceinline__ void gemm_phase(const u16* __restrict__ A, const u16* __restrict__ Bt, const int K,
;                                            const int nN, char* shm, const EpiArgs& ea) {
;     ...
;       LDA(At, 0, 1); WAIT_V(4); BAR; WAIT_L(0); MMA(1, 0, At, B0); MMA(1, 1, At, B1); BAR;
;     }
;     {
;       LDB(B0, 1, 0); LDA(At, 1, 0); WAIT_V(2); BAR; WAIT_L(0); MMA(0, 0, At, B0); BAR;
;       LDB(B1, 1, 1); WAIT_V(0); BAR; WAIT_L(0); MMA(0, 1, At, B1); BAR;
;       LDA(At, 1, 1); BAR; WAIT_L(0); MMA(1, 0, At, B0); MMA(1, 1, At, B1); BAR;
;     }
;     if (wr == 0) BAR;
	ds_read_b128 v[208:211], v140
	ds_read_b128 v[216:219], v140 offset:1024
	ds_read_b128 v[220:223], v140 offset:2048
	ds_read_b128 v[224:227], v140 offset:3072
	s_waitcnt vmcnt(0)
	s_barrier
	s_setprio 1
	s_waitcnt lgkmcnt(3)
	v_mfma_f32_16x16x32_bf16 v[96:99], v[208:211], v[24:27], v[212:215]
	s_waitcnt lgkmcnt(1)
	v_mfma_f32_16x16x32_bf16 v[24:27], v[220:223], v[24:27], v[162:165]
	s_waitcnt lgkmcnt(0)
	v_mfma_f32_16x16x32_bf16 v[104:107], v[224:227], v[28:31], v[24:27]
	v_mfma_f32_16x16x32_bf16 v[24:27], v[208:211], v[184:187], v[166:169]
	v_mfma_f32_16x16x32_bf16 v[100:103], v[216:219], v[188:191], v[24:27]
	v_mfma_f32_16x16x32_bf16 v[24:27], v[220:223], v[184:187], v[170:173]
	v_mfma_f32_16x16x32_bf16 v[108:111], v[216:219], v[28:31], v[96:99]
	v_mfma_f32_16x16x32_bf16 v[96:99], v[224:227], v[188:191], v[24:27]
	v_mfma_f32_16x16x32_bf16 v[24:27], v[208:211], v[192:195], v[76:79]
	v_mfma_f32_16x16x32_bf16 v[76:79], v[216:219], v[196:199], v[24:27]
	v_mfma_f32_16x16x32_bf16 v[24:27], v[220:223], v[192:195], v[72:75]
	v_mfma_f32_16x16x32_bf16 v[72:75], v[224:227], v[196:199], v[24:27]
	v_mfma_f32_16x16x32_bf16 v[24:27], v[208:211], v[200:203], v[68:71]
	v_mfma_f32_16x16x32_bf16 v[68:71], v[216:219], v[204:207], v[24:27]
	v_mfma_f32_16x16x32_bf16 v[24:27], v[220:223], v[200:203], v[64:67]
	v_mfma_f32_16x16x32_bf16 v[64:67], v[224:227], v[204:207], v[24:27]
	s_setprio 0
	s_barrier
	ds_read_b128 v[162:165], v134 offset:49152
	ds_read_b128 v[166:169], v134 offset:50176
	ds_read_b128 v[170:173], v135 offset:49152
	ds_read_b128 v[184:187], v135 offset:50176
	ds_read_b128 v[188:191], v136 offset:49152
	ds_read_b128 v[192:195], v136 offset:50176
	ds_read_b128 v[196:199], v137 offset:49152
	ds_read_b128 v[200:203], v137 offset:50176
	s_barrier
	s_setprio 1
	s_waitcnt lgkmcnt(7)
	v_mfma_f32_16x16x32_bf16 v[24:27], v[16:19], v[162:165], v[60:63]
	s_waitcnt lgkmcnt(6)
	v_mfma_f32_16x16x32_bf16 v[60:63], v[20:23], v[166:169], v[24:27]
	v_mfma_f32_16x16x32_bf16 v[24:27], v[176:179], v[162:165], v[56:59]
	v_mfma_f32_16x16x32_bf16 v[56:59], v[180:183], v[166:169], v[24:27]
	s_waitcnt lgkmcnt(5)
	v_mfma_f32_16x16x32_bf16 v[24:27], v[16:19], v[170:173], v[52:55]
	s_waitcnt lgkmcnt(4)
	v_mfma_f32_16x16x32_bf16 v[52:55], v[20:23], v[184:187], v[24:27]
	v_mfma_f32_16x16x32_bf16 v[24:27], v[176:179], v[170:173], v[48:51]
	v_mfma_f32_16x16x32_bf16 v[48:51], v[180:183], v[184:187], v[24:27]
	s_waitcnt lgkmcnt(3)
	v_mfma_f32_16x16x32_bf16 v[24:27], v[16:19], v[188:191], v[44:47]
	s_waitcnt lgkmcnt(1)
	v_mfma_f32_16x16x32_bf16 v[16:19], v[16:19], v[196:199], v[36:39]
	v_mfma_f32_16x16x32_bf16 v[28:31], v[20:23], v[192:195], v[24:27]
	v_mfma_f32_16x16x32_bf16 v[24:27], v[176:179], v[188:191], v[40:43]
	s_waitcnt lgkmcnt(0)
	v_mfma_f32_16x16x32_bf16 v[20:23], v[20:23], v[200:203], v[16:19]
	v_mfma_f32_16x16x32_bf16 v[16:19], v[176:179], v[196:199], v[32:35]
	v_mfma_f32_16x16x32_bf16 v[24:27], v[180:183], v[192:195], v[24:27]
	v_mfma_f32_16x16x32_bf16 v[16:19], v[180:183], v[200:203], v[16:19]
	s_setprio 0
	s_setprio 1
	v_mfma_f32_16x16x32_bf16 v[32:35], v[208:211], v[162:165], v[142:145]
	v_mfma_f32_16x16x32_bf16 v[44:47], v[216:219], v[166:169], v[32:35]
	v_mfma_f32_16x16x32_bf16 v[32:35], v[220:223], v[162:165], v[146:149]
	v_mfma_f32_16x16x32_bf16 v[40:43], v[224:227], v[166:169], v[32:35]
	v_mfma_f32_16x16x32_bf16 v[32:35], v[208:211], v[170:173], v[150:153]
	v_mfma_f32_16x16x32_bf16 v[36:39], v[216:219], v[184:187], v[32:35]
	v_mfma_f32_16x16x32_bf16 v[32:35], v[220:223], v[170:173], v[154:157]
	v_mfma_f32_16x16x32_bf16 v[12:15], v[208:211], v[188:191], v[12:15]
	v_mfma_f32_16x16x32_bf16 v[8:11], v[220:223], v[188:191], v[8:11]
	v_mfma_f32_16x16x32_bf16 v[4:7], v[208:211], v[196:199], v[4:7]
	v_mfma_f32_16x16x32_bf16 v[0:3], v[220:223], v[196:199], v[0:3]
	v_mfma_f32_16x16x32_bf16 v[32:35], v[224:227], v[184:187], v[32:35]
	v_mfma_f32_16x16x32_bf16 v[12:15], v[216:219], v[192:195], v[12:15]
	v_mfma_f32_16x16x32_bf16 v[8:11], v[224:227], v[192:195], v[8:11]
	v_mfma_f32_16x16x32_bf16 v[4:7], v[216:219], v[200:203], v[4:7]
	v_mfma_f32_16x16x32_bf16 v[0:3], v[224:227], v[200:203], v[0:3]
	s_setprio 0
	s_andn2_b64 vcc, exec, s[26:27]
	s_barrier
	s_cbranch_vccnz .LBB0_175
	s_barrier

; #define LDA(dst, b, h)                                                                                               \
;   _Pragma("unroll") for (int m = 0; m < 4; ++m) _Pragma("unroll") for (int k = 0; k < 2; ++k) dst[m][k] =            \
;       *reinterpret_cast<const bf16x8*>(SA(b, h) + lds_byte(wr * 64 + m * 16 + fr, k * 32 + fq * 8))
; #define LDB(dst, b, h)                                                                                               \
;   _Pragma("unroll") for (int n = 0; n < 2; ++n) _Pragma("unroll") for (int k = 0; k < 2; ++k) dst[n][k] =            \
;       *reinterpret_cast<const bf16x8*>(SB(b, h) + lds_byte(wc * 32 + n * 16 + fr, k * 32 + fq * 8))
; #define WAIT_V(n) asm volatile("s_waitcnt vmcnt(" #n ")" ::: "memory")
; #define WAIT_L(n) asm volatile("s_waitcnt lgkmcnt(" #n ")" ::: "memory")
; #define BAR __builtin_amdgcn_s_barrier()
; #define SCHED __builtin_amdgcn_sched_barrier(0)
; template <int EPI>
; __device__ __forceinline__ void gemm_phase(const u16* __restrict__ A, const u16* __restrict__ Bt, const int K,
;                                            const int nN, char* shm, const EpiArgs& ea) {
;     ...
;     for (int t = 0; t < nt - 2; t += 2) {
;       LDB(B0, 0, 0); SCHED; LDA(At, 0, 0); STAGE(SA(1, 1), rA, brow + HALF, t + 1);
;       WAIT_V(10); WAIT_L(8); BAR; WAIT_L(0); MMA(0, 0, At, B0); BAR; SCHED;
;       LDB(B1, 0, 1); STAGE(SB(0, 0), rB, bcol, t + 2);
;       WAIT_V(10); BAR; WAIT_L(0); MMA(0, 1, At, B1); BAR;
;       LDA(At, 0, 1); STAGE(SA(0, 0), rA, brow, t + 2);
;       BAR; WAIT_L(0); MMA(1, 0, At, B0); BAR; SCHED;
;       STAGE(SB(0, 1), rB, bcol + HALF, t + 2);
;       WAIT_V(10); BAR; MMA(1, 1, At, B1); BAR;
;       LDB(B0, 1, 0); SCHED; LDA(At, 1, 0); STAGE(SA(0, 1), rA, brow + HALF, t + 2);
;       WAIT_V(10); WAIT_L(8); BAR; WAIT_L(0); MMA(0, 0, At, B0); BAR; SCHED;
;       LDB(B1, 1, 1); STAGE(SB(1, 0), rB, bcol, t + 3);
;       WAIT_V(10); BAR; WAIT_L(0); MMA(0, 1, At, B1); BAR;
;       LDA(At, 1, 1); STAGE(SA(1, 0), rA, brow, t + 3);
;       BAR; WAIT_L(0); MMA(1, 0, At, B0); BAR; SCHED;
;       STAGE(SB(1, 1), rB, bcol + HALF, t + 3);
;       WAIT_V(10); BAR; MMA(1, 1, At, B1); BAR;
;     }
.LBB0_231:
	ds_read_b128 v[130:133], v138
	ds_read_b128 v[146:149], v138 offset:1024
	ds_read_b128 v[150:153], v138 offset:2048
	ds_read_b128 v[154:157], v138 offset:3072
	s_add_i32 s78, s70, s75
	s_mov_b32 m0, s48
	s_add_i32 s26, s78, 0x4000
	ds_read_b128 v[162:165], v139
	ds_read_b128 v[166:169], v139 offset:1024
	ds_read_b128 v[170:173], v140
	ds_read_b128 v[176:179], v140 offset:1024
	ds_read_b128 v[180:183], v141
	ds_read_b128 v[184:187], v141 offset:1024
	ds_read_b128 v[188:191], v142
	ds_read_b128 v[192:195], v142 offset:1024
	buffer_load_dwordx4 v134, s[0:3], s26 offen lds
	s_add_i32 s26, s78, 0x6000
	s_mov_b32 m0, s49
	s_nop 0
	buffer_load_dwordx4 v134, s[0:3], s26 offen lds
	s_waitcnt vmcnt(10)
	s_waitcnt lgkmcnt(8)
	s_barrier
	s_setprio 1
	s_waitcnt lgkmcnt(7)
	v_mfma_f32_16x16x32_bf16 v[124:127], v[130:133], v[162:165], v[124:127]
	v_mfma_f32_16x16x32_bf16 v[120:123], v[150:153], v[162:165], v[120:123]
	s_waitcnt lgkmcnt(5)
	v_mfma_f32_16x16x32_bf16 v[116:119], v[130:133], v[170:173], v[116:119]
	v_mfma_f32_16x16x32_bf16 v[112:115], v[150:153], v[170:173], v[112:115]
	s_waitcnt lgkmcnt(3)
	v_mfma_f32_16x16x32_bf16 v[108:111], v[130:133], v[180:183], v[108:111]
	v_mfma_f32_16x16x32_bf16 v[104:107], v[150:153], v[180:183], v[104:107]
	s_waitcnt lgkmcnt(1)
	v_mfma_f32_16x16x32_bf16 v[100:103], v[130:133], v[188:191], v[100:103]
	v_mfma_f32_16x16x32_bf16 v[96:99], v[150:153], v[188:191], v[96:99]
	v_mfma_f32_16x16x32_bf16 v[124:127], v[146:149], v[166:169], v[124:127]
	v_mfma_f32_16x16x32_bf16 v[120:123], v[154:157], v[166:169], v[120:123]
	v_mfma_f32_16x16x32_bf16 v[116:119], v[146:149], v[176:179], v[116:119]
	v_mfma_f32_16x16x32_bf16 v[112:115], v[154:157], v[176:179], v[112:115]
	v_mfma_f32_16x16x32_bf16 v[108:111], v[146:149], v[184:187], v[108:111]
	v_mfma_f32_16x16x32_bf16 v[104:107], v[154:157], v[184:187], v[104:107]
	s_waitcnt lgkmcnt(0)
	v_mfma_f32_16x16x32_bf16 v[100:103], v[146:149], v[192:195], v[100:103]
	v_mfma_f32_16x16x32_bf16 v[96:99], v[154:157], v[192:195], v[96:99]
	s_setprio 0
	s_barrier
	s_add_i32 s79, s73, s75
	s_mov_b32 m0, s52
	s_add_i32 s80, s79, 0x8000
	s_mov_b32 s26, s2
	s_mov_b32 s27, s3
	ds_read_b128 v[196:199], v143
	ds_read_b128 v[200:203], v143 offset:1024
	ds_read_b128 v[204:207], v143 offset:2048
	ds_read_b128 v[208:211], v143 offset:3072
	buffer_load_dwordx4 v134, s[24:27], s80 offen lds
	s_add_i32 s80, s79, 0xa000
	s_mov_b32 m0, s53
	s_nop 0
	buffer_load_dwordx4 v134, s[24:27], s80 offen lds
	s_waitcnt vmcnt(10)
	s_barrier
	s_setprio 1
	s_waitcnt lgkmcnt(3)
	v_mfma_f32_16x16x32_bf16 v[92:95], v[196:199], v[162:165], v[92:95]
	s_waitcnt lgkmcnt(1)
	v_mfma_f32_16x16x32_bf16 v[88:91], v[204:207], v[162:165], v[88:91]
	v_mfma_f32_16x16x32_bf16 v[84:87], v[196:199], v[170:173], v[84:87]
	v_mfma_f32_16x16x32_bf16 v[80:83], v[204:207], v[170:173], v[80:83]
	v_mfma_f32_16x16x32_bf16 v[76:79], v[196:199], v[180:183], v[76:79]
	v_mfma_f32_16x16x32_bf16 v[72:75], v[204:207], v[180:183], v[72:75]
	v_mfma_f32_16x16x32_bf16 v[68:71], v[196:199], v[188:191], v[68:71]
	v_mfma_f32_16x16x32_bf16 v[64:67], v[204:207], v[188:191], v[64:67]
	v_mfma_f32_16x16x32_bf16 v[92:95], v[200:203], v[166:169], v[92:95]
	s_waitcnt lgkmcnt(0)
	v_mfma_f32_16x16x32_bf16 v[88:91], v[208:211], v[166:169], v[88:91]
	v_mfma_f32_16x16x32_bf16 v[84:87], v[200:203], v[176:179], v[84:87]
	v_mfma_f32_16x16x32_bf16 v[80:83], v[208:211], v[176:179], v[80:83]
	v_mfma_f32_16x16x32_bf16 v[76:79], v[200:203], v[184:187], v[76:79]
	v_mfma_f32_16x16x32_bf16 v[72:75], v[208:211], v[184:187], v[72:75]
	v_mfma_f32_16x16x32_bf16 v[68:71], v[200:203], v[192:195], v[68:71]
	v_mfma_f32_16x16x32_bf16 v[64:67], v[208:211], v[192:195], v[64:67]
	s_setprio 0
	s_add_i32 s80, s72, s75
	s_mov_b32 m0, s43
	s_add_i32 s81, s80, 0x8000
	s_barrier
	ds_read_b128 v[162:165], v139 offset:16384
	ds_read_b128 v[166:169], v139 offset:17408
	ds_read_b128 v[170:173], v140 offset:16384
	ds_read_b128 v[176:179], v140 offset:17408
	ds_read_b128 v[180:183], v141 offset:16384
	ds_read_b128 v[184:187], v141 offset:17408
	ds_read_b128 v[188:191], v142 offset:16384
	ds_read_b128 v[192:195], v142 offset:17408
	buffer_load_dwordx4 v134, s[0:3], s81 offen lds
	s_add_i32 s81, s80, 0xa000
	s_mov_b32 m0, s54
	s_nop 0
	buffer_load_dwordx4 v134, s[0:3], s81 offen lds
	s_barrier
	s_setprio 1
	s_waitcnt lgkmcnt(7)
	v_mfma_f32_16x16x32_bf16 v[60:63], v[130:133], v[162:165], v[60:63]
	v_mfma_f32_16x16x32_bf16 v[56:59], v[150:153], v[162:165], v[56:59]
	s_waitcnt lgkmcnt(5)
	v_mfma_f32_16x16x32_bf16 v[52:55], v[130:133], v[170:173], v[52:55]
	v_mfma_f32_16x16x32_bf16 v[48:51], v[150:153], v[170:173], v[48:51]
	s_waitcnt lgkmcnt(3)
	v_mfma_f32_16x16x32_bf16 v[44:47], v[130:133], v[180:183], v[44:47]
	v_mfma_f32_16x16x32_bf16 v[40:43], v[150:153], v[180:183], v[40:43]
	s_waitcnt lgkmcnt(1)
	v_mfma_f32_16x16x32_bf16 v[36:39], v[130:133], v[188:191], v[36:39]
	v_mfma_f32_16x16x32_bf16 v[32:35], v[150:153], v[188:191], v[32:35]
	v_mfma_f32_16x16x32_bf16 v[60:63], v[146:149], v[166:169], v[60:63]
	v_mfma_f32_16x16x32_bf16 v[56:59], v[154:157], v[166:169], v[56:59]
	v_mfma_f32_16x16x32_bf16 v[52:55], v[146:149], v[176:179], v[52:55]
	v_mfma_f32_16x16x32_bf16 v[48:51], v[154:157], v[176:179], v[48:51]
	v_mfma_f32_16x16x32_bf16 v[44:47], v[146:149], v[184:187], v[44:47]
	v_mfma_f32_16x16x32_bf16 v[40:43], v[154:157], v[184:187], v[40:43]
	s_waitcnt lgkmcnt(0)
	v_mfma_f32_16x16x32_bf16 v[36:39], v[146:149], v[192:195], v[36:39]
	v_mfma_f32_16x16x32_bf16 v[32:35], v[154:157], v[192:195], v[32:35]
	s_setprio 0
	s_barrier
; #define LDA(dst, b, h)                                                                                               \
;   _Pragma("unroll") for (int m = 0; m < 4; ++m) _Pragma("unroll") for (int k = 0; k < 2; ++k) dst[m][k] =            \
;       *reinterpret_cast<const bf16x8*>(SA(b, h) + lds_byte(wr * 64 + m * 16 + fr, k * 32 + fq * 8))
; #define LDB(dst, b, h)                                                                                               \
;   _Pragma("unroll") for (int n = 0; n < 2; ++n) _Pragma("unroll") for (int k = 0; k < 2; ++k) dst[n][k] =            \
;       *reinterpret_cast<const bf16x8*>(SB(b, h) + lds_byte(wc * 32 + n * 16 + fr, k * 32 + fq * 8))
; #define WAIT_V(n) asm volatile("s_waitcnt vmcnt(" #n ")" ::: "memory")
; #define WAIT_L(n) asm volatile("s_waitcnt lgkmcnt(" #n ")" ::: "memory")
; #define BAR __builtin_amdgcn_s_barrier()
; #define SCHED __builtin_amdgcn_sched_barrier(0)
; template <int EPI>
; __device__ __forceinline__ void gemm_phase(const u16* __restrict__ A, const u16* __restrict__ Bt, const int K,
;                                            const int nN, char* shm, const EpiArgs& ea) {
;     ...
;     for (int t = 0; t < nt - 2; t += 2) {
;       LDB(B0, 0, 0); SCHED; LDA(At, 0, 0); STAGE(SA(1, 1), rA, brow + HALF, t + 1);
;       WAIT_V(10); WAIT_L(8); BAR; WAIT_L(0); MMA(0, 0, At, B0); BAR; SCHED;
;       LDB(B1, 0, 1); STAGE(SB(0, 0), rB, bcol, t + 2);
;       WAIT_V(10); BAR; WAIT_L(0); MMA(0, 1, At, B1); BAR;
;       LDA(At, 0, 1); STAGE(SA(0, 0), rA, brow, t + 2);
;       BAR; WAIT_L(0); MMA(1, 0, At, B0); BAR; SCHED;
;       STAGE(SB(0, 1), rB, bcol + HALF, t + 2);
;       WAIT_V(10); BAR; MMA(1, 1, At, B1); BAR;
;       LDB(B0, 1, 0); SCHED; LDA(At, 1, 0); STAGE(SA(0, 1), rA, brow + HALF, t + 2);
;       WAIT_V(10); WAIT_L(8); BAR; WAIT_L(0); MMA(0, 0, At, B0); BAR; SCHED;
;       LDB(B1, 1, 1); STAGE(SB(1, 0), rB, bcol, t + 3);
;       WAIT_V(10); BAR; WAIT_L(0); MMA(0, 1, At, B1); BAR;
;       LDA(At, 1, 1); STAGE(SA(1, 0), rA, brow, t + 3);
;       BAR; WAIT_L(0); MMA(1, 0, At, B0); BAR; SCHED;
;       STAGE(SB(1, 1), rB, bcol + HALF, t + 3);
;       WAIT_V(10); BAR; MMA(1, 1, At, B1); BAR;
;     }
	s_add_i32 s81, s71, s75
	s_mov_b32 m0, s55
	s_add_i32 s82, s81, 0x8000
	buffer_load_dwordx4 v134, s[24:27], s82 offen lds
	s_add_i32 s82, s81, 0xa000
	s_mov_b32 m0, s56
	s_nop 0
	buffer_load_dwordx4 v134, s[24:27], s82 offen lds
	s_waitcnt vmcnt(10)
	s_barrier
	s_setprio 1
	v_mfma_f32_16x16x32_bf16 v[28:31], v[196:199], v[162:165], v[28:31]
	v_mfma_f32_16x16x32_bf16 v[24:27], v[204:207], v[162:165], v[24:27]
	v_mfma_f32_16x16x32_bf16 v[20:23], v[196:199], v[170:173], v[20:23]
	v_mfma_f32_16x16x32_bf16 v[16:19], v[204:207], v[170:173], v[16:19]
	v_mfma_f32_16x16x32_bf16 v[12:15], v[196:199], v[180:183], v[12:15]
	v_mfma_f32_16x16x32_bf16 v[8:11], v[204:207], v[180:183], v[8:11]
	v_mfma_f32_16x16x32_bf16 v[4:7], v[196:199], v[188:191], v[4:7]
	v_mfma_f32_16x16x32_bf16 v[0:3], v[204:207], v[188:191], v[0:3]
	v_mfma_f32_16x16x32_bf16 v[28:31], v[200:203], v[166:169], v[28:31]
	v_mfma_f32_16x16x32_bf16 v[24:27], v[208:211], v[166:169], v[24:27]
	v_mfma_f32_16x16x32_bf16 v[20:23], v[200:203], v[176:179], v[20:23]
	v_mfma_f32_16x16x32_bf16 v[16:19], v[208:211], v[176:179], v[16:19]
	v_mfma_f32_16x16x32_bf16 v[12:15], v[200:203], v[184:187], v[12:15]
	v_mfma_f32_16x16x32_bf16 v[8:11], v[208:211], v[184:187], v[8:11]
	v_mfma_f32_16x16x32_bf16 v[4:7], v[200:203], v[192:195], v[4:7]
	v_mfma_f32_16x16x32_bf16 v[0:3], v[208:211], v[192:195], v[0:3]
	s_setprio 0
	s_barrier
	ds_read_b128 v[130:133], v144
	ds_read_b128 v[146:149], v144 offset:1024
	ds_read_b128 v[150:153], v144 offset:2048
	ds_read_b128 v[154:157], v144 offset:3072
	s_mov_b32 m0, s57
	s_add_i32 s82, s78, 0x8000
	ds_read_b128 v[162:165], v139 offset:32768
	ds_read_b128 v[166:169], v139 offset:33792
	ds_read_b128 v[170:173], v140 offset:32768
	ds_read_b128 v[176:179], v140 offset:33792
	ds_read_b128 v[180:183], v141 offset:32768
	ds_read_b128 v[184:187], v141 offset:33792
	ds_read_b128 v[188:191], v142 offset:32768
	ds_read_b128 v[192:195], v142 offset:33792
	buffer_load_dwordx4 v134, s[0:3], s82 offen lds
	s_add_i32 s78, s78, 0xa000
	s_mov_b32 m0, s58
	s_nop 0
	buffer_load_dwordx4 v134, s[0:3], s78 offen lds
	s_waitcnt vmcnt(10)
	s_waitcnt lgkmcnt(8)
	s_barrier
	s_setprio 1
	s_waitcnt lgkmcnt(7)
	v_mfma_f32_16x16x32_bf16 v[124:127], v[130:133], v[162:165], v[124:127]
	v_mfma_f32_16x16x32_bf16 v[120:123], v[150:153], v[162:165], v[120:123]
	s_waitcnt lgkmcnt(5)
	v_mfma_f32_16x16x32_bf16 v[116:119], v[130:133], v[170:173], v[116:119]
	v_mfma_f32_16x16x32_bf16 v[112:115], v[150:153], v[170:173], v[112:115]
	s_waitcnt lgkmcnt(3)
	v_mfma_f32_16x16x32_bf16 v[108:111], v[130:133], v[180:183], v[108:111]
	v_mfma_f32_16x16x32_bf16 v[104:107], v[150:153], v[180:183], v[104:107]
	s_waitcnt lgkmcnt(1)
	v_mfma_f32_16x16x32_bf16 v[100:103], v[130:133], v[188:191], v[100:103]
	v_mfma_f32_16x16x32_bf16 v[96:99], v[150:153], v[188:191], v[96:99]
	v_mfma_f32_16x16x32_bf16 v[124:127], v[146:149], v[166:169], v[124:127]
	v_mfma_f32_16x16x32_bf16 v[120:123], v[154:157], v[166:169], v[120:123]
	v_mfma_f32_16x16x32_bf16 v[116:119], v[146:149], v[176:179], v[116:119]
	v_mfma_f32_16x16x32_bf16 v[112:115], v[154:157], v[176:179], v[112:115]
	v_mfma_f32_16x16x32_bf16 v[108:111], v[146:149], v[184:187], v[108:111]
	v_mfma_f32_16x16x32_bf16 v[104:107], v[154:157], v[184:187], v[104:107]
	s_waitcnt lgkmcnt(0)
	v_mfma_f32_16x16x32_bf16 v[100:103], v[146:149], v[192:195], v[100:103]
	v_mfma_f32_16x16x32_bf16 v[96:99], v[154:157], v[192:195], v[96:99]
	s_setprio 0
	s_barrier
	s_mov_b32 m0, s59
	s_add_i32 s78, s79, 0xc000
	ds_read_b128 v[196:199], v145
	ds_read_b128 v[200:203], v145 offset:1024
	ds_read_b128 v[204:207], v145 offset:2048
	ds_read_b128 v[208:211], v145 offset:3072
	buffer_load_dwordx4 v134, s[24:27], s78 offen lds
	s_add_i32 s79, s79, 0xe000
	s_mov_b32 m0, s60
	s_nop 0
	buffer_load_dwordx4 v134, s[24:27], s79 offen lds
	s_waitcnt vmcnt(10)
	s_barrier
	s_setprio 1
	s_waitcnt lgkmcnt(3)
	v_mfma_f32_16x16x32_bf16 v[92:95], v[196:199], v[162:165], v[92:95]
	s_waitcnt lgkmcnt(1)
	v_mfma_f32_16x16x32_bf16 v[88:91], v[204:207], v[162:165], v[88:91]
	v_mfma_f32_16x16x32_bf16 v[84:87], v[196:199], v[170:173], v[84:87]
	v_mfma_f32_16x16x32_bf16 v[80:83], v[204:207], v[170:173], v[80:83]
	v_mfma_f32_16x16x32_bf16 v[76:79], v[196:199], v[180:183], v[76:79]
	v_mfma_f32_16x16x32_bf16 v[72:75], v[204:207], v[180:183], v[72:75]
	v_mfma_f32_16x16x32_bf16 v[68:71], v[196:199], v[188:191], v[68:71]
	v_mfma_f32_16x16x32_bf16 v[64:67], v[204:207], v[188:191], v[64:67]
	v_mfma_f32_16x16x32_bf16 v[92:95], v[200:203], v[166:169], v[92:95]
	s_waitcnt lgkmcnt(0)
	v_mfma_f32_16x16x32_bf16 v[88:91], v[208:211], v[166:169], v[88:91]
	v_mfma_f32_16x16x32_bf16 v[84:87], v[200:203], v[176:179], v[84:87]
	v_mfma_f32_16x16x32_bf16 v[80:83], v[208:211], v[176:179], v[80:83]
	v_mfma_f32_16x16x32_bf16 v[76:79], v[200:203], v[184:187], v[76:79]
	v_mfma_f32_16x16x32_bf16 v[72:75], v[208:211], v[184:187], v[72:75]
	v_mfma_f32_16x16x32_bf16 v[68:71], v[200:203], v[192:195], v[68:71]
	v_mfma_f32_16x16x32_bf16 v[64:67], v[208:211], v[192:195], v[64:67]
	s_setprio 0
	s_mov_b32 m0, s61
	s_add_i32 s78, s80, 0xc000
	s_barrier
	ds_read_b128 v[162:165], v139 offset:49152
	ds_read_b128 v[166:169], v139 offset:50176
	ds_read_b128 v[170:173], v140 offset:49152
	ds_read_b128 v[176:179], v140 offset:50176
	ds_read_b128 v[180:183], v141 offset:49152
	ds_read_b128 v[184:187], v141 offset:50176
	ds_read_b128 v[188:191], v142 offset:49152
	ds_read_b128 v[192:195], v142 offset:50176
	buffer_load_dwordx4 v134, s[0:3], s78 offen lds
	s_add_i32 s80, s80, 0xe000
	s_mov_b32 m0, s62
	s_nop 0
	buffer_load_dwordx4 v134, s[0:3], s80 offen lds
	s_barrier
; #define LDA(dst, b, h)                                                                                               \
;   _Pragma("unroll") for (int m = 0; m < 4; ++m) _Pragma("unroll") for (int k = 0; k < 2; ++k) dst[m][k] =            \
;       *reinterpret_cast<const bf16x8*>(SA(b, h) + lds_byte(wr * 64 + m * 16 + fr, k * 32 + fq * 8))
; #define LDB(dst, b, h)                                                                                               \
;   _Pragma("unroll") for (int n = 0; n < 2; ++n) _Pragma("unroll") for (int k = 0; k < 2; ++k) dst[n][k] =            \
;       *reinterpret_cast<const bf16x8*>(SB(b, h) + lds_byte(wc * 32 + n * 16 + fr, k * 32 + fq * 8))
; #define WAIT_V(n) asm volatile("s_waitcnt vmcnt(" #n ")" ::: "memory")
; #define WAIT_L(n) asm volatile("s_waitcnt lgkmcnt(" #n ")" ::: "memory")
; #define BAR __builtin_amdgcn_s_barrier()
; #define SCHED __builtin_amdgcn_sched_barrier(0)
; template <int EPI>
; __device__ __forceinline__ void gemm_phase(const u16* __restrict__ A, const u16* __restrict__ Bt, const int K,
;                                            const int nN, char* shm, const EpiArgs& ea) {
;     ...
;       WAIT_V(10); BAR; MMA(1, 1, At, B1); BAR;
;       LDB(B0, 1, 0); SCHED; LDA(At, 1, 0); STAGE(SA(0, 1), rA, brow + HALF, t + 2);
;       WAIT_V(10); WAIT_L(8); BAR; WAIT_L(0); MMA(0, 0, At, B0); BAR; SCHED;
;       LDB(B1, 1, 1); STAGE(SB(1, 0), rB, bcol, t + 3);
;       WAIT_V(10); BAR; WAIT_L(0); MMA(0, 1, At, B1); BAR;
;       LDA(At, 1, 1); STAGE(SA(1, 0), rA, brow, t + 3);
;       BAR; WAIT_L(0); MMA(1, 0, At, B0); BAR; SCHED;
;       STAGE(SB(1, 1), rB, bcol + HALF, t + 3);
;       WAIT_V(10); BAR; MMA(1, 1, At, B1); BAR;
;     }
;     ...
;     {
;       LDB(B0, 0, 0); LDA(At, 0, 0); STAGE(SA(1, 1), rA, brow + HALF, nt - 1);
;       WAIT_V(10); BAR; WAIT_L(0); MMA(0, 0, At, B0); BAR;
;       LDB(B1, 0, 1); WAIT_V(8); BAR; WAIT_L(0); MMA(0, 1, At, B1); BAR;
;       LDA(At, 0, 1); WAIT_V(4); BAR; WAIT_L(0); MMA(1, 0, At, B0); MMA(1, 1, At, B1); BAR;
	s_setprio 1
	s_waitcnt lgkmcnt(7)
	v_mfma_f32_16x16x32_bf16 v[60:63], v[130:133], v[162:165], v[60:63]
	v_mfma_f32_16x16x32_bf16 v[56:59], v[150:153], v[162:165], v[56:59]
	s_waitcnt lgkmcnt(5)
	v_mfma_f32_16x16x32_bf16 v[52:55], v[130:133], v[170:173], v[52:55]
	v_mfma_f32_16x16x32_bf16 v[48:51], v[150:153], v[170:173], v[48:51]
	s_waitcnt lgkmcnt(3)
	v_mfma_f32_16x16x32_bf16 v[44:47], v[130:133], v[180:183], v[44:47]
	v_mfma_f32_16x16x32_bf16 v[40:43], v[150:153], v[180:183], v[40:43]
	s_waitcnt lgkmcnt(1)
	v_mfma_f32_16x16x32_bf16 v[36:39], v[130:133], v[188:191], v[36:39]
	v_mfma_f32_16x16x32_bf16 v[32:35], v[150:153], v[188:191], v[32:35]
	v_mfma_f32_16x16x32_bf16 v[60:63], v[146:149], v[166:169], v[60:63]
	v_mfma_f32_16x16x32_bf16 v[56:59], v[154:157], v[166:169], v[56:59]
	v_mfma_f32_16x16x32_bf16 v[52:55], v[146:149], v[176:179], v[52:55]
	v_mfma_f32_16x16x32_bf16 v[48:51], v[154:157], v[176:179], v[48:51]
	v_mfma_f32_16x16x32_bf16 v[44:47], v[146:149], v[184:187], v[44:47]
	v_mfma_f32_16x16x32_bf16 v[40:43], v[154:157], v[184:187], v[40:43]
	s_waitcnt lgkmcnt(0)
	v_mfma_f32_16x16x32_bf16 v[36:39], v[146:149], v[192:195], v[36:39]
	v_mfma_f32_16x16x32_bf16 v[32:35], v[154:157], v[192:195], v[32:35]
	s_setprio 0
	s_barrier
	s_mov_b32 m0, s63
	s_add_i32 s78, s81, 0xc000
	buffer_load_dwordx4 v134, s[24:27], s78 offen lds
	s_add_i32 s81, s81, 0xe000
	s_mov_b32 m0, s64
	s_nop 0
	buffer_load_dwordx4 v134, s[24:27], s81 offen lds
	s_waitcnt vmcnt(10)
	s_barrier
	s_setprio 1
	v_mfma_f32_16x16x32_bf16 v[28:31], v[196:199], v[162:165], v[28:31]
	v_mfma_f32_16x16x32_bf16 v[24:27], v[204:207], v[162:165], v[24:27]
	v_mfma_f32_16x16x32_bf16 v[20:23], v[196:199], v[170:173], v[20:23]
	v_mfma_f32_16x16x32_bf16 v[16:19], v[204:207], v[170:173], v[16:19]
	v_mfma_f32_16x16x32_bf16 v[12:15], v[196:199], v[180:183], v[12:15]
	v_mfma_f32_16x16x32_bf16 v[8:11], v[204:207], v[180:183], v[8:11]
	v_mfma_f32_16x16x32_bf16 v[4:7], v[196:199], v[188:191], v[4:7]
	v_mfma_f32_16x16x32_bf16 v[0:3], v[204:207], v[188:191], v[0:3]
	v_mfma_f32_16x16x32_bf16 v[28:31], v[200:203], v[166:169], v[28:31]
	v_mfma_f32_16x16x32_bf16 v[24:27], v[208:211], v[166:169], v[24:27]
	v_mfma_f32_16x16x32_bf16 v[20:23], v[200:203], v[176:179], v[20:23]
	v_mfma_f32_16x16x32_bf16 v[16:19], v[208:211], v[176:179], v[16:19]
	v_mfma_f32_16x16x32_bf16 v[12:15], v[200:203], v[184:187], v[12:15]
	v_mfma_f32_16x16x32_bf16 v[8:11], v[208:211], v[184:187], v[8:11]
	v_mfma_f32_16x16x32_bf16 v[4:7], v[200:203], v[192:195], v[4:7]
	v_mfma_f32_16x16x32_bf16 v[0:3], v[208:211], v[192:195], v[0:3]
	s_setprio 0
	s_add_i32 s74, s74, 2
	s_add_i32 s75, s75, 0x8000
	s_cmpk_lt_u32 s74, 0x54
	s_barrier
	s_cbranch_scc1 .LBB0_231
	s_mov_b32 m0, s48
	s_add_i32 s26, s70, 0x15c000
	ds_read_b128 v[130:133], v138
	ds_read_b128 v[146:149], v138 offset:1024
	ds_read_b128 v[150:153], v138 offset:2048
	ds_read_b128 v[154:157], v138 offset:3072
	ds_read_b128 v[162:165], v139
	ds_read_b128 v[166:169], v139 offset:1024
	ds_read_b128 v[170:173], v140
	ds_read_b128 v[176:179], v140 offset:1024
	ds_read_b128 v[180:183], v141
	ds_read_b128 v[184:187], v141 offset:1024
	ds_read_b128 v[188:191], v142
	ds_read_b128 v[192:195], v142 offset:1024
	buffer_load_dwordx4 v134, s[0:3], s26 offen lds
	s_add_i32 s70, s70, 0x15e000
	s_mov_b32 m0, s49
	s_nop 0
	buffer_load_dwordx4 v134, s[0:3], s70 offen lds
	s_waitcnt vmcnt(10)
	s_barrier
	s_setprio 1
	s_waitcnt lgkmcnt(7)
	v_mfma_f32_16x16x32_bf16 v[124:127], v[130:133], v[162:165], v[124:127]
	s_waitcnt lgkmcnt(5)
	v_mfma_f32_16x16x32_bf16 v[116:119], v[130:133], v[170:173], v[116:119]
	v_mfma_f32_16x16x32_bf16 v[112:115], v[150:153], v[170:173], v[112:115]
	s_waitcnt lgkmcnt(1)
	v_mfma_f32_16x16x32_bf16 v[100:103], v[130:133], v[188:191], v[100:103]
	v_mfma_f32_16x16x32_bf16 v[96:99], v[150:153], v[188:191], v[96:99]
	v_mfma_f32_16x16x32_bf16 v[124:127], v[146:149], v[166:169], v[124:127]
	v_mfma_f32_16x16x32_bf16 v[120:123], v[150:153], v[162:165], v[120:123]
	v_mfma_f32_16x16x32_bf16 v[116:119], v[146:149], v[176:179], v[116:119]
	v_mfma_f32_16x16x32_bf16 v[112:115], v[154:157], v[176:179], v[112:115]
	v_mfma_f32_16x16x32_bf16 v[108:111], v[130:133], v[180:183], v[108:111]
	v_mfma_f32_16x16x32_bf16 v[104:107], v[150:153], v[180:183], v[104:107]
	s_waitcnt lgkmcnt(0)
	v_mfma_f32_16x16x32_bf16 v[100:103], v[146:149], v[192:195], v[100:103]
	v_mfma_f32_16x16x32_bf16 v[96:99], v[154:157], v[192:195], v[96:99]
	v_mfma_f32_16x16x32_bf16 v[196:199], v[154:157], v[166:169], v[120:123]
	v_mfma_f32_16x16x32_bf16 v[200:203], v[146:149], v[184:187], v[108:111]
	v_mfma_f32_16x16x32_bf16 v[204:207], v[154:157], v[184:187], v[104:107]
	s_setprio 0
	s_barrier
	s_nop 0
	ds_read_b128 v[104:107], v143
	ds_read_b128 v[108:111], v143 offset:1024
	ds_read_b128 v[120:123], v143 offset:2048
	ds_read_b128 v[208:211], v143 offset:3072
	s_waitcnt vmcnt(8)
	s_barrier
	s_setprio 1
	s_waitcnt lgkmcnt(3)
	v_mfma_f32_16x16x32_bf16 v[84:87], v[104:107], v[170:173], v[84:87]
	s_waitcnt lgkmcnt(1)
	v_mfma_f32_16x16x32_bf16 v[80:83], v[120:123], v[170:173], v[80:83]
	v_mfma_f32_16x16x32_bf16 v[68:71], v[104:107], v[188:191], v[68:71]
	v_mfma_f32_16x16x32_bf16 v[92:95], v[104:107], v[162:165], v[92:95]
	v_mfma_f32_16x16x32_bf16 v[88:91], v[120:123], v[162:165], v[88:91]
	v_mfma_f32_16x16x32_bf16 v[84:87], v[108:111], v[176:179], v[84:87]
	s_waitcnt lgkmcnt(0)
	v_mfma_f32_16x16x32_bf16 v[80:83], v[208:211], v[176:179], v[80:83]
	v_mfma_f32_16x16x32_bf16 v[76:79], v[104:107], v[180:183], v[76:79]
	v_mfma_f32_16x16x32_bf16 v[72:75], v[120:123], v[180:183], v[72:75]
	v_mfma_f32_16x16x32_bf16 v[68:71], v[108:111], v[192:195], v[68:71]
	v_mfma_f32_16x16x32_bf16 v[64:67], v[120:123], v[188:191], v[64:67]
	v_mfma_f32_16x16x32_bf16 v[212:215], v[108:111], v[166:169], v[92:95]
	v_mfma_f32_16x16x32_bf16 v[162:165], v[208:211], v[166:169], v[88:91]
	v_mfma_f32_16x16x32_bf16 v[166:169], v[108:111], v[184:187], v[76:79]
	v_mfma_f32_16x16x32_bf16 v[170:173], v[208:211], v[184:187], v[72:75]
	v_mfma_f32_16x16x32_bf16 v[176:179], v[208:211], v[192:195], v[64:67]
	s_setprio 0
	s_barrier
; #define LDA(dst, b, h)                                                                                               \
;   _Pragma("unroll") for (int m = 0; m < 4; ++m) _Pragma("unroll") for (int k = 0; k < 2; ++k) dst[m][k] =            \
;       *reinterpret_cast<const bf16x8*>(SA(b, h) + lds_byte(wr * 64 + m * 16 + fr, k * 32 + fq * 8))
; #define LDB(dst, b, h)                                                                                               \
;   _Pragma("unroll") for (int n = 0; n < 2; ++n) _Pragma("unroll") for (int k = 0; k < 2; ++k) dst[n][k] =            \
;       *reinterpret_cast<const bf16x8*>(SB(b, h) + lds_byte(wc * 32 + n * 16 + fr, k * 32 + fq * 8))
; #define WAIT_V(n) asm volatile("s_waitcnt vmcnt(" #n ")" ::: "memory")
; #define WAIT_L(n) asm volatile("s_waitcnt lgkmcnt(" #n ")" ::: "memory")
; #define BAR __builtin_amdgcn_s_barrier()
; template <int EPI>
; __device__ __forceinline__ void gemm_phase(const u16* __restrict__ A, const u16* __restrict__ Bt, const int K,
;                                            const int nN, char* shm, const EpiArgs& ea) {
;     ...
;       LDB(B1, 0, 1); WAIT_V(8); BAR; WAIT_L(0); MMA(0, 1, At, B1); BAR;
;       LDA(At, 0, 1); WAIT_V(4); BAR; WAIT_L(0); MMA(1, 0, At, B0); MMA(1, 1, At, B1); BAR;
;     }
;     {
;       LDB(B0, 1, 0); LDA(At, 1, 0); WAIT_V(2); BAR; WAIT_L(0); MMA(0, 0, At, B0); BAR;
;       LDB(B1, 1, 1); WAIT_V(0); BAR; WAIT_L(0); MMA(0, 1, At, B1); BAR;
	s_nop 0
	ds_read_b128 v[64:67], v139 offset:16384
	ds_read_b128 v[72:75], v139 offset:17408
	ds_read_b128 v[76:79], v140 offset:16384
	ds_read_b128 v[88:91], v140 offset:17408
	ds_read_b128 v[92:95], v141 offset:16384
	ds_read_b128 v[180:183], v141 offset:17408
	ds_read_b128 v[184:187], v142 offset:16384
	ds_read_b128 v[188:191], v142 offset:17408
	s_waitcnt vmcnt(4)
	s_barrier
	s_setprio 1
	s_waitcnt lgkmcnt(7)
	v_mfma_f32_16x16x32_bf16 v[60:63], v[130:133], v[64:67], v[60:63]
	s_waitcnt lgkmcnt(5)
	v_mfma_f32_16x16x32_bf16 v[52:55], v[130:133], v[76:79], v[52:55]
	v_mfma_f32_16x16x32_bf16 v[48:51], v[150:153], v[76:79], v[48:51]
	s_waitcnt lgkmcnt(1)
	v_mfma_f32_16x16x32_bf16 v[36:39], v[130:133], v[184:187], v[36:39]
	v_mfma_f32_16x16x32_bf16 v[32:35], v[150:153], v[184:187], v[32:35]
	v_mfma_f32_16x16x32_bf16 v[60:63], v[146:149], v[72:75], v[60:63]
	v_mfma_f32_16x16x32_bf16 v[56:59], v[150:153], v[64:67], v[56:59]
	v_mfma_f32_16x16x32_bf16 v[52:55], v[146:149], v[88:91], v[52:55]
	v_mfma_f32_16x16x32_bf16 v[48:51], v[154:157], v[88:91], v[48:51]
	v_mfma_f32_16x16x32_bf16 v[44:47], v[130:133], v[92:95], v[44:47]
	v_mfma_f32_16x16x32_bf16 v[40:43], v[150:153], v[92:95], v[40:43]
	s_waitcnt lgkmcnt(0)
	v_mfma_f32_16x16x32_bf16 v[36:39], v[146:149], v[188:191], v[36:39]
	v_mfma_f32_16x16x32_bf16 v[32:35], v[154:157], v[188:191], v[32:35]
	v_mfma_f32_16x16x32_bf16 v[192:195], v[154:157], v[72:75], v[56:59]
	v_mfma_f32_16x16x32_bf16 v[216:219], v[146:149], v[180:183], v[44:47]
	v_mfma_f32_16x16x32_bf16 v[220:223], v[154:157], v[180:183], v[40:43]
	s_setprio 0
	s_setprio 1
	v_mfma_f32_16x16x32_bf16 v[20:23], v[104:107], v[76:79], v[20:23]
	v_mfma_f32_16x16x32_bf16 v[16:19], v[120:123], v[76:79], v[16:19]
	v_mfma_f32_16x16x32_bf16 v[4:7], v[104:107], v[184:187], v[4:7]
	v_mfma_f32_16x16x32_bf16 v[28:31], v[104:107], v[64:67], v[28:31]
	v_mfma_f32_16x16x32_bf16 v[24:27], v[120:123], v[64:67], v[24:27]
	v_mfma_f32_16x16x32_bf16 v[20:23], v[108:111], v[88:91], v[20:23]
	v_mfma_f32_16x16x32_bf16 v[16:19], v[208:211], v[88:91], v[16:19]
	v_mfma_f32_16x16x32_bf16 v[12:15], v[104:107], v[92:95], v[12:15]
	v_mfma_f32_16x16x32_bf16 v[8:11], v[120:123], v[92:95], v[8:11]
	v_mfma_f32_16x16x32_bf16 v[4:7], v[108:111], v[188:191], v[4:7]
	v_mfma_f32_16x16x32_bf16 v[0:3], v[120:123], v[184:187], v[0:3]
	v_mfma_f32_16x16x32_bf16 v[130:133], v[108:111], v[72:75], v[28:31]
	v_mfma_f32_16x16x32_bf16 v[146:149], v[208:211], v[72:75], v[24:27]
	v_mfma_f32_16x16x32_bf16 v[150:153], v[108:111], v[180:183], v[12:15]
	v_mfma_f32_16x16x32_bf16 v[154:157], v[208:211], v[180:183], v[8:11]
	v_mfma_f32_16x16x32_bf16 v[180:183], v[208:211], v[188:191], v[0:3]
	s_setprio 0
	s_barrier
	s_nop 0
	ds_read_b128 v[0:3], v144
	ds_read_b128 v[8:11], v144 offset:1024
	ds_read_b128 v[12:15], v144 offset:2048
	ds_read_b128 v[184:187], v144 offset:3072
	ds_read_b128 v[24:27], v139 offset:32768
	ds_read_b128 v[28:31], v139 offset:33792
	ds_read_b128 v[40:43], v140 offset:32768
	ds_read_b128 v[44:47], v140 offset:33792
	ds_read_b128 v[56:59], v141 offset:32768
	ds_read_b128 v[64:67], v141 offset:33792
	ds_read_b128 v[188:191], v142 offset:32768
	ds_read_b128 v[208:211], v142 offset:33792
	s_waitcnt vmcnt(2)
	s_barrier
	s_setprio 1
	s_waitcnt lgkmcnt(7)
	v_mfma_f32_16x16x32_bf16 v[72:75], v[0:3], v[24:27], v[124:127]
	s_waitcnt lgkmcnt(6)
	v_mfma_f32_16x16x32_bf16 v[120:123], v[8:11], v[28:31], v[72:75]
	v_mfma_f32_16x16x32_bf16 v[72:75], v[12:15], v[24:27], v[196:199]
	v_mfma_f32_16x16x32_bf16 v[124:127], v[184:187], v[28:31], v[72:75]
	s_waitcnt lgkmcnt(5)
	v_mfma_f32_16x16x32_bf16 v[72:75], v[0:3], v[40:43], v[116:119]
	s_waitcnt lgkmcnt(4)
	v_mfma_f32_16x16x32_bf16 v[104:107], v[8:11], v[44:47], v[72:75]
	v_mfma_f32_16x16x32_bf16 v[72:75], v[12:15], v[40:43], v[112:115]
	v_mfma_f32_16x16x32_bf16 v[108:111], v[184:187], v[44:47], v[72:75]
	s_waitcnt lgkmcnt(3)
	v_mfma_f32_16x16x32_bf16 v[72:75], v[0:3], v[56:59], v[200:203]
	s_waitcnt lgkmcnt(2)
	v_mfma_f32_16x16x32_bf16 v[88:91], v[8:11], v[64:67], v[72:75]
	v_mfma_f32_16x16x32_bf16 v[72:75], v[12:15], v[56:59], v[204:207]
	v_mfma_f32_16x16x32_bf16 v[92:95], v[184:187], v[64:67], v[72:75]
	s_waitcnt lgkmcnt(1)
	v_mfma_f32_16x16x32_bf16 v[72:75], v[0:3], v[188:191], v[100:103]
	v_mfma_f32_16x16x32_bf16 v[76:79], v[12:15], v[188:191], v[96:99]
	s_waitcnt lgkmcnt(0)
	v_mfma_f32_16x16x32_bf16 v[72:75], v[8:11], v[208:211], v[72:75]
	v_mfma_f32_16x16x32_bf16 v[76:79], v[184:187], v[208:211], v[76:79]
	s_setprio 0
	s_barrier
; #define LDA(dst, b, h)                                                                                               \
;   _Pragma("unroll") for (int m = 0; m < 4; ++m) _Pragma("unroll") for (int k = 0; k < 2; ++k) dst[m][k] =            \
;       *reinterpret_cast<const bf16x8*>(SA(b, h) + lds_byte(wr * 64 + m * 16 + fr, k * 32 + fq * 8))
; #define LDB(dst, b, h)                                                                                               \
;   _Pragma("unroll") for (int n = 0; n < 2; ++n) _Pragma("unroll") for (int k = 0; k < 2; ++k) dst[n][k] =            \
;       *reinterpret_cast<const bf16x8*>(SB(b, h) + lds_byte(wc * 32 + n * 16 + fr, k * 32 + fq * 8))
; #define WAIT_V(n) asm volatile("s_waitcnt vmcnt(" #n ")" ::: "memory")
; #define WAIT_L(n) asm volatile("s_waitcnt lgkmcnt(" #n ")" ::: "memory")
; #define BAR __builtin_amdgcn_s_barrier()
; template <int EPI>
; __device__ __forceinline__ void gemm_phase(const u16* __restrict__ A, const u16* __restrict__ Bt, const int K,
;                                            const int nN, char* shm, const EpiArgs& ea) {
;     ...
;     {
;       LDB(B0, 1, 0); LDA(At, 1, 0); WAIT_V(2); BAR; WAIT_L(0); MMA(0, 0, At, B0); BAR;
;       LDB(B1, 1, 1); WAIT_V(0); BAR; WAIT_L(0); MMA(0, 1, At, B1); BAR;
;       LDA(At, 1, 1); BAR; WAIT_L(0); MMA(1, 0, At, B0); MMA(1, 1, At, B1); BAR;
;     }
;     if (wr == 0) BAR;
	ds_read_b128 v[196:199], v145
	ds_read_b128 v[200:203], v145 offset:1024
	ds_read_b128 v[204:207], v145 offset:2048
	ds_read_b128 v[224:227], v145 offset:3072
	s_waitcnt vmcnt(0)
	s_barrier
	s_setprio 1
	s_waitcnt lgkmcnt(3)
	v_mfma_f32_16x16x32_bf16 v[96:99], v[196:199], v[24:27], v[212:215]
	s_waitcnt lgkmcnt(1)
	v_mfma_f32_16x16x32_bf16 v[24:27], v[204:207], v[24:27], v[162:165]
	s_waitcnt lgkmcnt(0)
	v_mfma_f32_16x16x32_bf16 v[116:119], v[224:227], v[28:31], v[24:27]
	v_mfma_f32_16x16x32_bf16 v[24:27], v[196:199], v[40:43], v[84:87]
	v_mfma_f32_16x16x32_bf16 v[112:115], v[200:203], v[28:31], v[96:99]
	v_mfma_f32_16x16x32_bf16 v[96:99], v[200:203], v[44:47], v[24:27]
	v_mfma_f32_16x16x32_bf16 v[24:27], v[204:207], v[40:43], v[80:83]
	v_mfma_f32_16x16x32_bf16 v[100:103], v[224:227], v[44:47], v[24:27]
	v_mfma_f32_16x16x32_bf16 v[24:27], v[196:199], v[56:59], v[166:169]
	v_mfma_f32_16x16x32_bf16 v[80:83], v[200:203], v[64:67], v[24:27]
	v_mfma_f32_16x16x32_bf16 v[24:27], v[204:207], v[56:59], v[170:173]
	v_mfma_f32_16x16x32_bf16 v[84:87], v[224:227], v[64:67], v[24:27]
	v_mfma_f32_16x16x32_bf16 v[24:27], v[196:199], v[188:191], v[68:71]
	v_mfma_f32_16x16x32_bf16 v[64:67], v[200:203], v[208:211], v[24:27]
	v_mfma_f32_16x16x32_bf16 v[24:27], v[204:207], v[188:191], v[176:179]
	v_mfma_f32_16x16x32_bf16 v[68:71], v[224:227], v[208:211], v[24:27]
	s_setprio 0
	s_barrier
	ds_read_b128 v[162:165], v139 offset:49152
	ds_read_b128 v[166:169], v139 offset:50176
	ds_read_b128 v[170:173], v140 offset:49152
	ds_read_b128 v[176:179], v140 offset:50176
	ds_read_b128 v[188:191], v141 offset:49152
	ds_read_b128 v[208:211], v141 offset:50176
	ds_read_b128 v[212:215], v142 offset:49152
	ds_read_b128 v[228:231], v142 offset:50176
	s_barrier
	s_setprio 1
	s_waitcnt lgkmcnt(7)
	v_mfma_f32_16x16x32_bf16 v[24:27], v[0:3], v[162:165], v[60:63]
	s_waitcnt lgkmcnt(6)
	v_mfma_f32_16x16x32_bf16 v[56:59], v[8:11], v[166:169], v[24:27]
	v_mfma_f32_16x16x32_bf16 v[24:27], v[12:15], v[162:165], v[192:195]
	v_mfma_f32_16x16x32_bf16 v[60:63], v[184:187], v[166:169], v[24:27]
	s_waitcnt lgkmcnt(5)
	v_mfma_f32_16x16x32_bf16 v[24:27], v[0:3], v[170:173], v[52:55]
	s_waitcnt lgkmcnt(4)
	v_mfma_f32_16x16x32_bf16 v[40:43], v[8:11], v[176:179], v[24:27]
	v_mfma_f32_16x16x32_bf16 v[24:27], v[12:15], v[170:173], v[48:51]
	v_mfma_f32_16x16x32_bf16 v[44:47], v[184:187], v[176:179], v[24:27]
	s_waitcnt lgkmcnt(3)
	v_mfma_f32_16x16x32_bf16 v[24:27], v[0:3], v[188:191], v[216:219]
	s_waitcnt lgkmcnt(1)
	v_mfma_f32_16x16x32_bf16 v[0:3], v[0:3], v[212:215], v[36:39]
	v_mfma_f32_16x16x32_bf16 v[24:27], v[8:11], v[208:211], v[24:27]
	v_mfma_f32_16x16x32_bf16 v[28:31], v[12:15], v[188:191], v[220:223]
	s_waitcnt lgkmcnt(0)
	v_mfma_f32_16x16x32_bf16 v[8:11], v[8:11], v[228:231], v[0:3]
	v_mfma_f32_16x16x32_bf16 v[0:3], v[12:15], v[212:215], v[32:35]
	v_mfma_f32_16x16x32_bf16 v[28:31], v[184:187], v[208:211], v[28:31]
	v_mfma_f32_16x16x32_bf16 v[12:15], v[184:187], v[228:231], v[0:3]
	s_setprio 0
	s_setprio 1
	v_mfma_f32_16x16x32_bf16 v[0:3], v[196:199], v[162:165], v[130:133]
	v_mfma_f32_16x16x32_bf16 v[48:51], v[200:203], v[166:169], v[0:3]
	v_mfma_f32_16x16x32_bf16 v[0:3], v[204:207], v[162:165], v[146:149]
	v_mfma_f32_16x16x32_bf16 v[52:55], v[224:227], v[166:169], v[0:3]
	v_mfma_f32_16x16x32_bf16 v[0:3], v[196:199], v[170:173], v[20:23]
	v_mfma_f32_16x16x32_bf16 v[32:35], v[200:203], v[176:179], v[0:3]
	v_mfma_f32_16x16x32_bf16 v[0:3], v[204:207], v[170:173], v[16:19]
	v_mfma_f32_16x16x32_bf16 v[36:39], v[224:227], v[176:179], v[0:3]
	v_mfma_f32_16x16x32_bf16 v[0:3], v[196:199], v[188:191], v[150:153]
	v_mfma_f32_16x16x32_bf16 v[16:19], v[200:203], v[208:211], v[0:3]
	v_mfma_f32_16x16x32_bf16 v[0:3], v[204:207], v[188:191], v[154:157]
	v_mfma_f32_16x16x32_bf16 v[20:23], v[224:227], v[208:211], v[0:3]
	v_mfma_f32_16x16x32_bf16 v[0:3], v[196:199], v[212:215], v[4:7]
	v_mfma_f32_16x16x32_bf16 v[4:7], v[204:207], v[212:215], v[180:183]
	v_mfma_f32_16x16x32_bf16 v[0:3], v[200:203], v[228:231], v[0:3]
	v_mfma_f32_16x16x32_bf16 v[4:7], v[224:227], v[228:231], v[4:7]
	s_setprio 0
	s_andn2_b64 vcc, exec, s[30:31]
	s_barrier
	s_cbranch_vccnz .LBB0_234
	s_barrier

; #define LDA(dst, b, h)                                                                                               \
;   _Pragma("unroll") for (int m = 0; m < 4; ++m) _Pragma("unroll") for (int k = 0; k < 2; ++k) dst[m][k] =            \
;       *reinterpret_cast<const bf16x8*>(SA(b, h) + lds_byte(wr * 64 + m * 16 + fr, k * 32 + fq * 8))
; #define LDB(dst, b, h)                                                                                               \
;   _Pragma("unroll") for (int n = 0; n < 2; ++n) _Pragma("unroll") for (int k = 0; k < 2; ++k) dst[n][k] =            \
;       *reinterpret_cast<const bf16x8*>(SB(b, h) + lds_byte(wc * 32 + n * 16 + fr, k * 32 + fq * 8))
; #define WAIT_V(n) asm volatile("s_waitcnt vmcnt(" #n ")" ::: "memory")
; #define WAIT_L(n) asm volatile("s_waitcnt lgkmcnt(" #n ")" ::: "memory")
; #define BAR __builtin_amdgcn_s_barrier()
; #define SCHED __builtin_amdgcn_sched_barrier(0)
; template <int EPI>
; __device__ __forceinline__ void gemm_phase(const u16* __restrict__ A, const u16* __restrict__ Bt, const int K,
;                                            const int nN, char* shm, const EpiArgs& ea) {
;     ...
;     for (int t = 0; t < nt - 2; t += 2) {
;       LDB(B0, 0, 0); SCHED; LDA(At, 0, 0); STAGE(SA(1, 1), rA, brow + HALF, t + 1);
;       WAIT_V(10); WAIT_L(8); BAR; WAIT_L(0); MMA(0, 0, At, B0); BAR; SCHED;
;       LDB(B1, 0, 1); STAGE(SB(0, 0), rB, bcol, t + 2);
;       WAIT_V(10); BAR; WAIT_L(0); MMA(0, 1, At, B1); BAR;
;       LDA(At, 0, 1); STAGE(SA(0, 0), rA, brow, t + 2);
;       BAR; WAIT_L(0); MMA(1, 0, At, B0); BAR; SCHED;
;       STAGE(SB(0, 1), rB, bcol + HALF, t + 2);
;       WAIT_V(10); BAR; MMA(1, 1, At, B1); BAR;
;       LDB(B0, 1, 0); SCHED; LDA(At, 1, 0); STAGE(SA(0, 1), rA, brow + HALF, t + 2);
;       WAIT_V(10); WAIT_L(8); BAR; WAIT_L(0); MMA(0, 0, At, B0); BAR; SCHED;
;       LDB(B1, 1, 1); STAGE(SB(1, 0), rB, bcol, t + 3);
;       WAIT_V(10); BAR; WAIT_L(0); MMA(0, 1, At, B1); BAR;
;       LDA(At, 1, 1); STAGE(SA(1, 0), rA, brow, t + 3);
;       BAR; WAIT_L(0); MMA(1, 0, At, B0); BAR; SCHED;
;       STAGE(SB(1, 1), rB, bcol + HALF, t + 3);
;       WAIT_V(10); BAR; MMA(1, 1, At, B1); BAR;
;     }
.LBB0_306:
	ds_read_b128 v[128:131], v168
	ds_read_b128 v[132:135], v168 offset:1024
	ds_read_b128 v[136:139], v168 offset:2048
	ds_read_b128 v[140:143], v168 offset:3072
	s_add_i32 s79, s72, s78
	s_mov_b32 m0, s52
	s_add_i32 s26, s79, 0x4000
	ds_read_b128 v[144:147], v169
	ds_read_b128 v[148:151], v169 offset:1024
	ds_read_b128 v[152:155], v170
	ds_read_b128 v[156:159], v170 offset:1024
	ds_read_b128 v[180:183], v171
	ds_read_b128 v[184:187], v171 offset:1024
	ds_read_b128 v[188:191], v172
	ds_read_b128 v[192:195], v172 offset:1024
	buffer_load_dwordx4 v161, s[0:3], s26 offen lds
	s_add_i32 s26, s79, 0x6000
	s_mov_b32 m0, s53
	s_nop 0
	buffer_load_dwordx4 v161, s[0:3], s26 offen lds
	s_waitcnt vmcnt(10)
	s_waitcnt lgkmcnt(8)
	s_barrier
	s_setprio 1
	s_waitcnt lgkmcnt(7)
	v_mfma_f32_16x16x32_bf16 v[124:127], v[128:131], v[144:147], v[124:127]
	v_mfma_f32_16x16x32_bf16 v[120:123], v[136:139], v[144:147], v[120:123]
	s_waitcnt lgkmcnt(5)
	v_mfma_f32_16x16x32_bf16 v[116:119], v[128:131], v[152:155], v[116:119]
	v_mfma_f32_16x16x32_bf16 v[112:115], v[136:139], v[152:155], v[112:115]
	s_waitcnt lgkmcnt(3)
	v_mfma_f32_16x16x32_bf16 v[108:111], v[128:131], v[180:183], v[108:111]
	v_mfma_f32_16x16x32_bf16 v[104:107], v[136:139], v[180:183], v[104:107]
	s_waitcnt lgkmcnt(1)
	v_mfma_f32_16x16x32_bf16 v[100:103], v[128:131], v[188:191], v[100:103]
	v_mfma_f32_16x16x32_bf16 v[96:99], v[136:139], v[188:191], v[96:99]
	v_mfma_f32_16x16x32_bf16 v[124:127], v[132:135], v[148:151], v[124:127]
	v_mfma_f32_16x16x32_bf16 v[120:123], v[140:143], v[148:151], v[120:123]
	v_mfma_f32_16x16x32_bf16 v[116:119], v[132:135], v[156:159], v[116:119]
	v_mfma_f32_16x16x32_bf16 v[112:115], v[140:143], v[156:159], v[112:115]
	v_mfma_f32_16x16x32_bf16 v[108:111], v[132:135], v[184:187], v[108:111]
	v_mfma_f32_16x16x32_bf16 v[104:107], v[140:143], v[184:187], v[104:107]
	s_waitcnt lgkmcnt(0)
	v_mfma_f32_16x16x32_bf16 v[100:103], v[132:135], v[192:195], v[100:103]
	v_mfma_f32_16x16x32_bf16 v[96:99], v[140:143], v[192:195], v[96:99]
	s_setprio 0
	s_barrier
	s_add_i32 s80, s74, s78
	s_mov_b32 m0, s54
	s_add_i32 s81, s80, 0x8000
	s_mov_b32 s26, s2
	s_mov_b32 s27, s3
	ds_read_b128 v[196:199], v173
	ds_read_b128 v[200:203], v173 offset:1024
	ds_read_b128 v[204:207], v173 offset:2048
	ds_read_b128 v[208:211], v173 offset:3072
	buffer_load_dwordx4 v161, s[24:27], s81 offen lds
	s_add_i32 s81, s80, 0xa000
	s_mov_b32 m0, s55
	s_nop 0
	buffer_load_dwordx4 v161, s[24:27], s81 offen lds
	s_waitcnt vmcnt(10)
	s_barrier
	s_setprio 1
	s_waitcnt lgkmcnt(3)
	v_mfma_f32_16x16x32_bf16 v[92:95], v[196:199], v[144:147], v[92:95]
	s_waitcnt lgkmcnt(1)
	v_mfma_f32_16x16x32_bf16 v[88:91], v[204:207], v[144:147], v[88:91]
	v_mfma_f32_16x16x32_bf16 v[84:87], v[196:199], v[152:155], v[84:87]
	v_mfma_f32_16x16x32_bf16 v[80:83], v[204:207], v[152:155], v[80:83]
	v_mfma_f32_16x16x32_bf16 v[76:79], v[196:199], v[180:183], v[76:79]
	v_mfma_f32_16x16x32_bf16 v[72:75], v[204:207], v[180:183], v[72:75]
	v_mfma_f32_16x16x32_bf16 v[68:71], v[196:199], v[188:191], v[68:71]
	v_mfma_f32_16x16x32_bf16 v[64:67], v[204:207], v[188:191], v[64:67]
	v_mfma_f32_16x16x32_bf16 v[92:95], v[200:203], v[148:151], v[92:95]
	s_waitcnt lgkmcnt(0)
	v_mfma_f32_16x16x32_bf16 v[88:91], v[208:211], v[148:151], v[88:91]
	v_mfma_f32_16x16x32_bf16 v[84:87], v[200:203], v[156:159], v[84:87]
	v_mfma_f32_16x16x32_bf16 v[80:83], v[208:211], v[156:159], v[80:83]
	v_mfma_f32_16x16x32_bf16 v[76:79], v[200:203], v[184:187], v[76:79]
	v_mfma_f32_16x16x32_bf16 v[72:75], v[208:211], v[184:187], v[72:75]
	v_mfma_f32_16x16x32_bf16 v[68:71], v[200:203], v[192:195], v[68:71]
	v_mfma_f32_16x16x32_bf16 v[64:67], v[208:211], v[192:195], v[64:67]
	s_setprio 0
	s_add_i32 s81, s73, s78
	s_mov_b32 m0, s49
	s_add_i32 s82, s81, 0x8000
	s_barrier
	ds_read_b128 v[144:147], v169 offset:16384
	ds_read_b128 v[148:151], v169 offset:17408
	ds_read_b128 v[152:155], v170 offset:16384
	ds_read_b128 v[156:159], v170 offset:17408
	ds_read_b128 v[180:183], v171 offset:16384
	ds_read_b128 v[184:187], v171 offset:17408
	ds_read_b128 v[188:191], v172 offset:16384
	ds_read_b128 v[192:195], v172 offset:17408
	buffer_load_dwordx4 v161, s[0:3], s82 offen lds
	s_add_i32 s82, s81, 0xa000
	s_mov_b32 m0, s56
	s_nop 0
	buffer_load_dwordx4 v161, s[0:3], s82 offen lds
	s_barrier
	s_setprio 1
	s_waitcnt lgkmcnt(7)
	v_mfma_f32_16x16x32_bf16 v[60:63], v[128:131], v[144:147], v[60:63]
	v_mfma_f32_16x16x32_bf16 v[56:59], v[136:139], v[144:147], v[56:59]
	s_waitcnt lgkmcnt(5)
	v_mfma_f32_16x16x32_bf16 v[52:55], v[128:131], v[152:155], v[52:55]
	v_mfma_f32_16x16x32_bf16 v[48:51], v[136:139], v[152:155], v[48:51]
	s_waitcnt lgkmcnt(3)
	v_mfma_f32_16x16x32_bf16 v[44:47], v[128:131], v[180:183], v[44:47]
	v_mfma_f32_16x16x32_bf16 v[40:43], v[136:139], v[180:183], v[40:43]
	s_waitcnt lgkmcnt(1)
	v_mfma_f32_16x16x32_bf16 v[36:39], v[128:131], v[188:191], v[36:39]
	v_mfma_f32_16x16x32_bf16 v[32:35], v[136:139], v[188:191], v[32:35]
	v_mfma_f32_16x16x32_bf16 v[60:63], v[132:135], v[148:151], v[60:63]
	v_mfma_f32_16x16x32_bf16 v[56:59], v[140:143], v[148:151], v[56:59]
	v_mfma_f32_16x16x32_bf16 v[52:55], v[132:135], v[156:159], v[52:55]
	v_mfma_f32_16x16x32_bf16 v[48:51], v[140:143], v[156:159], v[48:51]
	v_mfma_f32_16x16x32_bf16 v[44:47], v[132:135], v[184:187], v[44:47]
	v_mfma_f32_16x16x32_bf16 v[40:43], v[140:143], v[184:187], v[40:43]
	s_waitcnt lgkmcnt(0)
	v_mfma_f32_16x16x32_bf16 v[36:39], v[132:135], v[192:195], v[36:39]
	v_mfma_f32_16x16x32_bf16 v[32:35], v[140:143], v[192:195], v[32:35]
	s_setprio 0
	s_barrier
; #define LDA(dst, b, h)                                                                                               \
;   _Pragma("unroll") for (int m = 0; m < 4; ++m) _Pragma("unroll") for (int k = 0; k < 2; ++k) dst[m][k] =            \
;       *reinterpret_cast<const bf16x8*>(SA(b, h) + lds_byte(wr * 64 + m * 16 + fr, k * 32 + fq * 8))
; #define LDB(dst, b, h)                                                                                               \
;   _Pragma("unroll") for (int n = 0; n < 2; ++n) _Pragma("unroll") for (int k = 0; k < 2; ++k) dst[n][k] =            \
;       *reinterpret_cast<const bf16x8*>(SB(b, h) + lds_byte(wc * 32 + n * 16 + fr, k * 32 + fq * 8))
; #define WAIT_V(n) asm volatile("s_waitcnt vmcnt(" #n ")" ::: "memory")
; #define WAIT_L(n) asm volatile("s_waitcnt lgkmcnt(" #n ")" ::: "memory")
; #define BAR __builtin_amdgcn_s_barrier()
; #define SCHED __builtin_amdgcn_sched_barrier(0)
; template <int EPI>
; __device__ __forceinline__ void gemm_phase(const u16* __restrict__ A, const u16* __restrict__ Bt, const int K,
;                                            const int nN, char* shm, const EpiArgs& ea) {
;     ...
;     for (int t = 0; t < nt - 2; t += 2) {
;       LDB(B0, 0, 0); SCHED; LDA(At, 0, 0); STAGE(SA(1, 1), rA, brow + HALF, t + 1);
;       WAIT_V(10); WAIT_L(8); BAR; WAIT_L(0); MMA(0, 0, At, B0); BAR; SCHED;
;       LDB(B1, 0, 1); STAGE(SB(0, 0), rB, bcol, t + 2);
;       WAIT_V(10); BAR; WAIT_L(0); MMA(0, 1, At, B1); BAR;
;       LDA(At, 0, 1); STAGE(SA(0, 0), rA, brow, t + 2);
;       BAR; WAIT_L(0); MMA(1, 0, At, B0); BAR; SCHED;
;       STAGE(SB(0, 1), rB, bcol + HALF, t + 2);
;       WAIT_V(10); BAR; MMA(1, 1, At, B1); BAR;
;       LDB(B0, 1, 0); SCHED; LDA(At, 1, 0); STAGE(SA(0, 1), rA, brow + HALF, t + 2);
;       WAIT_V(10); WAIT_L(8); BAR; WAIT_L(0); MMA(0, 0, At, B0); BAR; SCHED;
;       LDB(B1, 1, 1); STAGE(SB(1, 0), rB, bcol, t + 3);
;       WAIT_V(10); BAR; WAIT_L(0); MMA(0, 1, At, B1); BAR;
;       LDA(At, 1, 1); STAGE(SA(1, 0), rA, brow, t + 3);
;       BAR; WAIT_L(0); MMA(1, 0, At, B0); BAR; SCHED;
;       STAGE(SB(1, 1), rB, bcol + HALF, t + 3);
;       WAIT_V(10); BAR; MMA(1, 1, At, B1); BAR;
;     }
	s_add_i32 s82, s43, s78
	s_mov_b32 m0, s57
	s_add_i32 s83, s82, 0x8000
	buffer_load_dwordx4 v161, s[24:27], s83 offen lds
	s_add_i32 s83, s82, 0xa000
	s_mov_b32 m0, s58
	s_nop 0
	buffer_load_dwordx4 v161, s[24:27], s83 offen lds
	s_waitcnt vmcnt(10)
	s_barrier
	s_setprio 1
	v_mfma_f32_16x16x32_bf16 v[28:31], v[196:199], v[144:147], v[28:31]
	v_mfma_f32_16x16x32_bf16 v[24:27], v[204:207], v[144:147], v[24:27]
	v_mfma_f32_16x16x32_bf16 v[20:23], v[196:199], v[152:155], v[20:23]
	v_mfma_f32_16x16x32_bf16 v[16:19], v[204:207], v[152:155], v[16:19]
	v_mfma_f32_16x16x32_bf16 v[12:15], v[196:199], v[180:183], v[12:15]
	v_mfma_f32_16x16x32_bf16 v[8:11], v[204:207], v[180:183], v[8:11]
	v_mfma_f32_16x16x32_bf16 v[4:7], v[196:199], v[188:191], v[4:7]
	v_mfma_f32_16x16x32_bf16 v[0:3], v[204:207], v[188:191], v[0:3]
	v_mfma_f32_16x16x32_bf16 v[28:31], v[200:203], v[148:151], v[28:31]
	v_mfma_f32_16x16x32_bf16 v[24:27], v[208:211], v[148:151], v[24:27]
	v_mfma_f32_16x16x32_bf16 v[20:23], v[200:203], v[156:159], v[20:23]
	v_mfma_f32_16x16x32_bf16 v[16:19], v[208:211], v[156:159], v[16:19]
	v_mfma_f32_16x16x32_bf16 v[12:15], v[200:203], v[184:187], v[12:15]
	v_mfma_f32_16x16x32_bf16 v[8:11], v[208:211], v[184:187], v[8:11]
	v_mfma_f32_16x16x32_bf16 v[4:7], v[200:203], v[192:195], v[4:7]
	v_mfma_f32_16x16x32_bf16 v[0:3], v[208:211], v[192:195], v[0:3]
	s_setprio 0
	s_barrier
	ds_read_b128 v[128:131], v176
	ds_read_b128 v[132:135], v176 offset:1024
	ds_read_b128 v[136:139], v176 offset:2048
	ds_read_b128 v[140:143], v176 offset:3072
	s_mov_b32 m0, s59
	s_add_i32 s83, s79, 0x8000
	ds_read_b128 v[144:147], v169 offset:32768
	ds_read_b128 v[148:151], v169 offset:33792
	ds_read_b128 v[152:155], v170 offset:32768
	ds_read_b128 v[156:159], v170 offset:33792
	ds_read_b128 v[180:183], v171 offset:32768
	ds_read_b128 v[184:187], v171 offset:33792
	ds_read_b128 v[188:191], v172 offset:32768
	ds_read_b128 v[192:195], v172 offset:33792
	buffer_load_dwordx4 v161, s[0:3], s83 offen lds
	s_add_i32 s79, s79, 0xa000
	s_mov_b32 m0, s60
	s_nop 0
	buffer_load_dwordx4 v161, s[0:3], s79 offen lds
	s_waitcnt vmcnt(10)
	s_waitcnt lgkmcnt(8)
	s_barrier
	s_setprio 1
	s_waitcnt lgkmcnt(7)
	v_mfma_f32_16x16x32_bf16 v[124:127], v[128:131], v[144:147], v[124:127]
	v_mfma_f32_16x16x32_bf16 v[120:123], v[136:139], v[144:147], v[120:123]
	s_waitcnt lgkmcnt(5)
	v_mfma_f32_16x16x32_bf16 v[116:119], v[128:131], v[152:155], v[116:119]
	v_mfma_f32_16x16x32_bf16 v[112:115], v[136:139], v[152:155], v[112:115]
	s_waitcnt lgkmcnt(3)
	v_mfma_f32_16x16x32_bf16 v[108:111], v[128:131], v[180:183], v[108:111]
	v_mfma_f32_16x16x32_bf16 v[104:107], v[136:139], v[180:183], v[104:107]
	s_waitcnt lgkmcnt(1)
	v_mfma_f32_16x16x32_bf16 v[100:103], v[128:131], v[188:191], v[100:103]
	v_mfma_f32_16x16x32_bf16 v[96:99], v[136:139], v[188:191], v[96:99]
	v_mfma_f32_16x16x32_bf16 v[124:127], v[132:135], v[148:151], v[124:127]
	v_mfma_f32_16x16x32_bf16 v[120:123], v[140:143], v[148:151], v[120:123]
	v_mfma_f32_16x16x32_bf16 v[116:119], v[132:135], v[156:159], v[116:119]
	v_mfma_f32_16x16x32_bf16 v[112:115], v[140:143], v[156:159], v[112:115]
	v_mfma_f32_16x16x32_bf16 v[108:111], v[132:135], v[184:187], v[108:111]
	v_mfma_f32_16x16x32_bf16 v[104:107], v[140:143], v[184:187], v[104:107]
	s_waitcnt lgkmcnt(0)
	v_mfma_f32_16x16x32_bf16 v[100:103], v[132:135], v[192:195], v[100:103]
	v_mfma_f32_16x16x32_bf16 v[96:99], v[140:143], v[192:195], v[96:99]
	s_setprio 0
	s_barrier
	s_mov_b32 m0, s61
	s_add_i32 s79, s80, 0xc000
	ds_read_b128 v[196:199], v177
	ds_read_b128 v[200:203], v177 offset:1024
	ds_read_b128 v[204:207], v177 offset:2048
	ds_read_b128 v[208:211], v177 offset:3072
	buffer_load_dwordx4 v161, s[24:27], s79 offen lds
	s_add_i32 s80, s80, 0xe000
	s_mov_b32 m0, s62
	s_nop 0
	buffer_load_dwordx4 v161, s[24:27], s80 offen lds
	s_waitcnt vmcnt(10)
	s_barrier
; #define LDA(dst, b, h)                                                                                               \
;   _Pragma("unroll") for (int m = 0; m < 4; ++m) _Pragma("unroll") for (int k = 0; k < 2; ++k) dst[m][k] =            \
;       *reinterpret_cast<const bf16x8*>(SA(b, h) + lds_byte(wr * 64 + m * 16 + fr, k * 32 + fq * 8))
; #define LDB(dst, b, h)                                                                                               \
;   _Pragma("unroll") for (int n = 0; n < 2; ++n) _Pragma("unroll") for (int k = 0; k < 2; ++k) dst[n][k] =            \
;       *reinterpret_cast<const bf16x8*>(SB(b, h) + lds_byte(wc * 32 + n * 16 + fr, k * 32 + fq * 8))
; #define WAIT_V(n) asm volatile("s_waitcnt vmcnt(" #n ")" ::: "memory")
; #define WAIT_L(n) asm volatile("s_waitcnt lgkmcnt(" #n ")" ::: "memory")
; #define BAR __builtin_amdgcn_s_barrier()
; #define SCHED __builtin_amdgcn_sched_barrier(0)
; template <int EPI>
; __device__ __forceinline__ void gemm_phase(const u16* __restrict__ A, const u16* __restrict__ Bt, const int K,
;                                            const int nN, char* shm, const EpiArgs& ea) {
;     ...
;       WAIT_V(10); BAR; MMA(1, 1, At, B1); BAR;
;       LDB(B0, 1, 0); SCHED; LDA(At, 1, 0); STAGE(SA(0, 1), rA, brow + HALF, t + 2);
;       WAIT_V(10); WAIT_L(8); BAR; WAIT_L(0); MMA(0, 0, At, B0); BAR; SCHED;
;       LDB(B1, 1, 1); STAGE(SB(1, 0), rB, bcol, t + 3);
;       WAIT_V(10); BAR; WAIT_L(0); MMA(0, 1, At, B1); BAR;
;       LDA(At, 1, 1); STAGE(SA(1, 0), rA, brow, t + 3);
;       BAR; WAIT_L(0); MMA(1, 0, At, B0); BAR; SCHED;
;       STAGE(SB(1, 1), rB, bcol + HALF, t + 3);
;       WAIT_V(10); BAR; MMA(1, 1, At, B1); BAR;
;     }
;     ...
;     if (EPI == EPI_IN || EPI == EPI_SWIGLU_LN) {
;       if (wr == 0) {
;         eC = ea.c1[bcol + tid];
;         eS = *(const float2*)(ea.st_in + (size_t)(brow + tid) * 2);
;       } else {
;         eC = ea.c2[bcol + tid - 256];
;         if (EPI == EPI_IN) eB = ea.bias[bcol + tid - 256];
;       }
;     }
	s_setprio 1
	s_waitcnt lgkmcnt(3)
	v_mfma_f32_16x16x32_bf16 v[92:95], v[196:199], v[144:147], v[92:95]
	s_waitcnt lgkmcnt(1)
	v_mfma_f32_16x16x32_bf16 v[88:91], v[204:207], v[144:147], v[88:91]
	v_mfma_f32_16x16x32_bf16 v[84:87], v[196:199], v[152:155], v[84:87]
	v_mfma_f32_16x16x32_bf16 v[80:83], v[204:207], v[152:155], v[80:83]
	v_mfma_f32_16x16x32_bf16 v[76:79], v[196:199], v[180:183], v[76:79]
	v_mfma_f32_16x16x32_bf16 v[72:75], v[204:207], v[180:183], v[72:75]
	v_mfma_f32_16x16x32_bf16 v[68:71], v[196:199], v[188:191], v[68:71]
	v_mfma_f32_16x16x32_bf16 v[64:67], v[204:207], v[188:191], v[64:67]
	v_mfma_f32_16x16x32_bf16 v[92:95], v[200:203], v[148:151], v[92:95]
	s_waitcnt lgkmcnt(0)
	v_mfma_f32_16x16x32_bf16 v[88:91], v[208:211], v[148:151], v[88:91]
	v_mfma_f32_16x16x32_bf16 v[84:87], v[200:203], v[156:159], v[84:87]
	v_mfma_f32_16x16x32_bf16 v[80:83], v[208:211], v[156:159], v[80:83]
	v_mfma_f32_16x16x32_bf16 v[76:79], v[200:203], v[184:187], v[76:79]
	v_mfma_f32_16x16x32_bf16 v[72:75], v[208:211], v[184:187], v[72:75]
	v_mfma_f32_16x16x32_bf16 v[68:71], v[200:203], v[192:195], v[68:71]
	v_mfma_f32_16x16x32_bf16 v[64:67], v[208:211], v[192:195], v[64:67]
	s_setprio 0
	s_mov_b32 m0, s63
	s_add_i32 s79, s81, 0xc000
	s_barrier
	ds_read_b128 v[144:147], v169 offset:49152
	ds_read_b128 v[148:151], v169 offset:50176
	ds_read_b128 v[152:155], v170 offset:49152
	ds_read_b128 v[156:159], v170 offset:50176
	ds_read_b128 v[180:183], v171 offset:49152
	ds_read_b128 v[184:187], v171 offset:50176
	ds_read_b128 v[188:191], v172 offset:49152
	ds_read_b128 v[192:195], v172 offset:50176
	buffer_load_dwordx4 v161, s[0:3], s79 offen lds
	s_add_i32 s81, s81, 0xe000
	s_mov_b32 m0, s64
	s_nop 0
	buffer_load_dwordx4 v161, s[0:3], s81 offen lds
	s_barrier
	s_setprio 1
	s_waitcnt lgkmcnt(7)
	v_mfma_f32_16x16x32_bf16 v[60:63], v[128:131], v[144:147], v[60:63]
	v_mfma_f32_16x16x32_bf16 v[56:59], v[136:139], v[144:147], v[56:59]
	s_waitcnt lgkmcnt(5)
	v_mfma_f32_16x16x32_bf16 v[52:55], v[128:131], v[152:155], v[52:55]
	v_mfma_f32_16x16x32_bf16 v[48:51], v[136:139], v[152:155], v[48:51]
	s_waitcnt lgkmcnt(3)
	v_mfma_f32_16x16x32_bf16 v[44:47], v[128:131], v[180:183], v[44:47]
	v_mfma_f32_16x16x32_bf16 v[40:43], v[136:139], v[180:183], v[40:43]
	s_waitcnt lgkmcnt(1)
	v_mfma_f32_16x16x32_bf16 v[36:39], v[128:131], v[188:191], v[36:39]
	v_mfma_f32_16x16x32_bf16 v[32:35], v[136:139], v[188:191], v[32:35]
	v_mfma_f32_16x16x32_bf16 v[60:63], v[132:135], v[148:151], v[60:63]
	v_mfma_f32_16x16x32_bf16 v[56:59], v[140:143], v[148:151], v[56:59]
	v_mfma_f32_16x16x32_bf16 v[52:55], v[132:135], v[156:159], v[52:55]
	v_mfma_f32_16x16x32_bf16 v[48:51], v[140:143], v[156:159], v[48:51]
	v_mfma_f32_16x16x32_bf16 v[44:47], v[132:135], v[184:187], v[44:47]
	v_mfma_f32_16x16x32_bf16 v[40:43], v[140:143], v[184:187], v[40:43]
	s_waitcnt lgkmcnt(0)
	v_mfma_f32_16x16x32_bf16 v[36:39], v[132:135], v[192:195], v[36:39]
	v_mfma_f32_16x16x32_bf16 v[32:35], v[140:143], v[192:195], v[32:35]
	s_setprio 0
	s_barrier
	s_mov_b32 m0, s65
	s_add_i32 s79, s82, 0xc000
	buffer_load_dwordx4 v161, s[24:27], s79 offen lds
	s_add_i32 s82, s82, 0xe000
	s_mov_b32 m0, s66
	s_nop 0
	buffer_load_dwordx4 v161, s[24:27], s82 offen lds
	s_waitcnt vmcnt(10)
	s_barrier
	s_setprio 1
	v_mfma_f32_16x16x32_bf16 v[28:31], v[196:199], v[144:147], v[28:31]
	v_mfma_f32_16x16x32_bf16 v[24:27], v[204:207], v[144:147], v[24:27]
	v_mfma_f32_16x16x32_bf16 v[20:23], v[196:199], v[152:155], v[20:23]
	v_mfma_f32_16x16x32_bf16 v[16:19], v[204:207], v[152:155], v[16:19]
	v_mfma_f32_16x16x32_bf16 v[12:15], v[196:199], v[180:183], v[12:15]
	v_mfma_f32_16x16x32_bf16 v[8:11], v[204:207], v[180:183], v[8:11]
	v_mfma_f32_16x16x32_bf16 v[4:7], v[196:199], v[188:191], v[4:7]
	v_mfma_f32_16x16x32_bf16 v[0:3], v[204:207], v[188:191], v[0:3]
	v_mfma_f32_16x16x32_bf16 v[28:31], v[200:203], v[148:151], v[28:31]
	v_mfma_f32_16x16x32_bf16 v[24:27], v[208:211], v[148:151], v[24:27]
	v_mfma_f32_16x16x32_bf16 v[20:23], v[200:203], v[156:159], v[20:23]
	v_mfma_f32_16x16x32_bf16 v[16:19], v[208:211], v[156:159], v[16:19]
	v_mfma_f32_16x16x32_bf16 v[12:15], v[200:203], v[184:187], v[12:15]
	v_mfma_f32_16x16x32_bf16 v[8:11], v[208:211], v[184:187], v[8:11]
	v_mfma_f32_16x16x32_bf16 v[4:7], v[200:203], v[192:195], v[4:7]
	v_mfma_f32_16x16x32_bf16 v[0:3], v[208:211], v[192:195], v[0:3]
	s_setprio 0
	s_add_i32 s75, s75, 2
	s_add_i32 s78, s78, 0x8000
	s_cmp_lt_u32 s75, 28
	s_barrier
	s_cbranch_scc1 .LBB0_306
	s_mov_b64 s[26:27], -1
	s_and_b64 vcc, exec, s[38:39]
	s_cbranch_vccz .LBB0_309
	s_ashr_i32 s43, s42, 31
	v_lshl_add_u64 v[128:129], v[174:175], 0, s[42:43]
	v_lshl_add_u64 v[128:129], v[128:129], 2, s[50:51]
	global_load_dword v150, v[128:129], off offset:-1024
	v_add_u32_e32 v128, s42, v163
	v_ashrrev_i32_e32 v129, 31, v128
	v_lshl_add_u64 v[128:129], v[128:129], 2, s[18:19]
	s_mov_b64 s[26:27], 0

; #define LDA(dst, b, h)                                                                                               \
;   _Pragma("unroll") for (int m = 0; m < 4; ++m) _Pragma("unroll") for (int k = 0; k < 2; ++k) dst[m][k] =            \
;       *reinterpret_cast<const bf16x8*>(SA(b, h) + lds_byte(wr * 64 + m * 16 + fr, k * 32 + fq * 8))
; #define LDB(dst, b, h)                                                                                               \
;   _Pragma("unroll") for (int n = 0; n < 2; ++n) _Pragma("unroll") for (int k = 0; k < 2; ++k) dst[n][k] =            \
;       *reinterpret_cast<const bf16x8*>(SB(b, h) + lds_byte(wc * 32 + n * 16 + fr, k * 32 + fq * 8))
; #define WAIT_V(n) asm volatile("s_waitcnt vmcnt(" #n ")" ::: "memory")
; #define WAIT_L(n) asm volatile("s_waitcnt lgkmcnt(" #n ")" ::: "memory")
; #define BAR __builtin_amdgcn_s_barrier()
; template <int EPI>
; __device__ __forceinline__ void gemm_phase(const u16* __restrict__ A, const u16* __restrict__ Bt, const int K,
;                                            const int nN, char* shm, const EpiArgs& ea) {
;     ...
;         if (EPI == EPI_IN) eB = ea.bias[bcol + tid - 256];
;       }
;     }
;     {
;       LDB(B0, 0, 0); LDA(At, 0, 0); STAGE(SA(1, 1), rA, brow + HALF, nt - 1);
;       WAIT_V(10); BAR; WAIT_L(0); MMA(0, 0, At, B0); BAR;
;       LDB(B1, 0, 1); WAIT_V(8); BAR; WAIT_L(0); MMA(0, 1, At, B1); BAR;
;       LDA(At, 0, 1); WAIT_V(4); BAR; WAIT_L(0); MMA(1, 0, At, B0); MMA(1, 1, At, B1); BAR;
;     }
.LBB0_311:
	s_mov_b32 m0, s52
	s_add_i32 s26, s72, 0x7c000
	global_load_dword v151, v[128:129], off
	ds_read_b128 v[128:131], v168
	ds_read_b128 v[132:135], v168 offset:1024
	ds_read_b128 v[136:139], v168 offset:2048
	ds_read_b128 v[140:143], v168 offset:3072
	ds_read_b128 v[144:147], v169
	ds_read_b128 v[152:155], v169 offset:1024
	ds_read_b128 v[156:159], v170
	ds_read_b128 v[180:183], v170 offset:1024
	ds_read_b128 v[184:187], v171
	ds_read_b128 v[188:191], v171 offset:1024
	ds_read_b128 v[192:195], v172
	ds_read_b128 v[196:199], v172 offset:1024
	buffer_load_dwordx4 v161, s[0:3], s26 offen lds
	s_add_i32 s72, s72, 0x7e000
	s_mov_b32 m0, s53
	s_nop 0
	buffer_load_dwordx4 v161, s[0:3], s72 offen lds
	s_waitcnt vmcnt(10)
	s_barrier
	s_setprio 1
	s_waitcnt lgkmcnt(7)
	v_mfma_f32_16x16x32_bf16 v[124:127], v[128:131], v[144:147], v[124:127]
	v_mfma_f32_16x16x32_bf16 v[120:123], v[136:139], v[144:147], v[120:123]
	s_waitcnt lgkmcnt(5)
	v_mfma_f32_16x16x32_bf16 v[116:119], v[128:131], v[156:159], v[116:119]
	v_mfma_f32_16x16x32_bf16 v[112:115], v[136:139], v[156:159], v[112:115]
	s_waitcnt lgkmcnt(3)
	v_mfma_f32_16x16x32_bf16 v[108:111], v[128:131], v[184:187], v[108:111]
	v_mfma_f32_16x16x32_bf16 v[104:107], v[136:139], v[184:187], v[104:107]
	s_waitcnt lgkmcnt(1)
	v_mfma_f32_16x16x32_bf16 v[100:103], v[128:131], v[192:195], v[100:103]
	v_mfma_f32_16x16x32_bf16 v[96:99], v[136:139], v[192:195], v[96:99]
	v_mfma_f32_16x16x32_bf16 v[124:127], v[132:135], v[152:155], v[124:127]
	v_mfma_f32_16x16x32_bf16 v[120:123], v[140:143], v[152:155], v[120:123]
	v_mfma_f32_16x16x32_bf16 v[116:119], v[132:135], v[180:183], v[116:119]
	v_mfma_f32_16x16x32_bf16 v[112:115], v[140:143], v[180:183], v[112:115]
	v_mfma_f32_16x16x32_bf16 v[108:111], v[132:135], v[188:191], v[108:111]
	v_mfma_f32_16x16x32_bf16 v[104:107], v[140:143], v[188:191], v[104:107]
	s_waitcnt lgkmcnt(0)
	v_mfma_f32_16x16x32_bf16 v[100:103], v[132:135], v[196:199], v[100:103]
	v_mfma_f32_16x16x32_bf16 v[96:99], v[140:143], v[196:199], v[96:99]
	s_setprio 0
	s_barrier
	ds_read_b128 v[200:203], v173
	ds_read_b128 v[204:207], v173 offset:1024
	ds_read_b128 v[208:211], v173 offset:2048
	ds_read_b128 v[212:215], v173 offset:3072
	s_waitcnt vmcnt(8)
	s_barrier
	s_setprio 1
	s_waitcnt lgkmcnt(3)
	v_mfma_f32_16x16x32_bf16 v[92:95], v[200:203], v[144:147], v[92:95]
	s_waitcnt lgkmcnt(1)
	v_mfma_f32_16x16x32_bf16 v[88:91], v[208:211], v[144:147], v[88:91]
	v_mfma_f32_16x16x32_bf16 v[84:87], v[200:203], v[156:159], v[84:87]
	v_mfma_f32_16x16x32_bf16 v[80:83], v[208:211], v[156:159], v[80:83]
	v_mfma_f32_16x16x32_bf16 v[76:79], v[200:203], v[184:187], v[76:79]
	v_mfma_f32_16x16x32_bf16 v[72:75], v[208:211], v[184:187], v[72:75]
	v_mfma_f32_16x16x32_bf16 v[68:71], v[200:203], v[192:195], v[68:71]
	v_mfma_f32_16x16x32_bf16 v[64:67], v[208:211], v[192:195], v[64:67]
	v_mfma_f32_16x16x32_bf16 v[92:95], v[204:207], v[152:155], v[92:95]
	s_waitcnt lgkmcnt(0)
	v_mfma_f32_16x16x32_bf16 v[88:91], v[212:215], v[152:155], v[88:91]
	v_mfma_f32_16x16x32_bf16 v[84:87], v[204:207], v[180:183], v[84:87]
	v_mfma_f32_16x16x32_bf16 v[80:83], v[212:215], v[180:183], v[80:83]
	v_mfma_f32_16x16x32_bf16 v[76:79], v[204:207], v[188:191], v[76:79]
	v_mfma_f32_16x16x32_bf16 v[72:75], v[212:215], v[188:191], v[72:75]
	v_mfma_f32_16x16x32_bf16 v[68:71], v[204:207], v[196:199], v[68:71]
	v_mfma_f32_16x16x32_bf16 v[64:67], v[212:215], v[196:199], v[64:67]
	s_setprio 0
	s_barrier
	ds_read_b128 v[144:147], v169 offset:16384
	ds_read_b128 v[152:155], v169 offset:17408
	ds_read_b128 v[156:159], v170 offset:16384
	ds_read_b128 v[180:183], v170 offset:17408
	ds_read_b128 v[184:187], v171 offset:16384
	ds_read_b128 v[188:191], v171 offset:17408
	ds_read_b128 v[192:195], v172 offset:16384
	ds_read_b128 v[196:199], v172 offset:17408
	s_waitcnt vmcnt(4)
	s_barrier
	s_setprio 1
	s_waitcnt lgkmcnt(7)
	v_mfma_f32_16x16x32_bf16 v[60:63], v[128:131], v[144:147], v[60:63]
	v_mfma_f32_16x16x32_bf16 v[56:59], v[136:139], v[144:147], v[56:59]
	s_waitcnt lgkmcnt(3)
	v_mfma_f32_16x16x32_bf16 v[40:43], v[136:139], v[184:187], v[40:43]
	v_mfma_f32_16x16x32_bf16 v[60:63], v[132:135], v[152:155], v[60:63]
	v_mfma_f32_16x16x32_bf16 v[56:59], v[140:143], v[152:155], v[56:59]
	v_mfma_f32_16x16x32_bf16 v[52:55], v[128:131], v[156:159], v[52:55]
	v_mfma_f32_16x16x32_bf16 v[48:51], v[136:139], v[156:159], v[48:51]
	v_mfma_f32_16x16x32_bf16 v[44:47], v[128:131], v[184:187], v[44:47]
	s_waitcnt lgkmcnt(2)
	v_mfma_f32_16x16x32_bf16 v[40:43], v[140:143], v[188:191], v[40:43]
	s_waitcnt lgkmcnt(1)
	v_mfma_f32_16x16x32_bf16 v[36:39], v[128:131], v[192:195], v[36:39]
	v_mfma_f32_16x16x32_bf16 v[32:35], v[136:139], v[192:195], v[32:35]
	v_mfma_f32_16x16x32_bf16 v[52:55], v[132:135], v[180:183], v[52:55]
	v_mfma_f32_16x16x32_bf16 v[216:219], v[140:143], v[180:183], v[48:51]
	v_mfma_f32_16x16x32_bf16 v[44:47], v[132:135], v[188:191], v[44:47]
	s_waitcnt lgkmcnt(0)
	v_mfma_f32_16x16x32_bf16 v[220:223], v[132:135], v[196:199], v[36:39]
	v_mfma_f32_16x16x32_bf16 v[32:35], v[140:143], v[196:199], v[32:35]
	s_setprio 0
	s_setprio 1
	v_mfma_f32_16x16x32_bf16 v[16:19], v[208:211], v[156:159], v[16:19]
	v_mfma_f32_16x16x32_bf16 v[4:7], v[200:203], v[192:195], v[4:7]
	v_mfma_f32_16x16x32_bf16 v[0:3], v[208:211], v[192:195], v[0:3]
	v_mfma_f32_16x16x32_bf16 v[28:31], v[200:203], v[144:147], v[28:31]
	v_mfma_f32_16x16x32_bf16 v[24:27], v[208:211], v[144:147], v[24:27]
	v_mfma_f32_16x16x32_bf16 v[20:23], v[200:203], v[156:159], v[20:23]
	v_mfma_f32_16x16x32_bf16 v[16:19], v[212:215], v[180:183], v[16:19]
	v_mfma_f32_16x16x32_bf16 v[12:15], v[200:203], v[184:187], v[12:15]
	v_mfma_f32_16x16x32_bf16 v[8:11], v[208:211], v[184:187], v[8:11]
	v_mfma_f32_16x16x32_bf16 v[4:7], v[204:207], v[196:199], v[4:7]
	v_mfma_f32_16x16x32_bf16 v[0:3], v[212:215], v[196:199], v[0:3]
	v_mfma_f32_16x16x32_bf16 v[224:227], v[204:207], v[152:155], v[28:31]
	v_mfma_f32_16x16x32_bf16 v[24:27], v[212:215], v[152:155], v[24:27]
	v_mfma_f32_16x16x32_bf16 v[20:23], v[204:207], v[180:183], v[20:23]
	v_mfma_f32_16x16x32_bf16 v[152:155], v[204:207], v[188:191], v[12:15]
	v_mfma_f32_16x16x32_bf16 v[156:159], v[212:215], v[188:191], v[8:11]
	s_setprio 0
	s_barrier
; #define LDA(dst, b, h)                                                                                               \
;   _Pragma("unroll") for (int m = 0; m < 4; ++m) _Pragma("unroll") for (int k = 0; k < 2; ++k) dst[m][k] =            \
;       *reinterpret_cast<const bf16x8*>(SA(b, h) + lds_byte(wr * 64 + m * 16 + fr, k * 32 + fq * 8))
; #define LDB(dst, b, h)                                                                                               \
;   _Pragma("unroll") for (int n = 0; n < 2; ++n) _Pragma("unroll") for (int k = 0; k < 2; ++k) dst[n][k] =            \
;       *reinterpret_cast<const bf16x8*>(SB(b, h) + lds_byte(wc * 32 + n * 16 + fr, k * 32 + fq * 8))
; #define WAIT_V(n) asm volatile("s_waitcnt vmcnt(" #n ")" ::: "memory")
; #define WAIT_L(n) asm volatile("s_waitcnt lgkmcnt(" #n ")" ::: "memory")
; #define BAR __builtin_amdgcn_s_barrier()
; template <int EPI>
; __device__ __forceinline__ void gemm_phase(const u16* __restrict__ A, const u16* __restrict__ Bt, const int K,
;                                            const int nN, char* shm, const EpiArgs& ea) {
;     ...
;       LDA(At, 0, 1); WAIT_V(4); BAR; WAIT_L(0); MMA(1, 0, At, B0); MMA(1, 1, At, B1); BAR;
;     }
;     {
;       LDB(B0, 1, 0); LDA(At, 1, 0); WAIT_V(2); BAR; WAIT_L(0); MMA(0, 0, At, B0); BAR;
;       LDB(B1, 1, 1); WAIT_V(0); BAR; WAIT_L(0); MMA(0, 1, At, B1); BAR;
;       LDA(At, 1, 1); BAR; WAIT_L(0); MMA(1, 0, At, B0); MMA(1, 1, At, B1); BAR;
;     }
;     if (wr == 0) BAR;
	s_nop 0
	ds_read_b128 v[8:11], v176
	ds_read_b128 v[12:15], v176 offset:1024
	ds_read_b128 v[180:183], v176 offset:2048
	ds_read_b128 v[184:187], v176 offset:3072
	ds_read_b128 v[128:131], v169 offset:32768
	ds_read_b128 v[132:135], v169 offset:33792
	ds_read_b128 v[188:191], v170 offset:32768
	ds_read_b128 v[192:195], v170 offset:33792
	ds_read_b128 v[196:199], v171 offset:32768
	ds_read_b128 v[200:203], v171 offset:33792
	ds_read_b128 v[204:207], v172 offset:32768
	ds_read_b128 v[208:211], v172 offset:33792
	s_waitcnt vmcnt(2)
	s_barrier
	s_setprio 1
	s_waitcnt lgkmcnt(5)
	v_mfma_f32_16x16x32_bf16 v[48:51], v[8:11], v[188:191], v[116:119]
	s_waitcnt lgkmcnt(4)
	v_mfma_f32_16x16x32_bf16 v[140:143], v[12:15], v[192:195], v[48:51]
	v_mfma_f32_16x16x32_bf16 v[48:51], v[180:183], v[188:191], v[112:115]
	v_mfma_f32_16x16x32_bf16 v[136:139], v[184:187], v[192:195], v[48:51]
	s_waitcnt lgkmcnt(3)
	v_mfma_f32_16x16x32_bf16 v[48:51], v[8:11], v[196:199], v[108:111]
	v_mfma_f32_16x16x32_bf16 v[28:31], v[8:11], v[128:131], v[124:127]
	s_waitcnt lgkmcnt(2)
	v_mfma_f32_16x16x32_bf16 v[124:127], v[12:15], v[200:203], v[48:51]
	v_mfma_f32_16x16x32_bf16 v[48:51], v[180:183], v[196:199], v[104:107]
	v_mfma_f32_16x16x32_bf16 v[36:39], v[180:183], v[128:131], v[120:123]
	v_mfma_f32_16x16x32_bf16 v[120:123], v[184:187], v[200:203], v[48:51]
	s_waitcnt lgkmcnt(1)
	v_mfma_f32_16x16x32_bf16 v[48:51], v[8:11], v[204:207], v[100:103]
	s_waitcnt lgkmcnt(0)
	v_mfma_f32_16x16x32_bf16 v[108:111], v[12:15], v[208:211], v[48:51]
	v_mfma_f32_16x16x32_bf16 v[48:51], v[180:183], v[204:207], v[96:99]
	v_mfma_f32_16x16x32_bf16 v[28:31], v[12:15], v[132:135], v[28:31]
	v_mfma_f32_16x16x32_bf16 v[36:39], v[184:187], v[132:135], v[36:39]
	v_mfma_f32_16x16x32_bf16 v[104:107], v[184:187], v[208:211], v[48:51]
	s_setprio 0
	s_barrier
	ds_read_b128 v[212:215], v177
	ds_read_b128 v[228:231], v177 offset:1024
	ds_read_b128 v[232:235], v177 offset:2048
	ds_read_b128 v[236:239], v177 offset:3072
	s_waitcnt vmcnt(0)
	s_barrier
	s_setprio 1
	s_waitcnt lgkmcnt(3)
	v_mfma_f32_16x16x32_bf16 v[48:51], v[212:215], v[128:131], v[92:95]
	s_waitcnt lgkmcnt(1)
	v_mfma_f32_16x16x32_bf16 v[88:91], v[232:235], v[128:131], v[88:91]
	v_mfma_f32_16x16x32_bf16 v[84:87], v[212:215], v[188:191], v[84:87]
	v_mfma_f32_16x16x32_bf16 v[80:83], v[232:235], v[188:191], v[80:83]
	v_mfma_f32_16x16x32_bf16 v[76:79], v[212:215], v[196:199], v[76:79]
	v_mfma_f32_16x16x32_bf16 v[72:75], v[232:235], v[196:199], v[72:75]
	v_mfma_f32_16x16x32_bf16 v[68:71], v[212:215], v[204:207], v[68:71]
	v_mfma_f32_16x16x32_bf16 v[64:67], v[232:235], v[204:207], v[64:67]
	v_mfma_f32_16x16x32_bf16 v[48:51], v[228:231], v[132:135], v[48:51]
	s_waitcnt lgkmcnt(0)
	v_mfma_f32_16x16x32_bf16 v[144:147], v[236:239], v[132:135], v[88:91]
	v_mfma_f32_16x16x32_bf16 v[132:135], v[228:231], v[192:195], v[84:87]
	v_mfma_f32_16x16x32_bf16 v[128:131], v[236:239], v[192:195], v[80:83]
	v_mfma_f32_16x16x32_bf16 v[116:119], v[228:231], v[200:203], v[76:79]
	v_mfma_f32_16x16x32_bf16 v[112:115], v[236:239], v[200:203], v[72:75]
	v_mfma_f32_16x16x32_bf16 v[100:103], v[228:231], v[208:211], v[68:71]
	v_mfma_f32_16x16x32_bf16 v[96:99], v[236:239], v[208:211], v[64:67]
	s_setprio 0
	s_barrier
	s_nop 0
	ds_read_b128 v[64:67], v169 offset:49152
	ds_read_b128 v[68:71], v169 offset:50176
	ds_read_b128 v[188:191], v170 offset:49152
	ds_read_b128 v[192:195], v170 offset:50176
	ds_read_b128 v[196:199], v171 offset:49152
	ds_read_b128 v[200:203], v171 offset:50176
	ds_read_b128 v[204:207], v172 offset:49152
	ds_read_b128 v[208:211], v172 offset:50176
	s_barrier
	s_setprio 1
	s_waitcnt lgkmcnt(7)
	v_mfma_f32_16x16x32_bf16 v[60:63], v[8:11], v[64:67], v[60:63]
	s_waitcnt lgkmcnt(5)
	v_mfma_f32_16x16x32_bf16 v[52:55], v[8:11], v[188:191], v[52:55]
	s_waitcnt lgkmcnt(3)
	v_mfma_f32_16x16x32_bf16 v[44:47], v[8:11], v[196:199], v[44:47]
	s_waitcnt lgkmcnt(1)
	v_mfma_f32_16x16x32_bf16 v[8:11], v[8:11], v[204:207], v[220:223]
	v_mfma_f32_16x16x32_bf16 v[92:95], v[12:15], v[68:71], v[60:63]
	v_mfma_f32_16x16x32_bf16 v[56:59], v[180:183], v[64:67], v[56:59]
	v_mfma_f32_16x16x32_bf16 v[76:79], v[12:15], v[192:195], v[52:55]
	v_mfma_f32_16x16x32_bf16 v[52:55], v[180:183], v[188:191], v[216:219]
	v_mfma_f32_16x16x32_bf16 v[60:63], v[12:15], v[200:203], v[44:47]
	v_mfma_f32_16x16x32_bf16 v[40:43], v[180:183], v[196:199], v[40:43]
	s_waitcnt lgkmcnt(0)
	v_mfma_f32_16x16x32_bf16 v[12:15], v[12:15], v[208:211], v[8:11]
	v_mfma_f32_16x16x32_bf16 v[8:11], v[180:183], v[204:207], v[32:35]
	v_mfma_f32_16x16x32_bf16 v[88:91], v[184:187], v[68:71], v[56:59]
	v_mfma_f32_16x16x32_bf16 v[72:75], v[184:187], v[192:195], v[52:55]
	v_mfma_f32_16x16x32_bf16 v[56:59], v[184:187], v[200:203], v[40:43]
	v_mfma_f32_16x16x32_bf16 v[8:11], v[184:187], v[208:211], v[8:11]
	s_setprio 0
	s_setprio 1
	v_mfma_f32_16x16x32_bf16 v[16:19], v[232:235], v[188:191], v[16:19]
	v_mfma_f32_16x16x32_bf16 v[32:35], v[212:215], v[64:67], v[224:227]
	v_mfma_f32_16x16x32_bf16 v[24:27], v[232:235], v[64:67], v[24:27]
	v_mfma_f32_16x16x32_bf16 v[64:67], v[236:239], v[192:195], v[16:19]
	v_mfma_f32_16x16x32_bf16 v[16:19], v[212:215], v[196:199], v[152:155]
	v_mfma_f32_16x16x32_bf16 v[20:23], v[212:215], v[188:191], v[20:23]
	v_mfma_f32_16x16x32_bf16 v[40:43], v[228:231], v[200:203], v[16:19]
	v_mfma_f32_16x16x32_bf16 v[16:19], v[232:235], v[196:199], v[156:159]
	v_mfma_f32_16x16x32_bf16 v[4:7], v[212:215], v[204:207], v[4:7]
	v_mfma_f32_16x16x32_bf16 v[0:3], v[232:235], v[204:207], v[0:3]
	v_mfma_f32_16x16x32_bf16 v[84:87], v[228:231], v[68:71], v[32:35]
	v_mfma_f32_16x16x32_bf16 v[80:83], v[236:239], v[68:71], v[24:27]
	v_mfma_f32_16x16x32_bf16 v[68:71], v[228:231], v[192:195], v[20:23]
	v_mfma_f32_16x16x32_bf16 v[16:19], v[236:239], v[200:203], v[16:19]
	v_mfma_f32_16x16x32_bf16 v[4:7], v[228:231], v[208:211], v[4:7]
	v_mfma_f32_16x16x32_bf16 v[0:3], v[236:239], v[208:211], v[0:3]
	s_setprio 0
	s_andn2_b64 vcc, exec, s[36:37]
	s_barrier
	s_cbranch_vccz .LBB0_380
	s_andn2_b64 vcc, exec, s[4:5]
	s_cbranch_vccz .LBB0_381

; #define LDA(dst, b, h)                                                                                               \
;   _Pragma("unroll") for (int m = 0; m < 4; ++m) _Pragma("unroll") for (int k = 0; k < 2; ++k) dst[m][k] =            \
;       *reinterpret_cast<const bf16x8*>(SA(b, h) + lds_byte(wr * 64 + m * 16 + fr, k * 32 + fq * 8))
; #define LDB(dst, b, h)                                                                                               \
;   _Pragma("unroll") for (int n = 0; n < 2; ++n) _Pragma("unroll") for (int k = 0; k < 2; ++k) dst[n][k] =            \
;       *reinterpret_cast<const bf16x8*>(SB(b, h) + lds_byte(wc * 32 + n * 16 + fr, k * 32 + fq * 8))
; #define WAIT_V(n) asm volatile("s_waitcnt vmcnt(" #n ")" ::: "memory")
; #define WAIT_L(n) asm volatile("s_waitcnt lgkmcnt(" #n ")" ::: "memory")
; #define BAR __builtin_amdgcn_s_barrier()
; #define SCHED __builtin_amdgcn_sched_barrier(0)
; template <int EPI>
; __device__ __forceinline__ void gemm_phase(const u16* __restrict__ A, const u16* __restrict__ Bt, const int K,
;                                            const int nN, char* shm, const EpiArgs& ea) {
;     ...
;     for (int t = 0; t < nt - 2; t += 2) {
;       LDB(B0, 0, 0); SCHED; LDA(At, 0, 0); STAGE(SA(1, 1), rA, brow + HALF, t + 1);
;       WAIT_V(10); WAIT_L(8); BAR; WAIT_L(0); MMA(0, 0, At, B0); BAR; SCHED;
;       LDB(B1, 0, 1); STAGE(SB(0, 0), rB, bcol, t + 2);
;       WAIT_V(10); BAR; WAIT_L(0); MMA(0, 1, At, B1); BAR;
;       LDA(At, 0, 1); STAGE(SA(0, 0), rA, brow, t + 2);
;       BAR; WAIT_L(0); MMA(1, 0, At, B0); BAR; SCHED;
;       STAGE(SB(0, 1), rB, bcol + HALF, t + 2);
;       WAIT_V(10); BAR; MMA(1, 1, At, B1); BAR;
;       LDB(B0, 1, 0); SCHED; LDA(At, 1, 0); STAGE(SA(0, 1), rA, brow + HALF, t + 2);
;       WAIT_V(10); WAIT_L(8); BAR; WAIT_L(0); MMA(0, 0, At, B0); BAR; SCHED;
;       LDB(B1, 1, 1); STAGE(SB(1, 0), rB, bcol, t + 3);
;       WAIT_V(10); BAR; WAIT_L(0); MMA(0, 1, At, B1); BAR;
;       LDA(At, 1, 1); STAGE(SA(1, 0), rA, brow, t + 3);
;       BAR; WAIT_L(0); MMA(1, 0, At, B0); BAR; SCHED;
;       STAGE(SB(1, 1), rB, bcol + HALF, t + 3);
;       WAIT_V(10); BAR; MMA(1, 1, At, B1); BAR;
;     }
.LBB0_492:
	ds_read_b128 v[130:133], v146
	ds_read_b128 v[134:137], v146 offset:1024
	ds_read_b128 v[138:141], v146 offset:2048
	ds_read_b128 v[154:157], v146 offset:3072
	s_add_i32 s65, s59, s64
	s_mov_b32 m0, s34
	s_add_i32 s10, s65, 0x4000
	ds_read_b128 v[158:161], v147
	ds_read_b128 v[162:165], v147 offset:1024
	ds_read_b128 v[166:169], v148
	ds_read_b128 v[170:173], v148 offset:1024
	ds_read_b128 v[176:179], v149
	ds_read_b128 v[180:183], v149 offset:1024
	ds_read_b128 v[184:187], v150
	ds_read_b128 v[188:191], v150 offset:1024
	buffer_load_dwordx4 v142, s[0:3], s10 offen lds
	s_add_i32 s10, s65, 0x6000
	s_mov_b32 m0, s35
	s_nop 0
	buffer_load_dwordx4 v142, s[0:3], s10 offen lds
	s_waitcnt vmcnt(10)
	s_waitcnt lgkmcnt(8)
	s_barrier
	s_setprio 1
	s_waitcnt lgkmcnt(7)
	v_mfma_f32_16x16x32_bf16 v[124:127], v[130:133], v[158:161], v[124:127]
	v_mfma_f32_16x16x32_bf16 v[120:123], v[138:141], v[158:161], v[120:123]
	s_waitcnt lgkmcnt(5)
	v_mfma_f32_16x16x32_bf16 v[116:119], v[130:133], v[166:169], v[116:119]
	v_mfma_f32_16x16x32_bf16 v[112:115], v[138:141], v[166:169], v[112:115]
	s_waitcnt lgkmcnt(3)
	v_mfma_f32_16x16x32_bf16 v[108:111], v[130:133], v[176:179], v[108:111]
	v_mfma_f32_16x16x32_bf16 v[104:107], v[138:141], v[176:179], v[104:107]
	s_waitcnt lgkmcnt(1)
	v_mfma_f32_16x16x32_bf16 v[100:103], v[130:133], v[184:187], v[100:103]
	v_mfma_f32_16x16x32_bf16 v[96:99], v[138:141], v[184:187], v[96:99]
	v_mfma_f32_16x16x32_bf16 v[124:127], v[134:137], v[162:165], v[124:127]
	v_mfma_f32_16x16x32_bf16 v[120:123], v[154:157], v[162:165], v[120:123]
	v_mfma_f32_16x16x32_bf16 v[116:119], v[134:137], v[170:173], v[116:119]
	v_mfma_f32_16x16x32_bf16 v[112:115], v[154:157], v[170:173], v[112:115]
	v_mfma_f32_16x16x32_bf16 v[108:111], v[134:137], v[180:183], v[108:111]
	v_mfma_f32_16x16x32_bf16 v[104:107], v[154:157], v[180:183], v[104:107]
	s_waitcnt lgkmcnt(0)
	v_mfma_f32_16x16x32_bf16 v[100:103], v[134:137], v[188:191], v[100:103]
	v_mfma_f32_16x16x32_bf16 v[96:99], v[154:157], v[188:191], v[96:99]
	s_setprio 0
	s_barrier
	s_add_i32 s66, s62, s64
	s_mov_b32 m0, s36
	s_add_i32 s67, s66, 0x8000
	s_mov_b32 s10, s2
	s_mov_b32 s11, s3
	ds_read_b128 v[192:195], v151
	ds_read_b128 v[196:199], v151 offset:1024
	ds_read_b128 v[200:203], v151 offset:2048
	ds_read_b128 v[204:207], v151 offset:3072
	buffer_load_dwordx4 v142, s[8:11], s67 offen lds
	s_add_i32 s67, s66, 0xa000
	s_mov_b32 m0, s37
	s_nop 0
	buffer_load_dwordx4 v142, s[8:11], s67 offen lds
	s_waitcnt vmcnt(10)
	s_barrier
	s_setprio 1
	s_waitcnt lgkmcnt(3)
	v_mfma_f32_16x16x32_bf16 v[92:95], v[192:195], v[158:161], v[92:95]
	s_waitcnt lgkmcnt(1)
	v_mfma_f32_16x16x32_bf16 v[88:91], v[200:203], v[158:161], v[88:91]
	v_mfma_f32_16x16x32_bf16 v[84:87], v[192:195], v[166:169], v[84:87]
	v_mfma_f32_16x16x32_bf16 v[80:83], v[200:203], v[166:169], v[80:83]
	v_mfma_f32_16x16x32_bf16 v[76:79], v[192:195], v[176:179], v[76:79]
	v_mfma_f32_16x16x32_bf16 v[72:75], v[200:203], v[176:179], v[72:75]
	v_mfma_f32_16x16x32_bf16 v[68:71], v[192:195], v[184:187], v[68:71]
	v_mfma_f32_16x16x32_bf16 v[64:67], v[200:203], v[184:187], v[64:67]
	v_mfma_f32_16x16x32_bf16 v[92:95], v[196:199], v[162:165], v[92:95]
	s_waitcnt lgkmcnt(0)
	v_mfma_f32_16x16x32_bf16 v[88:91], v[204:207], v[162:165], v[88:91]
	v_mfma_f32_16x16x32_bf16 v[84:87], v[196:199], v[170:173], v[84:87]
	v_mfma_f32_16x16x32_bf16 v[80:83], v[204:207], v[170:173], v[80:83]
	v_mfma_f32_16x16x32_bf16 v[76:79], v[196:199], v[180:183], v[76:79]
	v_mfma_f32_16x16x32_bf16 v[72:75], v[204:207], v[180:183], v[72:75]
	v_mfma_f32_16x16x32_bf16 v[68:71], v[196:199], v[188:191], v[68:71]
	v_mfma_f32_16x16x32_bf16 v[64:67], v[204:207], v[188:191], v[64:67]
	s_setprio 0
	s_add_i32 s67, s61, s64
	s_mov_b32 m0, s27
	s_add_i32 s68, s67, 0x8000
	s_barrier
	ds_read_b128 v[158:161], v147 offset:16384
	ds_read_b128 v[162:165], v147 offset:17408
	ds_read_b128 v[166:169], v148 offset:16384
	ds_read_b128 v[170:173], v148 offset:17408
	ds_read_b128 v[176:179], v149 offset:16384
	ds_read_b128 v[180:183], v149 offset:17408
	ds_read_b128 v[184:187], v150 offset:16384
	ds_read_b128 v[188:191], v150 offset:17408
	buffer_load_dwordx4 v142, s[0:3], s68 offen lds
	s_add_i32 s68, s67, 0xa000
	s_mov_b32 m0, s38
	s_nop 0
	buffer_load_dwordx4 v142, s[0:3], s68 offen lds
	s_barrier
	s_setprio 1
	s_waitcnt lgkmcnt(7)
	v_mfma_f32_16x16x32_bf16 v[60:63], v[130:133], v[158:161], v[60:63]
	v_mfma_f32_16x16x32_bf16 v[56:59], v[138:141], v[158:161], v[56:59]
	s_waitcnt lgkmcnt(5)
	v_mfma_f32_16x16x32_bf16 v[52:55], v[130:133], v[166:169], v[52:55]
	v_mfma_f32_16x16x32_bf16 v[48:51], v[138:141], v[166:169], v[48:51]
	s_waitcnt lgkmcnt(3)
	v_mfma_f32_16x16x32_bf16 v[44:47], v[130:133], v[176:179], v[44:47]
	v_mfma_f32_16x16x32_bf16 v[40:43], v[138:141], v[176:179], v[40:43]
	s_waitcnt lgkmcnt(1)
	v_mfma_f32_16x16x32_bf16 v[36:39], v[130:133], v[184:187], v[36:39]
	v_mfma_f32_16x16x32_bf16 v[32:35], v[138:141], v[184:187], v[32:35]
	v_mfma_f32_16x16x32_bf16 v[60:63], v[134:137], v[162:165], v[60:63]
	v_mfma_f32_16x16x32_bf16 v[56:59], v[154:157], v[162:165], v[56:59]
	v_mfma_f32_16x16x32_bf16 v[52:55], v[134:137], v[170:173], v[52:55]
	v_mfma_f32_16x16x32_bf16 v[48:51], v[154:157], v[170:173], v[48:51]
	v_mfma_f32_16x16x32_bf16 v[44:47], v[134:137], v[180:183], v[44:47]
	v_mfma_f32_16x16x32_bf16 v[40:43], v[154:157], v[180:183], v[40:43]
	s_waitcnt lgkmcnt(0)
	v_mfma_f32_16x16x32_bf16 v[36:39], v[134:137], v[188:191], v[36:39]
	v_mfma_f32_16x16x32_bf16 v[32:35], v[154:157], v[188:191], v[32:35]
	s_setprio 0
	s_barrier
; #define LDA(dst, b, h)                                                                                               \
;   _Pragma("unroll") for (int m = 0; m < 4; ++m) _Pragma("unroll") for (int k = 0; k < 2; ++k) dst[m][k] =            \
;       *reinterpret_cast<const bf16x8*>(SA(b, h) + lds_byte(wr * 64 + m * 16 + fr, k * 32 + fq * 8))
; #define LDB(dst, b, h)                                                                                               \
;   _Pragma("unroll") for (int n = 0; n < 2; ++n) _Pragma("unroll") for (int k = 0; k < 2; ++k) dst[n][k] =            \
;       *reinterpret_cast<const bf16x8*>(SB(b, h) + lds_byte(wc * 32 + n * 16 + fr, k * 32 + fq * 8))
; #define WAIT_V(n) asm volatile("s_waitcnt vmcnt(" #n ")" ::: "memory")
; #define WAIT_L(n) asm volatile("s_waitcnt lgkmcnt(" #n ")" ::: "memory")
; #define BAR __builtin_amdgcn_s_barrier()
; #define SCHED __builtin_amdgcn_sched_barrier(0)
; template <int EPI>
; __device__ __forceinline__ void gemm_phase(const u16* __restrict__ A, const u16* __restrict__ Bt, const int K,
;                                            const int nN, char* shm, const EpiArgs& ea) {
;     ...
;     for (int t = 0; t < nt - 2; t += 2) {
;       LDB(B0, 0, 0); SCHED; LDA(At, 0, 0); STAGE(SA(1, 1), rA, brow + HALF, t + 1);
;       WAIT_V(10); WAIT_L(8); BAR; WAIT_L(0); MMA(0, 0, At, B0); BAR; SCHED;
;       LDB(B1, 0, 1); STAGE(SB(0, 0), rB, bcol, t + 2);
;       WAIT_V(10); BAR; WAIT_L(0); MMA(0, 1, At, B1); BAR;
;       LDA(At, 0, 1); STAGE(SA(0, 0), rA, brow, t + 2);
;       BAR; WAIT_L(0); MMA(1, 0, At, B0); BAR; SCHED;
;       STAGE(SB(0, 1), rB, bcol + HALF, t + 2);
;       WAIT_V(10); BAR; MMA(1, 1, At, B1); BAR;
;       LDB(B0, 1, 0); SCHED; LDA(At, 1, 0); STAGE(SA(0, 1), rA, brow + HALF, t + 2);
;       WAIT_V(10); WAIT_L(8); BAR; WAIT_L(0); MMA(0, 0, At, B0); BAR; SCHED;
;       LDB(B1, 1, 1); STAGE(SB(1, 0), rB, bcol, t + 3);
;       WAIT_V(10); BAR; WAIT_L(0); MMA(0, 1, At, B1); BAR;
;       LDA(At, 1, 1); STAGE(SA(1, 0), rA, brow, t + 3);
;       BAR; WAIT_L(0); MMA(1, 0, At, B0); BAR; SCHED;
;       STAGE(SB(1, 1), rB, bcol + HALF, t + 3);
;       WAIT_V(10); BAR; MMA(1, 1, At, B1); BAR;
;     }
	s_add_i32 s68, s60, s64
	s_mov_b32 m0, s39
	s_add_i32 s69, s68, 0x8000
	buffer_load_dwordx4 v142, s[8:11], s69 offen lds
	s_add_i32 s69, s68, 0xa000
	s_mov_b32 m0, s40
	s_nop 0
	buffer_load_dwordx4 v142, s[8:11], s69 offen lds
	s_waitcnt vmcnt(10)
	s_barrier
	s_setprio 1
	v_mfma_f32_16x16x32_bf16 v[28:31], v[192:195], v[158:161], v[28:31]
	v_mfma_f32_16x16x32_bf16 v[24:27], v[200:203], v[158:161], v[24:27]
	v_mfma_f32_16x16x32_bf16 v[20:23], v[192:195], v[166:169], v[20:23]
	v_mfma_f32_16x16x32_bf16 v[16:19], v[200:203], v[166:169], v[16:19]
	v_mfma_f32_16x16x32_bf16 v[12:15], v[192:195], v[176:179], v[12:15]
	v_mfma_f32_16x16x32_bf16 v[8:11], v[200:203], v[176:179], v[8:11]
	v_mfma_f32_16x16x32_bf16 v[4:7], v[192:195], v[184:187], v[4:7]
	v_mfma_f32_16x16x32_bf16 v[0:3], v[200:203], v[184:187], v[0:3]
	v_mfma_f32_16x16x32_bf16 v[28:31], v[196:199], v[162:165], v[28:31]
	v_mfma_f32_16x16x32_bf16 v[24:27], v[204:207], v[162:165], v[24:27]
	v_mfma_f32_16x16x32_bf16 v[20:23], v[196:199], v[170:173], v[20:23]
	v_mfma_f32_16x16x32_bf16 v[16:19], v[204:207], v[170:173], v[16:19]
	v_mfma_f32_16x16x32_bf16 v[12:15], v[196:199], v[180:183], v[12:15]
	v_mfma_f32_16x16x32_bf16 v[8:11], v[204:207], v[180:183], v[8:11]
	v_mfma_f32_16x16x32_bf16 v[4:7], v[196:199], v[188:191], v[4:7]
	v_mfma_f32_16x16x32_bf16 v[0:3], v[204:207], v[188:191], v[0:3]
	s_setprio 0
	s_barrier
	ds_read_b128 v[130:133], v152
	ds_read_b128 v[134:137], v152 offset:1024
	ds_read_b128 v[138:141], v152 offset:2048
	ds_read_b128 v[154:157], v152 offset:3072
	s_mov_b32 m0, s41
	s_add_i32 s69, s65, 0x8000
	ds_read_b128 v[158:161], v147 offset:32768
	ds_read_b128 v[162:165], v147 offset:33792
	ds_read_b128 v[166:169], v148 offset:32768
	ds_read_b128 v[170:173], v148 offset:33792
	ds_read_b128 v[176:179], v149 offset:32768
	ds_read_b128 v[180:183], v149 offset:33792
	ds_read_b128 v[184:187], v150 offset:32768
	ds_read_b128 v[188:191], v150 offset:33792
	buffer_load_dwordx4 v142, s[0:3], s69 offen lds
	s_add_i32 s65, s65, 0xa000
	s_mov_b32 m0, s42
	s_nop 0
	buffer_load_dwordx4 v142, s[0:3], s65 offen lds
	s_waitcnt vmcnt(10)
	s_waitcnt lgkmcnt(8)
	s_barrier
	s_setprio 1
	s_waitcnt lgkmcnt(7)
	v_mfma_f32_16x16x32_bf16 v[124:127], v[130:133], v[158:161], v[124:127]
	v_mfma_f32_16x16x32_bf16 v[120:123], v[138:141], v[158:161], v[120:123]
	s_waitcnt lgkmcnt(5)
	v_mfma_f32_16x16x32_bf16 v[116:119], v[130:133], v[166:169], v[116:119]
	v_mfma_f32_16x16x32_bf16 v[112:115], v[138:141], v[166:169], v[112:115]
	s_waitcnt lgkmcnt(3)
	v_mfma_f32_16x16x32_bf16 v[108:111], v[130:133], v[176:179], v[108:111]
	v_mfma_f32_16x16x32_bf16 v[104:107], v[138:141], v[176:179], v[104:107]
	s_waitcnt lgkmcnt(1)
	v_mfma_f32_16x16x32_bf16 v[100:103], v[130:133], v[184:187], v[100:103]
	v_mfma_f32_16x16x32_bf16 v[96:99], v[138:141], v[184:187], v[96:99]
	v_mfma_f32_16x16x32_bf16 v[124:127], v[134:137], v[162:165], v[124:127]
	v_mfma_f32_16x16x32_bf16 v[120:123], v[154:157], v[162:165], v[120:123]
	v_mfma_f32_16x16x32_bf16 v[116:119], v[134:137], v[170:173], v[116:119]
	v_mfma_f32_16x16x32_bf16 v[112:115], v[154:157], v[170:173], v[112:115]
	v_mfma_f32_16x16x32_bf16 v[108:111], v[134:137], v[180:183], v[108:111]
	v_mfma_f32_16x16x32_bf16 v[104:107], v[154:157], v[180:183], v[104:107]
	s_waitcnt lgkmcnt(0)
	v_mfma_f32_16x16x32_bf16 v[100:103], v[134:137], v[188:191], v[100:103]
	v_mfma_f32_16x16x32_bf16 v[96:99], v[154:157], v[188:191], v[96:99]
	s_setprio 0
	s_barrier
	s_mov_b32 m0, s43
	s_add_i32 s65, s66, 0xc000
	ds_read_b128 v[192:195], v153
	ds_read_b128 v[196:199], v153 offset:1024
	ds_read_b128 v[200:203], v153 offset:2048
	ds_read_b128 v[204:207], v153 offset:3072
	buffer_load_dwordx4 v142, s[8:11], s65 offen lds
	s_add_i32 s66, s66, 0xe000
	s_mov_b32 m0, s48
	s_nop 0
	buffer_load_dwordx4 v142, s[8:11], s66 offen lds
	s_waitcnt vmcnt(10)
	s_barrier
	s_setprio 1
	s_waitcnt lgkmcnt(3)
	v_mfma_f32_16x16x32_bf16 v[92:95], v[192:195], v[158:161], v[92:95]
	s_waitcnt lgkmcnt(1)
	v_mfma_f32_16x16x32_bf16 v[88:91], v[200:203], v[158:161], v[88:91]
	v_mfma_f32_16x16x32_bf16 v[84:87], v[192:195], v[166:169], v[84:87]
	v_mfma_f32_16x16x32_bf16 v[80:83], v[200:203], v[166:169], v[80:83]
	v_mfma_f32_16x16x32_bf16 v[76:79], v[192:195], v[176:179], v[76:79]
	v_mfma_f32_16x16x32_bf16 v[72:75], v[200:203], v[176:179], v[72:75]
	v_mfma_f32_16x16x32_bf16 v[68:71], v[192:195], v[184:187], v[68:71]
	v_mfma_f32_16x16x32_bf16 v[64:67], v[200:203], v[184:187], v[64:67]
	v_mfma_f32_16x16x32_bf16 v[92:95], v[196:199], v[162:165], v[92:95]
	s_waitcnt lgkmcnt(0)
	v_mfma_f32_16x16x32_bf16 v[88:91], v[204:207], v[162:165], v[88:91]
	v_mfma_f32_16x16x32_bf16 v[84:87], v[196:199], v[170:173], v[84:87]
	v_mfma_f32_16x16x32_bf16 v[80:83], v[204:207], v[170:173], v[80:83]
	v_mfma_f32_16x16x32_bf16 v[76:79], v[196:199], v[180:183], v[76:79]
	v_mfma_f32_16x16x32_bf16 v[72:75], v[204:207], v[180:183], v[72:75]
	v_mfma_f32_16x16x32_bf16 v[68:71], v[196:199], v[188:191], v[68:71]
	v_mfma_f32_16x16x32_bf16 v[64:67], v[204:207], v[188:191], v[64:67]
	s_setprio 0
	s_mov_b32 m0, s49
	s_add_i32 s65, s67, 0xc000
	s_barrier
	ds_read_b128 v[158:161], v147 offset:49152
	ds_read_b128 v[162:165], v147 offset:50176
	ds_read_b128 v[166:169], v148 offset:49152
	ds_read_b128 v[170:173], v148 offset:50176
	ds_read_b128 v[176:179], v149 offset:49152
	ds_read_b128 v[180:183], v149 offset:50176
	ds_read_b128 v[184:187], v150 offset:49152
	ds_read_b128 v[188:191], v150 offset:50176
	buffer_load_dwordx4 v142, s[0:3], s65 offen lds
	s_add_i32 s67, s67, 0xe000
	s_mov_b32 m0, s50
	s_nop 0
	buffer_load_dwordx4 v142, s[0:3], s67 offen lds
	s_barrier
; #define LDA(dst, b, h)                                                                                               \
;   _Pragma("unroll") for (int m = 0; m < 4; ++m) _Pragma("unroll") for (int k = 0; k < 2; ++k) dst[m][k] =            \
;       *reinterpret_cast<const bf16x8*>(SA(b, h) + lds_byte(wr * 64 + m * 16 + fr, k * 32 + fq * 8))
; #define LDB(dst, b, h)                                                                                               \
;   _Pragma("unroll") for (int n = 0; n < 2; ++n) _Pragma("unroll") for (int k = 0; k < 2; ++k) dst[n][k] =            \
;       *reinterpret_cast<const bf16x8*>(SB(b, h) + lds_byte(wc * 32 + n * 16 + fr, k * 32 + fq * 8))
; #define WAIT_V(n) asm volatile("s_waitcnt vmcnt(" #n ")" ::: "memory")
; #define WAIT_L(n) asm volatile("s_waitcnt lgkmcnt(" #n ")" ::: "memory")
; #define BAR __builtin_amdgcn_s_barrier()
; #define SCHED __builtin_amdgcn_sched_barrier(0)
; template <int EPI>
; __device__ __forceinline__ void gemm_phase(const u16* __restrict__ A, const u16* __restrict__ Bt, const int K,
;                                            const int nN, char* shm, const EpiArgs& ea) {
;     ...
;       BAR; WAIT_L(0); MMA(1, 0, At, B0); BAR; SCHED;
;       STAGE(SB(1, 1), rB, bcol + HALF, t + 3);
;       WAIT_V(10); BAR; MMA(1, 1, At, B1); BAR;
;     }
;     float eC = 0.f, eB = 0.f;
;     float2 eS = make_float2(0.f, 0.f);
;     if (EPI == EPI_IN || EPI == EPI_SWIGLU_LN) {
;       if (wr == 0) {
;         eC = ea.c1[bcol + tid];
;         eS = *(const float2*)(ea.st_in + (size_t)(brow + tid) * 2);
;       } else {
;         eC = ea.c2[bcol + tid - 256];
;         if (EPI == EPI_IN) eB = ea.bias[bcol + tid - 256];
;       }
;     }
;     {
;       LDB(B0, 0, 0); LDA(At, 0, 0); STAGE(SA(1, 1), rA, brow + HALF, nt - 1);
;       WAIT_V(10); BAR; WAIT_L(0); MMA(0, 0, At, B0); BAR;
;       LDB(B1, 0, 1); WAIT_V(8); BAR; WAIT_L(0); MMA(0, 1, At, B1); BAR;
;       LDA(At, 0, 1); WAIT_V(4); BAR; WAIT_L(0); MMA(1, 0, At, B0); MMA(1, 1, At, B1); BAR;
	s_setprio 1
	s_waitcnt lgkmcnt(7)
	v_mfma_f32_16x16x32_bf16 v[60:63], v[130:133], v[158:161], v[60:63]
	v_mfma_f32_16x16x32_bf16 v[56:59], v[138:141], v[158:161], v[56:59]
	s_waitcnt lgkmcnt(5)
	v_mfma_f32_16x16x32_bf16 v[52:55], v[130:133], v[166:169], v[52:55]
	v_mfma_f32_16x16x32_bf16 v[48:51], v[138:141], v[166:169], v[48:51]
	s_waitcnt lgkmcnt(3)
	v_mfma_f32_16x16x32_bf16 v[44:47], v[130:133], v[176:179], v[44:47]
	v_mfma_f32_16x16x32_bf16 v[40:43], v[138:141], v[176:179], v[40:43]
	s_waitcnt lgkmcnt(1)
	v_mfma_f32_16x16x32_bf16 v[36:39], v[130:133], v[184:187], v[36:39]
	v_mfma_f32_16x16x32_bf16 v[32:35], v[138:141], v[184:187], v[32:35]
	v_mfma_f32_16x16x32_bf16 v[60:63], v[134:137], v[162:165], v[60:63]
	v_mfma_f32_16x16x32_bf16 v[56:59], v[154:157], v[162:165], v[56:59]
	v_mfma_f32_16x16x32_bf16 v[52:55], v[134:137], v[170:173], v[52:55]
	v_mfma_f32_16x16x32_bf16 v[48:51], v[154:157], v[170:173], v[48:51]
	v_mfma_f32_16x16x32_bf16 v[44:47], v[134:137], v[180:183], v[44:47]
	v_mfma_f32_16x16x32_bf16 v[40:43], v[154:157], v[180:183], v[40:43]
	s_waitcnt lgkmcnt(0)
	v_mfma_f32_16x16x32_bf16 v[36:39], v[134:137], v[188:191], v[36:39]
	v_mfma_f32_16x16x32_bf16 v[32:35], v[154:157], v[188:191], v[32:35]
	s_setprio 0
	s_barrier
	s_mov_b32 m0, s51
	s_add_i32 s65, s68, 0xc000
	buffer_load_dwordx4 v142, s[8:11], s65 offen lds
	s_add_i32 s68, s68, 0xe000
	s_mov_b32 m0, s52
	s_nop 0
	buffer_load_dwordx4 v142, s[8:11], s68 offen lds
	s_waitcnt vmcnt(10)
	s_barrier
	s_setprio 1
	v_mfma_f32_16x16x32_bf16 v[28:31], v[192:195], v[158:161], v[28:31]
	v_mfma_f32_16x16x32_bf16 v[24:27], v[200:203], v[158:161], v[24:27]
	v_mfma_f32_16x16x32_bf16 v[20:23], v[192:195], v[166:169], v[20:23]
	v_mfma_f32_16x16x32_bf16 v[16:19], v[200:203], v[166:169], v[16:19]
	v_mfma_f32_16x16x32_bf16 v[12:15], v[192:195], v[176:179], v[12:15]
	v_mfma_f32_16x16x32_bf16 v[8:11], v[200:203], v[176:179], v[8:11]
	v_mfma_f32_16x16x32_bf16 v[4:7], v[192:195], v[184:187], v[4:7]
	v_mfma_f32_16x16x32_bf16 v[0:3], v[200:203], v[184:187], v[0:3]
	v_mfma_f32_16x16x32_bf16 v[28:31], v[196:199], v[162:165], v[28:31]
	v_mfma_f32_16x16x32_bf16 v[24:27], v[204:207], v[162:165], v[24:27]
	v_mfma_f32_16x16x32_bf16 v[20:23], v[196:199], v[170:173], v[20:23]
	v_mfma_f32_16x16x32_bf16 v[16:19], v[204:207], v[170:173], v[16:19]
	v_mfma_f32_16x16x32_bf16 v[12:15], v[196:199], v[180:183], v[12:15]
	v_mfma_f32_16x16x32_bf16 v[8:11], v[204:207], v[180:183], v[8:11]
	v_mfma_f32_16x16x32_bf16 v[4:7], v[196:199], v[188:191], v[4:7]
	v_mfma_f32_16x16x32_bf16 v[0:3], v[204:207], v[188:191], v[0:3]
	s_setprio 0
	s_add_i32 s63, s63, 2
	s_add_i32 s64, s64, 0x8000
	s_cmp_lt_u32 s63, 28
	s_barrier
	s_cbranch_scc1 .LBB0_492
	s_mov_b32 m0, s34
	s_add_i32 s10, s59, 0x7c000
	ds_read_b128 v[130:133], v146
	ds_read_b128 v[134:137], v146 offset:1024
	ds_read_b128 v[138:141], v146 offset:2048
	ds_read_b128 v[154:157], v146 offset:3072
	ds_read_b128 v[158:161], v147
	ds_read_b128 v[162:165], v147 offset:1024
	ds_read_b128 v[166:169], v148
	ds_read_b128 v[170:173], v148 offset:1024
	ds_read_b128 v[176:179], v149
	ds_read_b128 v[180:183], v149 offset:1024
	ds_read_b128 v[184:187], v150
	ds_read_b128 v[188:191], v150 offset:1024
	buffer_load_dwordx4 v142, s[0:3], s10 offen lds
	s_add_i32 s59, s59, 0x7e000
	s_mov_b32 m0, s35
	s_nop 0
	buffer_load_dwordx4 v142, s[0:3], s59 offen lds
	s_waitcnt vmcnt(10)
	s_barrier
	s_setprio 1
	s_waitcnt lgkmcnt(7)
	v_mfma_f32_16x16x32_bf16 v[124:127], v[130:133], v[158:161], v[124:127]
	v_mfma_f32_16x16x32_bf16 v[120:123], v[138:141], v[158:161], v[120:123]
	s_waitcnt lgkmcnt(5)
	v_mfma_f32_16x16x32_bf16 v[116:119], v[130:133], v[166:169], v[116:119]
	v_mfma_f32_16x16x32_bf16 v[112:115], v[138:141], v[166:169], v[112:115]
	s_waitcnt lgkmcnt(1)
	v_mfma_f32_16x16x32_bf16 v[100:103], v[130:133], v[184:187], v[100:103]
	v_mfma_f32_16x16x32_bf16 v[96:99], v[138:141], v[184:187], v[96:99]
	v_mfma_f32_16x16x32_bf16 v[124:127], v[134:137], v[162:165], v[124:127]
	v_mfma_f32_16x16x32_bf16 v[120:123], v[154:157], v[162:165], v[120:123]
	v_mfma_f32_16x16x32_bf16 v[116:119], v[134:137], v[170:173], v[116:119]
	v_mfma_f32_16x16x32_bf16 v[112:115], v[154:157], v[170:173], v[112:115]
	v_mfma_f32_16x16x32_bf16 v[108:111], v[130:133], v[176:179], v[108:111]
	v_mfma_f32_16x16x32_bf16 v[104:107], v[138:141], v[176:179], v[104:107]
	s_waitcnt lgkmcnt(0)
	v_mfma_f32_16x16x32_bf16 v[100:103], v[134:137], v[188:191], v[100:103]
	v_mfma_f32_16x16x32_bf16 v[96:99], v[154:157], v[188:191], v[96:99]
	v_mfma_f32_16x16x32_bf16 v[192:195], v[134:137], v[180:183], v[108:111]
	v_mfma_f32_16x16x32_bf16 v[196:199], v[154:157], v[180:183], v[104:107]
	s_setprio 0
	s_barrier
	s_nop 0
	ds_read_b128 v[104:107], v151
	ds_read_b128 v[108:111], v151 offset:1024
	ds_read_b128 v[200:203], v151 offset:2048
	ds_read_b128 v[204:207], v151 offset:3072
	s_waitcnt vmcnt(8)
	s_barrier
	s_setprio 1
	s_waitcnt lgkmcnt(3)
	v_mfma_f32_16x16x32_bf16 v[84:87], v[104:107], v[166:169], v[84:87]
	s_waitcnt lgkmcnt(1)
	v_mfma_f32_16x16x32_bf16 v[80:83], v[200:203], v[166:169], v[80:83]
	v_mfma_f32_16x16x32_bf16 v[68:71], v[104:107], v[184:187], v[68:71]
	v_mfma_f32_16x16x32_bf16 v[64:67], v[200:203], v[184:187], v[64:67]
	v_mfma_f32_16x16x32_bf16 v[92:95], v[104:107], v[158:161], v[92:95]
	v_mfma_f32_16x16x32_bf16 v[88:91], v[200:203], v[158:161], v[88:91]
	v_mfma_f32_16x16x32_bf16 v[84:87], v[108:111], v[170:173], v[84:87]
	s_waitcnt lgkmcnt(0)
	v_mfma_f32_16x16x32_bf16 v[80:83], v[204:207], v[170:173], v[80:83]
	v_mfma_f32_16x16x32_bf16 v[76:79], v[104:107], v[176:179], v[76:79]
	v_mfma_f32_16x16x32_bf16 v[72:75], v[200:203], v[176:179], v[72:75]
	v_mfma_f32_16x16x32_bf16 v[68:71], v[108:111], v[188:191], v[68:71]
	v_mfma_f32_16x16x32_bf16 v[64:67], v[204:207], v[188:191], v[64:67]
	v_mfma_f32_16x16x32_bf16 v[208:211], v[108:111], v[162:165], v[92:95]
	v_mfma_f32_16x16x32_bf16 v[158:161], v[204:207], v[162:165], v[88:91]
	v_mfma_f32_16x16x32_bf16 v[162:165], v[108:111], v[180:183], v[76:79]
	v_mfma_f32_16x16x32_bf16 v[166:169], v[204:207], v[180:183], v[72:75]
	s_setprio 0
	s_barrier
; #define LDA(dst, b, h)                                                                                               \
;   _Pragma("unroll") for (int m = 0; m < 4; ++m) _Pragma("unroll") for (int k = 0; k < 2; ++k) dst[m][k] =            \
;       *reinterpret_cast<const bf16x8*>(SA(b, h) + lds_byte(wr * 64 + m * 16 + fr, k * 32 + fq * 8))
; #define LDB(dst, b, h)                                                                                               \
;   _Pragma("unroll") for (int n = 0; n < 2; ++n) _Pragma("unroll") for (int k = 0; k < 2; ++k) dst[n][k] =            \
;       *reinterpret_cast<const bf16x8*>(SB(b, h) + lds_byte(wc * 32 + n * 16 + fr, k * 32 + fq * 8))
; #define WAIT_V(n) asm volatile("s_waitcnt vmcnt(" #n ")" ::: "memory")
; #define WAIT_L(n) asm volatile("s_waitcnt lgkmcnt(" #n ")" ::: "memory")
; #define BAR __builtin_amdgcn_s_barrier()
; template <int EPI>
; __device__ __forceinline__ void gemm_phase(const u16* __restrict__ A, const u16* __restrict__ Bt, const int K,
;                                            const int nN, char* shm, const EpiArgs& ea) {
;     ...
;       LDA(At, 0, 1); WAIT_V(4); BAR; WAIT_L(0); MMA(1, 0, At, B0); MMA(1, 1, At, B1); BAR;
;     }
;     {
;       LDB(B0, 1, 0); LDA(At, 1, 0); WAIT_V(2); BAR; WAIT_L(0); MMA(0, 0, At, B0); BAR;
	s_nop 0
	ds_read_b128 v[72:75], v147 offset:16384
	ds_read_b128 v[76:79], v147 offset:17408
	ds_read_b128 v[88:91], v148 offset:16384
	ds_read_b128 v[92:95], v148 offset:17408
	ds_read_b128 v[170:173], v149 offset:16384
	ds_read_b128 v[176:179], v149 offset:17408
	ds_read_b128 v[180:183], v150 offset:16384
	ds_read_b128 v[184:187], v150 offset:17408
	s_waitcnt vmcnt(4)
	s_barrier
	s_setprio 1
	s_waitcnt lgkmcnt(7)
	v_mfma_f32_16x16x32_bf16 v[60:63], v[130:133], v[72:75], v[60:63]
	s_waitcnt lgkmcnt(5)
	v_mfma_f32_16x16x32_bf16 v[52:55], v[130:133], v[88:91], v[52:55]
	v_mfma_f32_16x16x32_bf16 v[48:51], v[138:141], v[88:91], v[48:51]
	s_waitcnt lgkmcnt(1)
	v_mfma_f32_16x16x32_bf16 v[36:39], v[130:133], v[180:183], v[36:39]
	v_mfma_f32_16x16x32_bf16 v[32:35], v[138:141], v[180:183], v[32:35]
	v_mfma_f32_16x16x32_bf16 v[60:63], v[134:137], v[76:79], v[60:63]
	v_mfma_f32_16x16x32_bf16 v[56:59], v[138:141], v[72:75], v[56:59]
	v_mfma_f32_16x16x32_bf16 v[52:55], v[134:137], v[92:95], v[52:55]
	v_mfma_f32_16x16x32_bf16 v[48:51], v[154:157], v[92:95], v[48:51]
	v_mfma_f32_16x16x32_bf16 v[44:47], v[130:133], v[170:173], v[44:47]
	v_mfma_f32_16x16x32_bf16 v[40:43], v[138:141], v[170:173], v[40:43]
	s_waitcnt lgkmcnt(0)
	v_mfma_f32_16x16x32_bf16 v[36:39], v[134:137], v[184:187], v[36:39]
	v_mfma_f32_16x16x32_bf16 v[32:35], v[154:157], v[184:187], v[32:35]
	v_mfma_f32_16x16x32_bf16 v[188:191], v[154:157], v[76:79], v[56:59]
	v_mfma_f32_16x16x32_bf16 v[212:215], v[134:137], v[176:179], v[44:47]
	v_mfma_f32_16x16x32_bf16 v[216:219], v[154:157], v[176:179], v[40:43]
	s_setprio 0
	s_setprio 1
	v_mfma_f32_16x16x32_bf16 v[20:23], v[104:107], v[88:91], v[20:23]
	v_mfma_f32_16x16x32_bf16 v[16:19], v[200:203], v[88:91], v[16:19]
	v_mfma_f32_16x16x32_bf16 v[4:7], v[104:107], v[180:183], v[4:7]
	v_mfma_f32_16x16x32_bf16 v[0:3], v[200:203], v[180:183], v[0:3]
	v_mfma_f32_16x16x32_bf16 v[28:31], v[104:107], v[72:75], v[28:31]
	v_mfma_f32_16x16x32_bf16 v[24:27], v[200:203], v[72:75], v[24:27]
	v_mfma_f32_16x16x32_bf16 v[20:23], v[108:111], v[92:95], v[20:23]
	v_mfma_f32_16x16x32_bf16 v[16:19], v[204:207], v[92:95], v[16:19]
	v_mfma_f32_16x16x32_bf16 v[12:15], v[104:107], v[170:173], v[12:15]
	v_mfma_f32_16x16x32_bf16 v[8:11], v[200:203], v[170:173], v[8:11]
	v_mfma_f32_16x16x32_bf16 v[4:7], v[108:111], v[184:187], v[4:7]
	v_mfma_f32_16x16x32_bf16 v[0:3], v[204:207], v[184:187], v[0:3]
	v_mfma_f32_16x16x32_bf16 v[130:133], v[108:111], v[76:79], v[28:31]
	v_mfma_f32_16x16x32_bf16 v[134:137], v[204:207], v[76:79], v[24:27]
	v_mfma_f32_16x16x32_bf16 v[138:141], v[108:111], v[176:179], v[12:15]
	v_mfma_f32_16x16x32_bf16 v[154:157], v[204:207], v[176:179], v[8:11]
	s_setprio 0
	s_barrier
	s_nop 0
	ds_read_b128 v[8:11], v152
	ds_read_b128 v[12:15], v152 offset:1024
	ds_read_b128 v[170:173], v152 offset:2048
	ds_read_b128 v[176:179], v152 offset:3072
	ds_read_b128 v[24:27], v147 offset:32768
	ds_read_b128 v[28:31], v147 offset:33792
	ds_read_b128 v[40:43], v148 offset:32768
	ds_read_b128 v[44:47], v148 offset:33792
	ds_read_b128 v[56:59], v149 offset:32768
	ds_read_b128 v[180:183], v149 offset:33792
	ds_read_b128 v[184:187], v150 offset:32768
	ds_read_b128 v[200:203], v150 offset:33792
	s_waitcnt vmcnt(2)
	s_barrier
	s_setprio 1
	s_waitcnt lgkmcnt(7)
	v_mfma_f32_16x16x32_bf16 v[72:75], v[8:11], v[24:27], v[124:127]
	s_waitcnt lgkmcnt(6)
	v_mfma_f32_16x16x32_bf16 v[124:127], v[12:15], v[28:31], v[72:75]
	v_mfma_f32_16x16x32_bf16 v[72:75], v[170:173], v[24:27], v[120:123]
	v_mfma_f32_16x16x32_bf16 v[120:123], v[176:179], v[28:31], v[72:75]
	s_waitcnt lgkmcnt(5)
	v_mfma_f32_16x16x32_bf16 v[72:75], v[8:11], v[40:43], v[116:119]
	s_waitcnt lgkmcnt(4)
	v_mfma_f32_16x16x32_bf16 v[104:107], v[12:15], v[44:47], v[72:75]
	v_mfma_f32_16x16x32_bf16 v[72:75], v[170:173], v[40:43], v[112:115]
	v_mfma_f32_16x16x32_bf16 v[108:111], v[176:179], v[44:47], v[72:75]
	s_waitcnt lgkmcnt(3)
	v_mfma_f32_16x16x32_bf16 v[72:75], v[8:11], v[56:59], v[192:195]
	s_waitcnt lgkmcnt(2)
	v_mfma_f32_16x16x32_bf16 v[88:91], v[12:15], v[180:183], v[72:75]
	v_mfma_f32_16x16x32_bf16 v[72:75], v[170:173], v[56:59], v[196:199]
	v_mfma_f32_16x16x32_bf16 v[92:95], v[176:179], v[180:183], v[72:75]
	s_waitcnt lgkmcnt(1)
	v_mfma_f32_16x16x32_bf16 v[72:75], v[8:11], v[184:187], v[100:103]
	v_mfma_f32_16x16x32_bf16 v[76:79], v[170:173], v[184:187], v[96:99]
	s_waitcnt lgkmcnt(0)
	v_mfma_f32_16x16x32_bf16 v[72:75], v[12:15], v[200:203], v[72:75]
	v_mfma_f32_16x16x32_bf16 v[76:79], v[176:179], v[200:203], v[76:79]
	s_setprio 0
	s_barrier
; #define LDA(dst, b, h)                                                                                               \
;   _Pragma("unroll") for (int m = 0; m < 4; ++m) _Pragma("unroll") for (int k = 0; k < 2; ++k) dst[m][k] =            \
;       *reinterpret_cast<const bf16x8*>(SA(b, h) + lds_byte(wr * 64 + m * 16 + fr, k * 32 + fq * 8))
; #define LDB(dst, b, h)                                                                                               \
;   _Pragma("unroll") for (int n = 0; n < 2; ++n) _Pragma("unroll") for (int k = 0; k < 2; ++k) dst[n][k] =            \
;       *reinterpret_cast<const bf16x8*>(SB(b, h) + lds_byte(wc * 32 + n * 16 + fr, k * 32 + fq * 8))
; #define WAIT_V(n) asm volatile("s_waitcnt vmcnt(" #n ")" ::: "memory")
; #define WAIT_L(n) asm volatile("s_waitcnt lgkmcnt(" #n ")" ::: "memory")
; #define BAR __builtin_amdgcn_s_barrier()
; template <int EPI>
; __device__ __forceinline__ void gemm_phase(const u16* __restrict__ A, const u16* __restrict__ Bt, const int K,
;                                            const int nN, char* shm, const EpiArgs& ea) {
;     ...
;       LDB(B0, 1, 0); LDA(At, 1, 0); WAIT_V(2); BAR; WAIT_L(0); MMA(0, 0, At, B0); BAR;
;       LDB(B1, 1, 1); WAIT_V(0); BAR; WAIT_L(0); MMA(0, 1, At, B1); BAR;
;       LDA(At, 1, 1); BAR; WAIT_L(0); MMA(1, 0, At, B0); MMA(1, 1, At, B1); BAR;
;     }
;     if (wr == 0) BAR;
	ds_read_b128 v[192:195], v153
	ds_read_b128 v[196:199], v153 offset:1024
	ds_read_b128 v[204:207], v153 offset:2048
	ds_read_b128 v[220:223], v153 offset:3072
	s_waitcnt vmcnt(0)
	s_barrier
	s_setprio 1
	s_waitcnt lgkmcnt(3)
	v_mfma_f32_16x16x32_bf16 v[96:99], v[192:195], v[24:27], v[208:211]
	s_waitcnt lgkmcnt(1)
	v_mfma_f32_16x16x32_bf16 v[24:27], v[204:207], v[24:27], v[158:161]
	s_waitcnt lgkmcnt(0)
	v_mfma_f32_16x16x32_bf16 v[112:115], v[220:223], v[28:31], v[24:27]
	v_mfma_f32_16x16x32_bf16 v[24:27], v[192:195], v[40:43], v[84:87]
	v_mfma_f32_16x16x32_bf16 v[100:103], v[196:199], v[44:47], v[24:27]
	v_mfma_f32_16x16x32_bf16 v[24:27], v[204:207], v[40:43], v[80:83]
	v_mfma_f32_16x16x32_bf16 v[116:119], v[196:199], v[28:31], v[96:99]
	v_mfma_f32_16x16x32_bf16 v[96:99], v[220:223], v[44:47], v[24:27]
	v_mfma_f32_16x16x32_bf16 v[24:27], v[192:195], v[56:59], v[162:165]
	v_mfma_f32_16x16x32_bf16 v[84:87], v[196:199], v[180:183], v[24:27]
	v_mfma_f32_16x16x32_bf16 v[24:27], v[204:207], v[56:59], v[166:169]
	v_mfma_f32_16x16x32_bf16 v[80:83], v[220:223], v[180:183], v[24:27]
	v_mfma_f32_16x16x32_bf16 v[24:27], v[192:195], v[184:187], v[68:71]
	v_mfma_f32_16x16x32_bf16 v[68:71], v[196:199], v[200:203], v[24:27]
	v_mfma_f32_16x16x32_bf16 v[24:27], v[204:207], v[184:187], v[64:67]
	v_mfma_f32_16x16x32_bf16 v[64:67], v[220:223], v[200:203], v[24:27]
	s_setprio 0
	s_barrier
	ds_read_b128 v[158:161], v147 offset:49152
	ds_read_b128 v[162:165], v147 offset:50176
	ds_read_b128 v[166:169], v148 offset:49152
	ds_read_b128 v[180:183], v148 offset:50176
	ds_read_b128 v[184:187], v149 offset:49152
	ds_read_b128 v[200:203], v149 offset:50176
	ds_read_b128 v[208:211], v150 offset:49152
	ds_read_b128 v[224:227], v150 offset:50176
	s_barrier
	s_setprio 1
	s_waitcnt lgkmcnt(7)
	v_mfma_f32_16x16x32_bf16 v[24:27], v[8:11], v[158:161], v[60:63]
	s_waitcnt lgkmcnt(6)
	v_mfma_f32_16x16x32_bf16 v[56:59], v[12:15], v[162:165], v[24:27]
	v_mfma_f32_16x16x32_bf16 v[24:27], v[170:173], v[158:161], v[188:191]
	v_mfma_f32_16x16x32_bf16 v[60:63], v[176:179], v[162:165], v[24:27]
	s_waitcnt lgkmcnt(5)
	v_mfma_f32_16x16x32_bf16 v[24:27], v[8:11], v[166:169], v[52:55]
	s_waitcnt lgkmcnt(4)
	v_mfma_f32_16x16x32_bf16 v[40:43], v[12:15], v[180:183], v[24:27]
	v_mfma_f32_16x16x32_bf16 v[24:27], v[170:173], v[166:169], v[48:51]
	v_mfma_f32_16x16x32_bf16 v[44:47], v[176:179], v[180:183], v[24:27]
	s_waitcnt lgkmcnt(3)
	v_mfma_f32_16x16x32_bf16 v[24:27], v[8:11], v[184:187], v[212:215]
	s_waitcnt lgkmcnt(1)
	v_mfma_f32_16x16x32_bf16 v[8:11], v[8:11], v[208:211], v[36:39]
	v_mfma_f32_16x16x32_bf16 v[24:27], v[12:15], v[200:203], v[24:27]
	v_mfma_f32_16x16x32_bf16 v[28:31], v[170:173], v[184:187], v[216:219]
	s_waitcnt lgkmcnt(0)
	v_mfma_f32_16x16x32_bf16 v[8:11], v[12:15], v[224:227], v[8:11]
	v_mfma_f32_16x16x32_bf16 v[12:15], v[170:173], v[208:211], v[32:35]
	v_mfma_f32_16x16x32_bf16 v[28:31], v[176:179], v[200:203], v[28:31]
	v_mfma_f32_16x16x32_bf16 v[12:15], v[176:179], v[224:227], v[12:15]
	s_setprio 0
	s_setprio 1
	v_mfma_f32_16x16x32_bf16 v[32:35], v[192:195], v[158:161], v[130:133]
	v_mfma_f32_16x16x32_bf16 v[52:55], v[196:199], v[162:165], v[32:35]
	v_mfma_f32_16x16x32_bf16 v[32:35], v[204:207], v[158:161], v[134:137]
	v_mfma_f32_16x16x32_bf16 v[16:19], v[204:207], v[166:169], v[16:19]
	v_mfma_f32_16x16x32_bf16 v[48:51], v[220:223], v[162:165], v[32:35]
	v_mfma_f32_16x16x32_bf16 v[20:23], v[192:195], v[166:169], v[20:23]
	v_mfma_f32_16x16x32_bf16 v[32:35], v[220:223], v[180:183], v[16:19]
	v_mfma_f32_16x16x32_bf16 v[16:19], v[192:195], v[184:187], v[138:141]
	v_mfma_f32_16x16x32_bf16 v[36:39], v[196:199], v[180:183], v[20:23]
	v_mfma_f32_16x16x32_bf16 v[20:23], v[196:199], v[200:203], v[16:19]
	v_mfma_f32_16x16x32_bf16 v[16:19], v[204:207], v[184:187], v[154:157]
	v_mfma_f32_16x16x32_bf16 v[4:7], v[192:195], v[208:211], v[4:7]
	v_mfma_f32_16x16x32_bf16 v[0:3], v[204:207], v[208:211], v[0:3]
	v_mfma_f32_16x16x32_bf16 v[16:19], v[220:223], v[200:203], v[16:19]
	v_mfma_f32_16x16x32_bf16 v[4:7], v[196:199], v[224:227], v[4:7]
	v_mfma_f32_16x16x32_bf16 v[0:3], v[220:223], v[224:227], v[0:3]
	s_setprio 0
	s_andn2_b64 vcc, exec, s[18:19]
	s_barrier
	s_cbranch_vccnz .LBB0_495
	s_barrier

; #define LDA(dst, b, h)                                                                                               \
;   _Pragma("unroll") for (int m = 0; m < 4; ++m) _Pragma("unroll") for (int k = 0; k < 2; ++k) dst[m][k] =            \
;       *reinterpret_cast<const bf16x8*>(SA(b, h) + lds_byte(wr * 64 + m * 16 + fr, k * 32 + fq * 8))
; #define LDB(dst, b, h)                                                                                               \
;   _Pragma("unroll") for (int n = 0; n < 2; ++n) _Pragma("unroll") for (int k = 0; k < 2; ++k) dst[n][k] =            \
;       *reinterpret_cast<const bf16x8*>(SB(b, h) + lds_byte(wc * 32 + n * 16 + fr, k * 32 + fq * 8))
; #define WAIT_V(n) asm volatile("s_waitcnt vmcnt(" #n ")" ::: "memory")
; #define WAIT_L(n) asm volatile("s_waitcnt lgkmcnt(" #n ")" ::: "memory")
; #define BAR __builtin_amdgcn_s_barrier()
; #define SCHED __builtin_amdgcn_sched_barrier(0)
; template <int EPI>
; __device__ __forceinline__ void gemm_phase(const u16* __restrict__ A, const u16* __restrict__ Bt, const int K,
;                                            const int nN, char* shm, const EpiArgs& ea) {
;     ...
;       LDB(B0, 0, 0); SCHED; LDA(At, 0, 0); STAGE(SA(1, 1), rA, brow + HALF, t + 1);
;       WAIT_V(10); WAIT_L(8); BAR; WAIT_L(0); MMA(0, 0, At, B0); BAR; SCHED;
;       LDB(B1, 0, 1); STAGE(SB(0, 0), rB, bcol, t + 2);
;       WAIT_V(10); BAR; WAIT_L(0); MMA(0, 1, At, B1); BAR;
;       LDA(At, 0, 1); STAGE(SA(0, 0), rA, brow, t + 2);
;       BAR; WAIT_L(0); MMA(1, 0, At, B0); BAR; SCHED;
.LBB0_565:
	ds_read_b128 v[128:131], v183
	ds_read_b128 v[132:135], v183 offset:1024
	ds_read_b128 v[136:139], v183 offset:2048
	ds_read_b128 v[140:143], v183 offset:3072
	s_add_i32 s64, s58, s63
	s_mov_b32 m0, s46
	s_add_i32 s6, s64, 0x4000
	ds_read_b128 v[144:147], v184
	ds_read_b128 v[148:151], v184 offset:1024
	ds_read_b128 v[152:155], v185
	ds_read_b128 v[156:159], v185 offset:1024
	ds_read_b128 v[160:163], v186
	ds_read_b128 v[164:167], v186 offset:1024
	ds_read_b128 v[168:171], v187
	ds_read_b128 v[192:195], v187 offset:1024
	buffer_load_dwordx4 v175, s[0:3], s6 offen lds
	s_add_i32 s6, s64, 0x6000
	s_mov_b32 m0, s47
	s_nop 0
	buffer_load_dwordx4 v175, s[0:3], s6 offen lds
	s_waitcnt vmcnt(10)
	s_waitcnt lgkmcnt(8)
	s_barrier
	s_setprio 1
	s_waitcnt lgkmcnt(7)
	v_mfma_f32_16x16x32_bf16 v[124:127], v[128:131], v[144:147], v[124:127]
	v_mfma_f32_16x16x32_bf16 v[120:123], v[136:139], v[144:147], v[120:123]
	s_waitcnt lgkmcnt(5)
	v_mfma_f32_16x16x32_bf16 v[116:119], v[128:131], v[152:155], v[116:119]
	v_mfma_f32_16x16x32_bf16 v[112:115], v[136:139], v[152:155], v[112:115]
	s_waitcnt lgkmcnt(3)
	v_mfma_f32_16x16x32_bf16 v[108:111], v[128:131], v[160:163], v[108:111]
	v_mfma_f32_16x16x32_bf16 v[104:107], v[136:139], v[160:163], v[104:107]
	s_waitcnt lgkmcnt(1)
	v_mfma_f32_16x16x32_bf16 v[100:103], v[128:131], v[168:171], v[100:103]
	v_mfma_f32_16x16x32_bf16 v[96:99], v[136:139], v[168:171], v[96:99]
	v_mfma_f32_16x16x32_bf16 v[124:127], v[132:135], v[148:151], v[124:127]
	v_mfma_f32_16x16x32_bf16 v[120:123], v[140:143], v[148:151], v[120:123]
	v_mfma_f32_16x16x32_bf16 v[116:119], v[132:135], v[156:159], v[116:119]
	v_mfma_f32_16x16x32_bf16 v[112:115], v[140:143], v[156:159], v[112:115]
	v_mfma_f32_16x16x32_bf16 v[108:111], v[132:135], v[164:167], v[108:111]
	v_mfma_f32_16x16x32_bf16 v[104:107], v[140:143], v[164:167], v[104:107]
	s_waitcnt lgkmcnt(0)
	v_mfma_f32_16x16x32_bf16 v[100:103], v[132:135], v[192:195], v[100:103]
	v_mfma_f32_16x16x32_bf16 v[96:99], v[140:143], v[192:195], v[96:99]
	s_setprio 0
	s_barrier
	s_add_i32 s65, s61, s63
	s_mov_b32 m0, s30
	s_add_i32 s66, s65, 0x8000
	s_mov_b32 s6, s2
	s_mov_b32 s7, s3
	ds_read_b128 v[196:199], v188
	ds_read_b128 v[200:203], v188 offset:1024
	ds_read_b128 v[204:207], v188 offset:2048
	ds_read_b128 v[208:211], v188 offset:3072
	buffer_load_dwordx4 v175, s[4:7], s66 offen lds
	s_add_i32 s66, s65, 0xa000
	s_mov_b32 m0, s31
	s_nop 0
	buffer_load_dwordx4 v175, s[4:7], s66 offen lds
	s_waitcnt vmcnt(10)
	s_barrier
	s_setprio 1
	s_waitcnt lgkmcnt(3)
	v_mfma_f32_16x16x32_bf16 v[92:95], v[196:199], v[144:147], v[92:95]
	s_waitcnt lgkmcnt(1)
	v_mfma_f32_16x16x32_bf16 v[88:91], v[204:207], v[144:147], v[88:91]
	v_mfma_f32_16x16x32_bf16 v[84:87], v[196:199], v[152:155], v[84:87]
	v_mfma_f32_16x16x32_bf16 v[80:83], v[204:207], v[152:155], v[80:83]
	v_mfma_f32_16x16x32_bf16 v[76:79], v[196:199], v[160:163], v[76:79]
	v_mfma_f32_16x16x32_bf16 v[72:75], v[204:207], v[160:163], v[72:75]
	v_mfma_f32_16x16x32_bf16 v[68:71], v[196:199], v[168:171], v[68:71]
	v_mfma_f32_16x16x32_bf16 v[64:67], v[204:207], v[168:171], v[64:67]
	v_mfma_f32_16x16x32_bf16 v[92:95], v[200:203], v[148:151], v[92:95]
	s_waitcnt lgkmcnt(0)
	v_mfma_f32_16x16x32_bf16 v[88:91], v[208:211], v[148:151], v[88:91]
	v_mfma_f32_16x16x32_bf16 v[84:87], v[200:203], v[156:159], v[84:87]
	v_mfma_f32_16x16x32_bf16 v[80:83], v[208:211], v[156:159], v[80:83]
	v_mfma_f32_16x16x32_bf16 v[76:79], v[200:203], v[164:167], v[76:79]
	v_mfma_f32_16x16x32_bf16 v[72:75], v[208:211], v[164:167], v[72:75]
	v_mfma_f32_16x16x32_bf16 v[68:71], v[200:203], v[192:195], v[68:71]
	v_mfma_f32_16x16x32_bf16 v[64:67], v[208:211], v[192:195], v[64:67]
	s_setprio 0
	s_add_i32 s66, s60, s63
	s_mov_b32 m0, s33
	s_add_i32 s67, s66, 0x8000
	s_barrier
	ds_read_b128 v[144:147], v184 offset:16384
	ds_read_b128 v[148:151], v184 offset:17408
	ds_read_b128 v[152:155], v185 offset:16384
	ds_read_b128 v[156:159], v185 offset:17408
	ds_read_b128 v[160:163], v186 offset:16384
	ds_read_b128 v[164:167], v186 offset:17408
	ds_read_b128 v[168:171], v187 offset:16384
	ds_read_b128 v[192:195], v187 offset:17408
	buffer_load_dwordx4 v175, s[0:3], s67 offen lds
	s_add_i32 s67, s66, 0xa000
	s_mov_b32 m0, s34
	s_nop 0
	buffer_load_dwordx4 v175, s[0:3], s67 offen lds
	s_barrier
	s_setprio 1
	s_waitcnt lgkmcnt(7)
	v_mfma_f32_16x16x32_bf16 v[60:63], v[128:131], v[144:147], v[60:63]
	v_mfma_f32_16x16x32_bf16 v[56:59], v[136:139], v[144:147], v[56:59]
	s_waitcnt lgkmcnt(5)
	v_mfma_f32_16x16x32_bf16 v[52:55], v[128:131], v[152:155], v[52:55]
	v_mfma_f32_16x16x32_bf16 v[48:51], v[136:139], v[152:155], v[48:51]
	s_waitcnt lgkmcnt(3)
	v_mfma_f32_16x16x32_bf16 v[44:47], v[128:131], v[160:163], v[44:47]
	v_mfma_f32_16x16x32_bf16 v[40:43], v[136:139], v[160:163], v[40:43]
	s_waitcnt lgkmcnt(1)
	v_mfma_f32_16x16x32_bf16 v[36:39], v[128:131], v[168:171], v[36:39]
	v_mfma_f32_16x16x32_bf16 v[32:35], v[136:139], v[168:171], v[32:35]
	v_mfma_f32_16x16x32_bf16 v[60:63], v[132:135], v[148:151], v[60:63]
	v_mfma_f32_16x16x32_bf16 v[56:59], v[140:143], v[148:151], v[56:59]
	v_mfma_f32_16x16x32_bf16 v[52:55], v[132:135], v[156:159], v[52:55]
	v_mfma_f32_16x16x32_bf16 v[48:51], v[140:143], v[156:159], v[48:51]
	v_mfma_f32_16x16x32_bf16 v[44:47], v[132:135], v[164:167], v[44:47]
	v_mfma_f32_16x16x32_bf16 v[40:43], v[140:143], v[164:167], v[40:43]
	s_waitcnt lgkmcnt(0)
	v_mfma_f32_16x16x32_bf16 v[36:39], v[132:135], v[192:195], v[36:39]
	v_mfma_f32_16x16x32_bf16 v[32:35], v[140:143], v[192:195], v[32:35]
	s_setprio 0
	s_barrier
; #define LDA(dst, b, h)                                                                                               \
;   _Pragma("unroll") for (int m = 0; m < 4; ++m) _Pragma("unroll") for (int k = 0; k < 2; ++k) dst[m][k] =            \
;       *reinterpret_cast<const bf16x8*>(SA(b, h) + lds_byte(wr * 64 + m * 16 + fr, k * 32 + fq * 8))
; #define LDB(dst, b, h)                                                                                               \
;   _Pragma("unroll") for (int n = 0; n < 2; ++n) _Pragma("unroll") for (int k = 0; k < 2; ++k) dst[n][k] =            \
;       *reinterpret_cast<const bf16x8*>(SB(b, h) + lds_byte(wc * 32 + n * 16 + fr, k * 32 + fq * 8))
; #define WAIT_V(n) asm volatile("s_waitcnt vmcnt(" #n ")" ::: "memory")
; #define WAIT_L(n) asm volatile("s_waitcnt lgkmcnt(" #n ")" ::: "memory")
; #define BAR __builtin_amdgcn_s_barrier()
; #define SCHED __builtin_amdgcn_sched_barrier(0)
; template <int EPI>
; __device__ __forceinline__ void gemm_phase(const u16* __restrict__ A, const u16* __restrict__ Bt, const int K,
;                                            const int nN, char* shm, const EpiArgs& ea) {
;     ...
;       STAGE(SB(0, 1), rB, bcol + HALF, t + 2);
;       WAIT_V(10); BAR; MMA(1, 1, At, B1); BAR;
;       LDB(B0, 1, 0); SCHED; LDA(At, 1, 0); STAGE(SA(0, 1), rA, brow + HALF, t + 2);
;       WAIT_V(10); WAIT_L(8); BAR; WAIT_L(0); MMA(0, 0, At, B0); BAR; SCHED;
;       LDB(B1, 1, 1); STAGE(SB(1, 0), rB, bcol, t + 3);
;       WAIT_V(10); BAR; WAIT_L(0); MMA(0, 1, At, B1); BAR;
;       LDA(At, 1, 1); STAGE(SA(1, 0), rA, brow, t + 3);
	s_add_i32 s67, s59, s63
	s_mov_b32 m0, s35
	s_add_i32 s68, s67, 0x8000
	buffer_load_dwordx4 v175, s[4:7], s68 offen lds
	s_add_i32 s68, s67, 0xa000
	s_mov_b32 m0, s36
	s_nop 0
	buffer_load_dwordx4 v175, s[4:7], s68 offen lds
	s_waitcnt vmcnt(10)
	s_barrier
	s_setprio 1
	v_mfma_f32_16x16x32_bf16 v[28:31], v[196:199], v[144:147], v[28:31]
	v_mfma_f32_16x16x32_bf16 v[24:27], v[204:207], v[144:147], v[24:27]
	v_mfma_f32_16x16x32_bf16 v[20:23], v[196:199], v[152:155], v[20:23]
	v_mfma_f32_16x16x32_bf16 v[16:19], v[204:207], v[152:155], v[16:19]
	v_mfma_f32_16x16x32_bf16 v[12:15], v[196:199], v[160:163], v[12:15]
	v_mfma_f32_16x16x32_bf16 v[8:11], v[204:207], v[160:163], v[8:11]
	v_mfma_f32_16x16x32_bf16 v[4:7], v[196:199], v[168:171], v[4:7]
	v_mfma_f32_16x16x32_bf16 v[0:3], v[204:207], v[168:171], v[0:3]
	v_mfma_f32_16x16x32_bf16 v[28:31], v[200:203], v[148:151], v[28:31]
	v_mfma_f32_16x16x32_bf16 v[24:27], v[208:211], v[148:151], v[24:27]
	v_mfma_f32_16x16x32_bf16 v[20:23], v[200:203], v[156:159], v[20:23]
	v_mfma_f32_16x16x32_bf16 v[16:19], v[208:211], v[156:159], v[16:19]
	v_mfma_f32_16x16x32_bf16 v[12:15], v[200:203], v[164:167], v[12:15]
	v_mfma_f32_16x16x32_bf16 v[8:11], v[208:211], v[164:167], v[8:11]
	v_mfma_f32_16x16x32_bf16 v[4:7], v[200:203], v[192:195], v[4:7]
	v_mfma_f32_16x16x32_bf16 v[0:3], v[208:211], v[192:195], v[0:3]
	s_setprio 0
	s_barrier
	ds_read_b128 v[128:131], v189
	ds_read_b128 v[132:135], v189 offset:1024
	ds_read_b128 v[136:139], v189 offset:2048
	ds_read_b128 v[140:143], v189 offset:3072
	s_mov_b32 m0, s37
	s_add_i32 s68, s64, 0x8000
	ds_read_b128 v[144:147], v184 offset:32768
	ds_read_b128 v[148:151], v184 offset:33792
	ds_read_b128 v[152:155], v185 offset:32768
	ds_read_b128 v[156:159], v185 offset:33792
	ds_read_b128 v[160:163], v186 offset:32768
	ds_read_b128 v[164:167], v186 offset:33792
	ds_read_b128 v[168:171], v187 offset:32768
	ds_read_b128 v[192:195], v187 offset:33792
	buffer_load_dwordx4 v175, s[0:3], s68 offen lds
	s_add_i32 s64, s64, 0xa000
	s_mov_b32 m0, s38
	s_nop 0
	buffer_load_dwordx4 v175, s[0:3], s64 offen lds
	s_waitcnt vmcnt(10)
	s_waitcnt lgkmcnt(8)
	s_barrier
	s_setprio 1
	s_waitcnt lgkmcnt(7)
	v_mfma_f32_16x16x32_bf16 v[124:127], v[128:131], v[144:147], v[124:127]
	v_mfma_f32_16x16x32_bf16 v[120:123], v[136:139], v[144:147], v[120:123]
	s_waitcnt lgkmcnt(5)
	v_mfma_f32_16x16x32_bf16 v[116:119], v[128:131], v[152:155], v[116:119]
	v_mfma_f32_16x16x32_bf16 v[112:115], v[136:139], v[152:155], v[112:115]
	s_waitcnt lgkmcnt(3)
	v_mfma_f32_16x16x32_bf16 v[108:111], v[128:131], v[160:163], v[108:111]
	v_mfma_f32_16x16x32_bf16 v[104:107], v[136:139], v[160:163], v[104:107]
	s_waitcnt lgkmcnt(1)
	v_mfma_f32_16x16x32_bf16 v[100:103], v[128:131], v[168:171], v[100:103]
	v_mfma_f32_16x16x32_bf16 v[96:99], v[136:139], v[168:171], v[96:99]
	v_mfma_f32_16x16x32_bf16 v[124:127], v[132:135], v[148:151], v[124:127]
	v_mfma_f32_16x16x32_bf16 v[120:123], v[140:143], v[148:151], v[120:123]
	v_mfma_f32_16x16x32_bf16 v[116:119], v[132:135], v[156:159], v[116:119]
	v_mfma_f32_16x16x32_bf16 v[112:115], v[140:143], v[156:159], v[112:115]
	v_mfma_f32_16x16x32_bf16 v[108:111], v[132:135], v[164:167], v[108:111]
	v_mfma_f32_16x16x32_bf16 v[104:107], v[140:143], v[164:167], v[104:107]
	s_waitcnt lgkmcnt(0)
	v_mfma_f32_16x16x32_bf16 v[100:103], v[132:135], v[192:195], v[100:103]
	v_mfma_f32_16x16x32_bf16 v[96:99], v[140:143], v[192:195], v[96:99]
	s_setprio 0
	s_barrier
	s_mov_b32 m0, s39
	s_add_i32 s64, s65, 0xc000
	ds_read_b128 v[196:199], v190
	ds_read_b128 v[200:203], v190 offset:1024
	ds_read_b128 v[204:207], v190 offset:2048
	ds_read_b128 v[208:211], v190 offset:3072
	buffer_load_dwordx4 v175, s[4:7], s64 offen lds
	s_add_i32 s65, s65, 0xe000
	s_mov_b32 m0, s40
	s_nop 0
	buffer_load_dwordx4 v175, s[4:7], s65 offen lds
	s_waitcnt vmcnt(10)
	s_barrier
; #define LDA(dst, b, h)                                                                                               \
;   _Pragma("unroll") for (int m = 0; m < 4; ++m) _Pragma("unroll") for (int k = 0; k < 2; ++k) dst[m][k] =            \
;       *reinterpret_cast<const bf16x8*>(SA(b, h) + lds_byte(wr * 64 + m * 16 + fr, k * 32 + fq * 8))
; #define WAIT_V(n) asm volatile("s_waitcnt vmcnt(" #n ")" ::: "memory")
; #define WAIT_L(n) asm volatile("s_waitcnt lgkmcnt(" #n ")" ::: "memory")
; #define BAR __builtin_amdgcn_s_barrier()
; #define SCHED __builtin_amdgcn_sched_barrier(0)
; template <int EPI>
; __device__ __forceinline__ void gemm_phase(const u16* __restrict__ A, const u16* __restrict__ Bt, const int K,
;                                            const int nN, char* shm, const EpiArgs& ea) {
;     ...
;       WAIT_V(10); BAR; WAIT_L(0); MMA(0, 1, At, B1); BAR;
;       LDA(At, 1, 1); STAGE(SA(1, 0), rA, brow, t + 3);
;       BAR; WAIT_L(0); MMA(1, 0, At, B0); BAR; SCHED;
;       STAGE(SB(1, 1), rB, bcol + HALF, t + 3);
;       WAIT_V(10); BAR; MMA(1, 1, At, B1); BAR;
;     }
;     float eC = 0.f, eB = 0.f;
;     float2 eS = make_float2(0.f, 0.f);
;     if (EPI == EPI_IN || EPI == EPI_SWIGLU_LN) {
;       if (wr == 0) {
;         eC = ea.c1[bcol + tid];
;         eS = *(const float2*)(ea.st_in + (size_t)(brow + tid) * 2);
;       } else {
;         eC = ea.c2[bcol + tid - 256];
;         if (EPI == EPI_IN) eB = ea.bias[bcol + tid - 256];
;       }
	s_setprio 1
	s_waitcnt lgkmcnt(3)
	v_mfma_f32_16x16x32_bf16 v[92:95], v[196:199], v[144:147], v[92:95]
	s_waitcnt lgkmcnt(1)
	v_mfma_f32_16x16x32_bf16 v[88:91], v[204:207], v[144:147], v[88:91]
	v_mfma_f32_16x16x32_bf16 v[84:87], v[196:199], v[152:155], v[84:87]
	v_mfma_f32_16x16x32_bf16 v[80:83], v[204:207], v[152:155], v[80:83]
	v_mfma_f32_16x16x32_bf16 v[76:79], v[196:199], v[160:163], v[76:79]
	v_mfma_f32_16x16x32_bf16 v[72:75], v[204:207], v[160:163], v[72:75]
	v_mfma_f32_16x16x32_bf16 v[68:71], v[196:199], v[168:171], v[68:71]
	v_mfma_f32_16x16x32_bf16 v[64:67], v[204:207], v[168:171], v[64:67]
	v_mfma_f32_16x16x32_bf16 v[92:95], v[200:203], v[148:151], v[92:95]
	s_waitcnt lgkmcnt(0)
	v_mfma_f32_16x16x32_bf16 v[88:91], v[208:211], v[148:151], v[88:91]
	v_mfma_f32_16x16x32_bf16 v[84:87], v[200:203], v[156:159], v[84:87]
	v_mfma_f32_16x16x32_bf16 v[80:83], v[208:211], v[156:159], v[80:83]
	v_mfma_f32_16x16x32_bf16 v[76:79], v[200:203], v[164:167], v[76:79]
	v_mfma_f32_16x16x32_bf16 v[72:75], v[208:211], v[164:167], v[72:75]
	v_mfma_f32_16x16x32_bf16 v[68:71], v[200:203], v[192:195], v[68:71]
	v_mfma_f32_16x16x32_bf16 v[64:67], v[208:211], v[192:195], v[64:67]
	s_setprio 0
	s_mov_b32 m0, s41
	s_add_i32 s64, s66, 0xc000
	s_barrier
	ds_read_b128 v[144:147], v184 offset:49152
	ds_read_b128 v[148:151], v184 offset:50176
	ds_read_b128 v[152:155], v185 offset:49152
	ds_read_b128 v[156:159], v185 offset:50176
	ds_read_b128 v[160:163], v186 offset:49152
	ds_read_b128 v[164:167], v186 offset:50176
	ds_read_b128 v[168:171], v187 offset:49152
	ds_read_b128 v[192:195], v187 offset:50176
	buffer_load_dwordx4 v175, s[0:3], s64 offen lds
	s_add_i32 s66, s66, 0xe000
	s_mov_b32 m0, s42
	s_nop 0
	buffer_load_dwordx4 v175, s[0:3], s66 offen lds
	s_barrier
	s_setprio 1
	s_waitcnt lgkmcnt(7)
	v_mfma_f32_16x16x32_bf16 v[60:63], v[128:131], v[144:147], v[60:63]
	v_mfma_f32_16x16x32_bf16 v[56:59], v[136:139], v[144:147], v[56:59]
	s_waitcnt lgkmcnt(5)
	v_mfma_f32_16x16x32_bf16 v[52:55], v[128:131], v[152:155], v[52:55]
	v_mfma_f32_16x16x32_bf16 v[48:51], v[136:139], v[152:155], v[48:51]
	s_waitcnt lgkmcnt(3)
	v_mfma_f32_16x16x32_bf16 v[44:47], v[128:131], v[160:163], v[44:47]
	v_mfma_f32_16x16x32_bf16 v[40:43], v[136:139], v[160:163], v[40:43]
	s_waitcnt lgkmcnt(1)
	v_mfma_f32_16x16x32_bf16 v[36:39], v[128:131], v[168:171], v[36:39]
	v_mfma_f32_16x16x32_bf16 v[32:35], v[136:139], v[168:171], v[32:35]
	v_mfma_f32_16x16x32_bf16 v[60:63], v[132:135], v[148:151], v[60:63]
	v_mfma_f32_16x16x32_bf16 v[56:59], v[140:143], v[148:151], v[56:59]
	v_mfma_f32_16x16x32_bf16 v[52:55], v[132:135], v[156:159], v[52:55]
	v_mfma_f32_16x16x32_bf16 v[48:51], v[140:143], v[156:159], v[48:51]
	v_mfma_f32_16x16x32_bf16 v[44:47], v[132:135], v[164:167], v[44:47]
	v_mfma_f32_16x16x32_bf16 v[40:43], v[140:143], v[164:167], v[40:43]
	s_waitcnt lgkmcnt(0)
	v_mfma_f32_16x16x32_bf16 v[36:39], v[132:135], v[192:195], v[36:39]
	v_mfma_f32_16x16x32_bf16 v[32:35], v[140:143], v[192:195], v[32:35]
	s_setprio 0
	s_barrier
	s_mov_b32 m0, s43
	s_add_i32 s64, s67, 0xc000
	buffer_load_dwordx4 v175, s[4:7], s64 offen lds
	s_add_i32 s67, s67, 0xe000
	s_mov_b32 m0, s44
	s_nop 0
	buffer_load_dwordx4 v175, s[4:7], s67 offen lds
	s_waitcnt vmcnt(10)
	s_barrier
	s_setprio 1
	v_mfma_f32_16x16x32_bf16 v[28:31], v[196:199], v[144:147], v[28:31]
	v_mfma_f32_16x16x32_bf16 v[24:27], v[204:207], v[144:147], v[24:27]
	v_mfma_f32_16x16x32_bf16 v[20:23], v[196:199], v[152:155], v[20:23]
	v_mfma_f32_16x16x32_bf16 v[16:19], v[204:207], v[152:155], v[16:19]
	v_mfma_f32_16x16x32_bf16 v[12:15], v[196:199], v[160:163], v[12:15]
	v_mfma_f32_16x16x32_bf16 v[8:11], v[204:207], v[160:163], v[8:11]
	v_mfma_f32_16x16x32_bf16 v[4:7], v[196:199], v[168:171], v[4:7]
	v_mfma_f32_16x16x32_bf16 v[0:3], v[204:207], v[168:171], v[0:3]
	v_mfma_f32_16x16x32_bf16 v[28:31], v[200:203], v[148:151], v[28:31]
	v_mfma_f32_16x16x32_bf16 v[24:27], v[208:211], v[148:151], v[24:27]
	v_mfma_f32_16x16x32_bf16 v[20:23], v[200:203], v[156:159], v[20:23]
	v_mfma_f32_16x16x32_bf16 v[16:19], v[208:211], v[156:159], v[16:19]
	v_mfma_f32_16x16x32_bf16 v[12:15], v[200:203], v[164:167], v[12:15]
	v_mfma_f32_16x16x32_bf16 v[8:11], v[208:211], v[164:167], v[8:11]
	v_mfma_f32_16x16x32_bf16 v[4:7], v[200:203], v[192:195], v[4:7]
	v_mfma_f32_16x16x32_bf16 v[0:3], v[208:211], v[192:195], v[0:3]
	s_setprio 0
	s_add_i32 s62, s62, 2
	s_add_i32 s63, s63, 0x8000
	s_cmp_lt_u32 s62, 28
	s_barrier
	s_cbranch_scc1 .LBB0_565
	v_add_u32_e32 v128, s57, v174
	v_ashrrev_i32_e32 v129, 31, v128
	s_mov_b64 s[6:7], -1
	s_and_b64 vcc, exec, s[18:19]
	s_cbranch_vccz .LBB0_568
	v_lshl_add_u64 v[130:131], v[128:129], 2, s[90:91]
	v_lshl_add_u64 v[130:131], v[130:131], 0, s[20:21]
	s_mov_b64 s[6:7], 0

; #define LDA(dst, b, h)                                                                                               \
;   _Pragma("unroll") for (int m = 0; m < 4; ++m) _Pragma("unroll") for (int k = 0; k < 2; ++k) dst[m][k] =            \
;       *reinterpret_cast<const bf16x8*>(SA(b, h) + lds_byte(wr * 64 + m * 16 + fr, k * 32 + fq * 8))
; #define LDB(dst, b, h)                                                                                               \
;   _Pragma("unroll") for (int n = 0; n < 2; ++n) _Pragma("unroll") for (int k = 0; k < 2; ++k) dst[n][k] =            \
;       *reinterpret_cast<const bf16x8*>(SB(b, h) + lds_byte(wc * 32 + n * 16 + fr, k * 32 + fq * 8))
; #define WAIT_V(n) asm volatile("s_waitcnt vmcnt(" #n ")" ::: "memory")
; #define WAIT_L(n) asm volatile("s_waitcnt lgkmcnt(" #n ")" ::: "memory")
; #define BAR __builtin_amdgcn_s_barrier()
; template <int EPI>
; __device__ __forceinline__ void gemm_phase(const u16* __restrict__ A, const u16* __restrict__ Bt, const int K,
;                                            const int nN, char* shm, const EpiArgs& ea) {
;     ...
;         eC = ea.c1[bcol + tid];
;         eS = *(const float2*)(ea.st_in + (size_t)(brow + tid) * 2);
;       } else {
;         eC = ea.c2[bcol + tid - 256];
;         if (EPI == EPI_IN) eB = ea.bias[bcol + tid - 256];
;       }
;     }
;     {
;       LDB(B0, 0, 0); LDA(At, 0, 0); STAGE(SA(1, 1), rA, brow + HALF, nt - 1);
;       WAIT_V(10); BAR; WAIT_L(0); MMA(0, 0, At, B0); BAR;
;       LDB(B1, 0, 1); WAIT_V(8); BAR; WAIT_L(0); MMA(0, 1, At, B1); BAR;
;       LDA(At, 0, 1); WAIT_V(4); BAR; WAIT_L(0); MMA(1, 0, At, B0); MMA(1, 1, At, B1); BAR;
.LBB0_570:
	s_mov_b32 m0, s46
	s_add_i32 s6, s58, 0x7c000
	global_load_dword v154, v[130:131], off
	ds_read_b128 v[128:131], v183
	ds_read_b128 v[132:135], v183 offset:1024
	ds_read_b128 v[136:139], v183 offset:2048
	ds_read_b128 v[140:143], v183 offset:3072
	ds_read_b128 v[144:147], v184
	ds_read_b128 v[148:151], v184 offset:1024
	ds_read_b128 v[156:159], v185
	ds_read_b128 v[160:163], v185 offset:1024
	ds_read_b128 v[164:167], v186
	ds_read_b128 v[168:171], v186 offset:1024
	ds_read_b128 v[192:195], v187
	ds_read_b128 v[196:199], v187 offset:1024
	buffer_load_dwordx4 v175, s[0:3], s6 offen lds
	s_add_i32 s58, s58, 0x7e000
	s_mov_b32 m0, s47
	s_nop 0
	buffer_load_dwordx4 v175, s[0:3], s58 offen lds
	s_waitcnt vmcnt(10)
	s_barrier
	s_setprio 1
	s_waitcnt lgkmcnt(7)
	v_mfma_f32_16x16x32_bf16 v[124:127], v[128:131], v[144:147], v[124:127]
	v_mfma_f32_16x16x32_bf16 v[120:123], v[136:139], v[144:147], v[120:123]
	s_waitcnt lgkmcnt(5)
	v_mfma_f32_16x16x32_bf16 v[116:119], v[128:131], v[156:159], v[116:119]
	v_mfma_f32_16x16x32_bf16 v[112:115], v[136:139], v[156:159], v[112:115]
	s_waitcnt lgkmcnt(3)
	v_mfma_f32_16x16x32_bf16 v[108:111], v[128:131], v[164:167], v[108:111]
	v_mfma_f32_16x16x32_bf16 v[104:107], v[136:139], v[164:167], v[104:107]
	s_waitcnt lgkmcnt(1)
	v_mfma_f32_16x16x32_bf16 v[100:103], v[128:131], v[192:195], v[100:103]
	v_mfma_f32_16x16x32_bf16 v[96:99], v[136:139], v[192:195], v[96:99]
	v_mfma_f32_16x16x32_bf16 v[124:127], v[132:135], v[148:151], v[124:127]
	v_mfma_f32_16x16x32_bf16 v[120:123], v[140:143], v[148:151], v[120:123]
	v_mfma_f32_16x16x32_bf16 v[116:119], v[132:135], v[160:163], v[116:119]
	v_mfma_f32_16x16x32_bf16 v[112:115], v[140:143], v[160:163], v[112:115]
	v_mfma_f32_16x16x32_bf16 v[108:111], v[132:135], v[168:171], v[108:111]
	v_mfma_f32_16x16x32_bf16 v[104:107], v[140:143], v[168:171], v[104:107]
	s_waitcnt lgkmcnt(0)
	v_mfma_f32_16x16x32_bf16 v[100:103], v[132:135], v[196:199], v[100:103]
	v_mfma_f32_16x16x32_bf16 v[96:99], v[140:143], v[196:199], v[96:99]
	s_setprio 0
	s_barrier
	ds_read_b128 v[200:203], v188
	ds_read_b128 v[204:207], v188 offset:1024
	ds_read_b128 v[208:211], v188 offset:2048
	ds_read_b128 v[212:215], v188 offset:3072
	s_waitcnt vmcnt(8)
	s_barrier
	s_setprio 1
	s_waitcnt lgkmcnt(3)
	v_mfma_f32_16x16x32_bf16 v[92:95], v[200:203], v[144:147], v[92:95]
	s_waitcnt lgkmcnt(1)
	v_mfma_f32_16x16x32_bf16 v[88:91], v[208:211], v[144:147], v[88:91]
	v_mfma_f32_16x16x32_bf16 v[84:87], v[200:203], v[156:159], v[84:87]
	v_mfma_f32_16x16x32_bf16 v[80:83], v[208:211], v[156:159], v[80:83]
	v_mfma_f32_16x16x32_bf16 v[76:79], v[200:203], v[164:167], v[76:79]
	v_mfma_f32_16x16x32_bf16 v[72:75], v[208:211], v[164:167], v[72:75]
	v_mfma_f32_16x16x32_bf16 v[68:71], v[200:203], v[192:195], v[68:71]
	v_mfma_f32_16x16x32_bf16 v[92:95], v[204:207], v[148:151], v[92:95]
	s_waitcnt lgkmcnt(0)
	v_mfma_f32_16x16x32_bf16 v[88:91], v[212:215], v[148:151], v[88:91]
	v_mfma_f32_16x16x32_bf16 v[84:87], v[204:207], v[160:163], v[84:87]
	v_mfma_f32_16x16x32_bf16 v[80:83], v[212:215], v[160:163], v[80:83]
	v_mfma_f32_16x16x32_bf16 v[76:79], v[204:207], v[168:171], v[76:79]
	v_mfma_f32_16x16x32_bf16 v[72:75], v[212:215], v[168:171], v[72:75]
	v_mfma_f32_16x16x32_bf16 v[68:71], v[204:207], v[196:199], v[68:71]
	v_mfma_f32_16x16x32_bf16 v[64:67], v[208:211], v[192:195], v[64:67]
	v_mfma_f32_16x16x32_bf16 v[64:67], v[212:215], v[196:199], v[64:67]
	s_setprio 0
	s_barrier
	ds_read_b128 v[144:147], v184 offset:16384
	ds_read_b128 v[148:151], v184 offset:17408
	ds_read_b128 v[156:159], v185 offset:16384
	ds_read_b128 v[160:163], v185 offset:17408
	ds_read_b128 v[164:167], v186 offset:16384
	ds_read_b128 v[168:171], v186 offset:17408
	ds_read_b128 v[192:195], v187 offset:16384
	ds_read_b128 v[196:199], v187 offset:17408
	s_waitcnt vmcnt(4)
	s_barrier
	s_setprio 1
	s_waitcnt lgkmcnt(3)
	v_mfma_f32_16x16x32_bf16 v[40:43], v[136:139], v[164:167], v[40:43]
	s_waitcnt lgkmcnt(1)
	v_mfma_f32_16x16x32_bf16 v[36:39], v[128:131], v[192:195], v[36:39]
	v_mfma_f32_16x16x32_bf16 v[60:63], v[128:131], v[144:147], v[60:63]
	v_mfma_f32_16x16x32_bf16 v[56:59], v[136:139], v[144:147], v[56:59]
	v_mfma_f32_16x16x32_bf16 v[52:55], v[128:131], v[156:159], v[52:55]
	v_mfma_f32_16x16x32_bf16 v[48:51], v[136:139], v[156:159], v[48:51]
	v_mfma_f32_16x16x32_bf16 v[44:47], v[128:131], v[164:167], v[44:47]
	v_mfma_f32_16x16x32_bf16 v[40:43], v[140:143], v[168:171], v[40:43]
	s_waitcnt lgkmcnt(0)
	v_mfma_f32_16x16x32_bf16 v[36:39], v[132:135], v[196:199], v[36:39]
	v_mfma_f32_16x16x32_bf16 v[32:35], v[136:139], v[192:195], v[32:35]
	v_mfma_f32_16x16x32_bf16 v[60:63], v[132:135], v[148:151], v[60:63]
	v_mfma_f32_16x16x32_bf16 v[56:59], v[140:143], v[148:151], v[56:59]
	v_mfma_f32_16x16x32_bf16 v[52:55], v[132:135], v[160:163], v[52:55]
	v_mfma_f32_16x16x32_bf16 v[48:51], v[140:143], v[160:163], v[48:51]
	v_mfma_f32_16x16x32_bf16 v[44:47], v[132:135], v[168:171], v[44:47]
	v_mfma_f32_16x16x32_bf16 v[32:35], v[140:143], v[196:199], v[32:35]
	s_setprio 0
	s_setprio 1
	v_mfma_f32_16x16x32_bf16 v[12:15], v[200:203], v[164:167], v[12:15]
	v_mfma_f32_16x16x32_bf16 v[8:11], v[208:211], v[164:167], v[8:11]
	v_mfma_f32_16x16x32_bf16 v[4:7], v[200:203], v[192:195], v[4:7]
	v_mfma_f32_16x16x32_bf16 v[0:3], v[208:211], v[192:195], v[0:3]
	v_mfma_f32_16x16x32_bf16 v[28:31], v[200:203], v[144:147], v[28:31]
	v_mfma_f32_16x16x32_bf16 v[24:27], v[208:211], v[144:147], v[24:27]
	v_mfma_f32_16x16x32_bf16 v[20:23], v[200:203], v[156:159], v[20:23]
	v_mfma_f32_16x16x32_bf16 v[16:19], v[208:211], v[156:159], v[16:19]
	v_mfma_f32_16x16x32_bf16 v[12:15], v[204:207], v[168:171], v[12:15]
	v_mfma_f32_16x16x32_bf16 v[8:11], v[212:215], v[168:171], v[8:11]
	v_mfma_f32_16x16x32_bf16 v[4:7], v[204:207], v[196:199], v[4:7]
	v_mfma_f32_16x16x32_bf16 v[0:3], v[212:215], v[196:199], v[0:3]
	v_mfma_f32_16x16x32_bf16 v[216:219], v[204:207], v[148:151], v[28:31]
	v_mfma_f32_16x16x32_bf16 v[220:223], v[212:215], v[148:151], v[24:27]
	v_mfma_f32_16x16x32_bf16 v[224:227], v[204:207], v[160:163], v[20:23]
	v_mfma_f32_16x16x32_bf16 v[160:163], v[212:215], v[160:163], v[16:19]
	s_setprio 0
	s_barrier
; #define LDA(dst, b, h)                                                                                               \
;   _Pragma("unroll") for (int m = 0; m < 4; ++m) _Pragma("unroll") for (int k = 0; k < 2; ++k) dst[m][k] =            \
;       *reinterpret_cast<const bf16x8*>(SA(b, h) + lds_byte(wr * 64 + m * 16 + fr, k * 32 + fq * 8))
; #define LDB(dst, b, h)                                                                                               \
;   _Pragma("unroll") for (int n = 0; n < 2; ++n) _Pragma("unroll") for (int k = 0; k < 2; ++k) dst[n][k] =            \
;       *reinterpret_cast<const bf16x8*>(SB(b, h) + lds_byte(wc * 32 + n * 16 + fr, k * 32 + fq * 8))
; #define WAIT_V(n) asm volatile("s_waitcnt vmcnt(" #n ")" ::: "memory")
; #define WAIT_L(n) asm volatile("s_waitcnt lgkmcnt(" #n ")" ::: "memory")
; #define BAR __builtin_amdgcn_s_barrier()
; template <int EPI>
; __device__ __forceinline__ void gemm_phase(const u16* __restrict__ A, const u16* __restrict__ Bt, const int K,
;                                            const int nN, char* shm, const EpiArgs& ea) {
;     ...
;       LDB(B0, 1, 0); LDA(At, 1, 0); WAIT_V(2); BAR; WAIT_L(0); MMA(0, 0, At, B0); BAR;
;       LDB(B1, 1, 1); WAIT_V(0); BAR; WAIT_L(0); MMA(0, 1, At, B1); BAR;
;       LDA(At, 1, 1); BAR; WAIT_L(0); MMA(1, 0, At, B0); MMA(1, 1, At, B1); BAR;
;     }
;     if (wr == 0) BAR;
;     if (has_next) STAGE7(brow2, bcol2);
	s_nop 0
	ds_read_b128 v[16:19], v189
	ds_read_b128 v[20:23], v189 offset:1024
	ds_read_b128 v[164:167], v189 offset:2048
	ds_read_b128 v[168:171], v189 offset:3072
	ds_read_b128 v[24:27], v184 offset:32768
	ds_read_b128 v[28:31], v184 offset:33792
	ds_read_b128 v[192:195], v185 offset:32768
	ds_read_b128 v[196:199], v185 offset:33792
	ds_read_b128 v[200:203], v186 offset:32768
	ds_read_b128 v[204:207], v186 offset:33792
	ds_read_b128 v[208:211], v187 offset:32768
	ds_read_b128 v[212:215], v187 offset:33792
	s_waitcnt vmcnt(2)
	s_barrier
	s_setprio 1
	s_waitcnt lgkmcnt(7)
	v_mfma_f32_16x16x32_bf16 v[124:127], v[16:19], v[24:27], v[124:127]
	v_mfma_f32_16x16x32_bf16 v[120:123], v[164:167], v[24:27], v[120:123]
	s_waitcnt lgkmcnt(5)
	v_mfma_f32_16x16x32_bf16 v[116:119], v[16:19], v[192:195], v[116:119]
	v_mfma_f32_16x16x32_bf16 v[112:115], v[164:167], v[192:195], v[112:115]
	s_waitcnt lgkmcnt(3)
	v_mfma_f32_16x16x32_bf16 v[108:111], v[16:19], v[200:203], v[108:111]
	v_mfma_f32_16x16x32_bf16 v[104:107], v[164:167], v[200:203], v[104:107]
	s_waitcnt lgkmcnt(1)
	v_mfma_f32_16x16x32_bf16 v[100:103], v[16:19], v[208:211], v[100:103]
	v_mfma_f32_16x16x32_bf16 v[96:99], v[164:167], v[208:211], v[96:99]
	v_mfma_f32_16x16x32_bf16 v[156:159], v[20:23], v[28:31], v[124:127]
	v_mfma_f32_16x16x32_bf16 v[148:151], v[168:171], v[28:31], v[120:123]
	v_mfma_f32_16x16x32_bf16 v[144:147], v[20:23], v[196:199], v[116:119]
	v_mfma_f32_16x16x32_bf16 v[140:143], v[168:171], v[196:199], v[112:115]
	v_mfma_f32_16x16x32_bf16 v[120:123], v[20:23], v[204:207], v[108:111]
	v_mfma_f32_16x16x32_bf16 v[116:119], v[168:171], v[204:207], v[104:107]
	s_waitcnt lgkmcnt(0)
	v_mfma_f32_16x16x32_bf16 v[112:115], v[20:23], v[212:215], v[100:103]
	v_mfma_f32_16x16x32_bf16 v[108:111], v[168:171], v[212:215], v[96:99]
	s_setprio 0
	s_barrier
	ds_read_b128 v[228:231], v190
	ds_read_b128 v[232:235], v190 offset:1024
	ds_read_b128 v[236:239], v190 offset:2048
	ds_read_b128 v[240:243], v190 offset:3072
	s_waitcnt vmcnt(0)
	s_barrier
	s_setprio 1
	s_waitcnt lgkmcnt(3)
	v_mfma_f32_16x16x32_bf16 v[92:95], v[228:231], v[24:27], v[92:95]
	s_waitcnt lgkmcnt(1)
	v_mfma_f32_16x16x32_bf16 v[24:27], v[236:239], v[24:27], v[88:91]
	s_waitcnt lgkmcnt(0)
	v_mfma_f32_16x16x32_bf16 v[132:135], v[240:243], v[28:31], v[24:27]
	v_mfma_f32_16x16x32_bf16 v[24:27], v[228:231], v[192:195], v[84:87]
	v_mfma_f32_16x16x32_bf16 v[128:131], v[232:235], v[196:199], v[24:27]
	v_mfma_f32_16x16x32_bf16 v[24:27], v[236:239], v[192:195], v[80:83]
	v_mfma_f32_16x16x32_bf16 v[124:127], v[240:243], v[196:199], v[24:27]
	v_mfma_f32_16x16x32_bf16 v[24:27], v[228:231], v[200:203], v[76:79]
	v_mfma_f32_16x16x32_bf16 v[104:107], v[232:235], v[204:207], v[24:27]
	v_mfma_f32_16x16x32_bf16 v[24:27], v[236:239], v[200:203], v[72:75]
	v_mfma_f32_16x16x32_bf16 v[100:103], v[240:243], v[204:207], v[24:27]
	v_mfma_f32_16x16x32_bf16 v[24:27], v[228:231], v[208:211], v[68:71]
	v_mfma_f32_16x16x32_bf16 v[96:99], v[232:235], v[212:215], v[24:27]
	v_mfma_f32_16x16x32_bf16 v[24:27], v[236:239], v[208:211], v[64:67]
	v_mfma_f32_16x16x32_bf16 v[136:139], v[232:235], v[28:31], v[92:95]
	v_mfma_f32_16x16x32_bf16 v[92:95], v[240:243], v[212:215], v[24:27]
	s_setprio 0
	s_barrier
	ds_read_b128 v[64:67], v184 offset:49152
	ds_read_b128 v[68:71], v184 offset:50176
	ds_read_b128 v[192:195], v185 offset:49152
	ds_read_b128 v[196:199], v185 offset:50176
	ds_read_b128 v[200:203], v186 offset:49152
	ds_read_b128 v[204:207], v186 offset:50176
	ds_read_b128 v[208:211], v187 offset:49152
	ds_read_b128 v[212:215], v187 offset:50176
	s_barrier
	s_setprio 1
	s_waitcnt lgkmcnt(7)
	v_mfma_f32_16x16x32_bf16 v[24:27], v[16:19], v[64:67], v[60:63]
	s_waitcnt lgkmcnt(6)
	v_mfma_f32_16x16x32_bf16 v[88:91], v[20:23], v[68:71], v[24:27]
	v_mfma_f32_16x16x32_bf16 v[24:27], v[164:167], v[64:67], v[56:59]
	v_mfma_f32_16x16x32_bf16 v[84:87], v[168:171], v[68:71], v[24:27]
	s_waitcnt lgkmcnt(5)
	v_mfma_f32_16x16x32_bf16 v[24:27], v[16:19], v[192:195], v[52:55]
	s_waitcnt lgkmcnt(4)
	v_mfma_f32_16x16x32_bf16 v[80:83], v[20:23], v[196:199], v[24:27]
	v_mfma_f32_16x16x32_bf16 v[24:27], v[164:167], v[192:195], v[48:51]
	v_mfma_f32_16x16x32_bf16 v[76:79], v[168:171], v[196:199], v[24:27]
	s_waitcnt lgkmcnt(3)
	v_mfma_f32_16x16x32_bf16 v[24:27], v[16:19], v[200:203], v[44:47]
	s_waitcnt lgkmcnt(1)
	v_mfma_f32_16x16x32_bf16 v[16:19], v[16:19], v[208:211], v[36:39]
	v_mfma_f32_16x16x32_bf16 v[28:31], v[20:23], v[204:207], v[24:27]
	v_mfma_f32_16x16x32_bf16 v[24:27], v[164:167], v[200:203], v[40:43]
	s_waitcnt lgkmcnt(0)
	v_mfma_f32_16x16x32_bf16 v[20:23], v[20:23], v[212:215], v[16:19]
	v_mfma_f32_16x16x32_bf16 v[16:19], v[164:167], v[208:211], v[32:35]
	v_mfma_f32_16x16x32_bf16 v[24:27], v[168:171], v[204:207], v[24:27]
	v_mfma_f32_16x16x32_bf16 v[16:19], v[168:171], v[212:215], v[16:19]
	s_setprio 0
	s_setprio 1
	v_mfma_f32_16x16x32_bf16 v[32:35], v[228:231], v[64:67], v[216:219]
	v_mfma_f32_16x16x32_bf16 v[72:75], v[232:235], v[68:71], v[32:35]
	v_mfma_f32_16x16x32_bf16 v[32:35], v[236:239], v[64:67], v[220:223]
	v_mfma_f32_16x16x32_bf16 v[68:71], v[240:243], v[68:71], v[32:35]
	v_mfma_f32_16x16x32_bf16 v[32:35], v[228:231], v[192:195], v[224:227]
	v_mfma_f32_16x16x32_bf16 v[40:43], v[232:235], v[196:199], v[32:35]
	v_mfma_f32_16x16x32_bf16 v[32:35], v[236:239], v[192:195], v[160:163]
	v_mfma_f32_16x16x32_bf16 v[12:15], v[228:231], v[200:203], v[12:15]
	v_mfma_f32_16x16x32_bf16 v[8:11], v[236:239], v[200:203], v[8:11]
	v_mfma_f32_16x16x32_bf16 v[4:7], v[228:231], v[208:211], v[4:7]
	v_mfma_f32_16x16x32_bf16 v[0:3], v[236:239], v[208:211], v[0:3]
	v_mfma_f32_16x16x32_bf16 v[36:39], v[240:243], v[196:199], v[32:35]
	v_mfma_f32_16x16x32_bf16 v[12:15], v[232:235], v[204:207], v[12:15]
	v_mfma_f32_16x16x32_bf16 v[8:11], v[240:243], v[204:207], v[8:11]
	v_mfma_f32_16x16x32_bf16 v[4:7], v[232:235], v[212:215], v[4:7]
	v_mfma_f32_16x16x32_bf16 v[0:3], v[240:243], v[212:215], v[0:3]
	s_setprio 0
	s_andn2_b64 vcc, exec, s[16:17]
	s_barrier
	s_cbranch_vccz .LBB0_574
	s_andn2_b64 vcc, exec, s[28:29]
	s_cbranch_vccz .LBB0_575

; #define LDA(dst, b, h)                                                                                               \
;   _Pragma("unroll") for (int m = 0; m < 4; ++m) _Pragma("unroll") for (int k = 0; k < 2; ++k) dst[m][k] =            \
;       *reinterpret_cast<const bf16x8*>(SA(b, h) + lds_byte(wr * 64 + m * 16 + fr, k * 32 + fq * 8))
; #define LDB(dst, b, h)                                                                                               \
;   _Pragma("unroll") for (int n = 0; n < 2; ++n) _Pragma("unroll") for (int k = 0; k < 2; ++k) dst[n][k] =            \
;       *reinterpret_cast<const bf16x8*>(SB(b, h) + lds_byte(wc * 32 + n * 16 + fr, k * 32 + fq * 8))
; #define WAIT_V(n) asm volatile("s_waitcnt vmcnt(" #n ")" ::: "memory")
; #define WAIT_L(n) asm volatile("s_waitcnt lgkmcnt(" #n ")" ::: "memory")
; #define BAR __builtin_amdgcn_s_barrier()
; #define SCHED __builtin_amdgcn_sched_barrier(0)
; template <int EPI>
; __device__ __forceinline__ void gemm_phase(const u16* __restrict__ A, const u16* __restrict__ Bt, const int K,
;                                            const int nN, char* shm, const EpiArgs& ea) {
;     ...
;       LDB(B0, 0, 0); SCHED; LDA(At, 0, 0); STAGE(SA(1, 1), rA, brow + HALF, t + 1);
;       WAIT_V(10); WAIT_L(8); BAR; WAIT_L(0); MMA(0, 0, At, B0); BAR; SCHED;
;       LDB(B1, 0, 1); STAGE(SB(0, 0), rB, bcol, t + 2);
;       WAIT_V(10); BAR; WAIT_L(0); MMA(0, 1, At, B1); BAR;
;       LDA(At, 0, 1); STAGE(SA(0, 0), rA, brow, t + 2);
;       BAR; WAIT_L(0); MMA(1, 0, At, B0); BAR; SCHED;
.LBB0_631:
	ds_read_b128 v[130:133], v141
	ds_read_b128 v[134:137], v141 offset:1024
	ds_read_b128 v[150:153], v141 offset:2048
	ds_read_b128 v[154:157], v141 offset:3072
	s_add_i32 s54, s48, s53
	s_mov_b32 m0, s41
	s_add_i32 s6, s54, 0x4000
	ds_read_b128 v[158:161], v142
	ds_read_b128 v[162:165], v142 offset:1024
	ds_read_b128 v[166:169], v143
	ds_read_b128 v[170:173], v143 offset:1024
	ds_read_b128 v[176:179], v144
	ds_read_b128 v[180:183], v144 offset:1024
	ds_read_b128 v[184:187], v145
	ds_read_b128 v[188:191], v145 offset:1024
	buffer_load_dwordx4 v138, s[0:3], s6 offen lds
	s_add_i32 s6, s54, 0x6000
	s_mov_b32 m0, s42
	s_nop 0
	buffer_load_dwordx4 v138, s[0:3], s6 offen lds
	s_waitcnt vmcnt(10)
	s_waitcnt lgkmcnt(8)
	s_barrier
	s_setprio 1
	s_waitcnt lgkmcnt(7)
	v_mfma_f32_16x16x32_bf16 v[124:127], v[130:133], v[158:161], v[124:127]
	v_mfma_f32_16x16x32_bf16 v[120:123], v[150:153], v[158:161], v[120:123]
	s_waitcnt lgkmcnt(5)
	v_mfma_f32_16x16x32_bf16 v[116:119], v[130:133], v[166:169], v[116:119]
	v_mfma_f32_16x16x32_bf16 v[112:115], v[150:153], v[166:169], v[112:115]
	s_waitcnt lgkmcnt(3)
	v_mfma_f32_16x16x32_bf16 v[108:111], v[130:133], v[176:179], v[108:111]
	v_mfma_f32_16x16x32_bf16 v[104:107], v[150:153], v[176:179], v[104:107]
	s_waitcnt lgkmcnt(1)
	v_mfma_f32_16x16x32_bf16 v[100:103], v[130:133], v[184:187], v[100:103]
	v_mfma_f32_16x16x32_bf16 v[96:99], v[150:153], v[184:187], v[96:99]
	v_mfma_f32_16x16x32_bf16 v[124:127], v[134:137], v[162:165], v[124:127]
	v_mfma_f32_16x16x32_bf16 v[120:123], v[154:157], v[162:165], v[120:123]
	v_mfma_f32_16x16x32_bf16 v[116:119], v[134:137], v[170:173], v[116:119]
	v_mfma_f32_16x16x32_bf16 v[112:115], v[154:157], v[170:173], v[112:115]
	v_mfma_f32_16x16x32_bf16 v[108:111], v[134:137], v[180:183], v[108:111]
	v_mfma_f32_16x16x32_bf16 v[104:107], v[154:157], v[180:183], v[104:107]
	s_waitcnt lgkmcnt(0)
	v_mfma_f32_16x16x32_bf16 v[100:103], v[134:137], v[188:191], v[100:103]
	v_mfma_f32_16x16x32_bf16 v[96:99], v[154:157], v[188:191], v[96:99]
	s_setprio 0
	s_barrier
	s_add_i32 s55, s51, s53
	s_mov_b32 m0, s19
	s_add_i32 s56, s55, 0x8000
	s_mov_b32 s6, s2
	s_mov_b32 s7, s3
	ds_read_b128 v[192:195], v146
	ds_read_b128 v[196:199], v146 offset:1024
	ds_read_b128 v[200:203], v146 offset:2048
	ds_read_b128 v[204:207], v146 offset:3072
	buffer_load_dwordx4 v138, s[4:7], s56 offen lds
	s_add_i32 s56, s55, 0xa000
	s_mov_b32 m0, s26
	s_nop 0
	buffer_load_dwordx4 v138, s[4:7], s56 offen lds
	s_waitcnt vmcnt(10)
	s_barrier
	s_setprio 1
	s_waitcnt lgkmcnt(3)
	v_mfma_f32_16x16x32_bf16 v[92:95], v[192:195], v[158:161], v[92:95]
	s_waitcnt lgkmcnt(1)
	v_mfma_f32_16x16x32_bf16 v[88:91], v[200:203], v[158:161], v[88:91]
	v_mfma_f32_16x16x32_bf16 v[84:87], v[192:195], v[166:169], v[84:87]
	v_mfma_f32_16x16x32_bf16 v[80:83], v[200:203], v[166:169], v[80:83]
	v_mfma_f32_16x16x32_bf16 v[76:79], v[192:195], v[176:179], v[76:79]
	v_mfma_f32_16x16x32_bf16 v[72:75], v[200:203], v[176:179], v[72:75]
	v_mfma_f32_16x16x32_bf16 v[68:71], v[192:195], v[184:187], v[68:71]
	v_mfma_f32_16x16x32_bf16 v[64:67], v[200:203], v[184:187], v[64:67]
	v_mfma_f32_16x16x32_bf16 v[92:95], v[196:199], v[162:165], v[92:95]
	s_waitcnt lgkmcnt(0)
	v_mfma_f32_16x16x32_bf16 v[88:91], v[204:207], v[162:165], v[88:91]
	v_mfma_f32_16x16x32_bf16 v[84:87], v[196:199], v[170:173], v[84:87]
	v_mfma_f32_16x16x32_bf16 v[80:83], v[204:207], v[170:173], v[80:83]
	v_mfma_f32_16x16x32_bf16 v[76:79], v[196:199], v[180:183], v[76:79]
	v_mfma_f32_16x16x32_bf16 v[72:75], v[204:207], v[180:183], v[72:75]
	v_mfma_f32_16x16x32_bf16 v[68:71], v[196:199], v[188:191], v[68:71]
	v_mfma_f32_16x16x32_bf16 v[64:67], v[204:207], v[188:191], v[64:67]
	s_setprio 0
	s_add_i32 s56, s50, s53
	s_mov_b32 m0, s27
	s_add_i32 s57, s56, 0x8000
	s_barrier
	ds_read_b128 v[158:161], v142 offset:16384
	ds_read_b128 v[162:165], v142 offset:17408
	ds_read_b128 v[166:169], v143 offset:16384
	ds_read_b128 v[170:173], v143 offset:17408
	ds_read_b128 v[176:179], v144 offset:16384
	ds_read_b128 v[180:183], v144 offset:17408
	ds_read_b128 v[184:187], v145 offset:16384
	ds_read_b128 v[188:191], v145 offset:17408
	buffer_load_dwordx4 v138, s[0:3], s57 offen lds
	s_add_i32 s57, s56, 0xa000
	s_mov_b32 m0, s28
	s_nop 0
	buffer_load_dwordx4 v138, s[0:3], s57 offen lds
	s_barrier
	s_setprio 1
	s_waitcnt lgkmcnt(7)
	v_mfma_f32_16x16x32_bf16 v[60:63], v[130:133], v[158:161], v[60:63]
	v_mfma_f32_16x16x32_bf16 v[56:59], v[150:153], v[158:161], v[56:59]
	s_waitcnt lgkmcnt(5)
	v_mfma_f32_16x16x32_bf16 v[52:55], v[130:133], v[166:169], v[52:55]
	v_mfma_f32_16x16x32_bf16 v[48:51], v[150:153], v[166:169], v[48:51]
	s_waitcnt lgkmcnt(3)
	v_mfma_f32_16x16x32_bf16 v[44:47], v[130:133], v[176:179], v[44:47]
	v_mfma_f32_16x16x32_bf16 v[40:43], v[150:153], v[176:179], v[40:43]
	s_waitcnt lgkmcnt(1)
	v_mfma_f32_16x16x32_bf16 v[36:39], v[130:133], v[184:187], v[36:39]
	v_mfma_f32_16x16x32_bf16 v[32:35], v[150:153], v[184:187], v[32:35]
	v_mfma_f32_16x16x32_bf16 v[60:63], v[134:137], v[162:165], v[60:63]
	v_mfma_f32_16x16x32_bf16 v[56:59], v[154:157], v[162:165], v[56:59]
	v_mfma_f32_16x16x32_bf16 v[52:55], v[134:137], v[170:173], v[52:55]
	v_mfma_f32_16x16x32_bf16 v[48:51], v[154:157], v[170:173], v[48:51]
	v_mfma_f32_16x16x32_bf16 v[44:47], v[134:137], v[180:183], v[44:47]
	v_mfma_f32_16x16x32_bf16 v[40:43], v[154:157], v[180:183], v[40:43]
	s_waitcnt lgkmcnt(0)
	v_mfma_f32_16x16x32_bf16 v[36:39], v[134:137], v[188:191], v[36:39]
	v_mfma_f32_16x16x32_bf16 v[32:35], v[154:157], v[188:191], v[32:35]
	s_setprio 0
	s_barrier
; #define LDA(dst, b, h)                                                                                               \
;   _Pragma("unroll") for (int m = 0; m < 4; ++m) _Pragma("unroll") for (int k = 0; k < 2; ++k) dst[m][k] =            \
;       *reinterpret_cast<const bf16x8*>(SA(b, h) + lds_byte(wr * 64 + m * 16 + fr, k * 32 + fq * 8))
; #define LDB(dst, b, h)                                                                                               \
;   _Pragma("unroll") for (int n = 0; n < 2; ++n) _Pragma("unroll") for (int k = 0; k < 2; ++k) dst[n][k] =            \
;       *reinterpret_cast<const bf16x8*>(SB(b, h) + lds_byte(wc * 32 + n * 16 + fr, k * 32 + fq * 8))
; #define WAIT_V(n) asm volatile("s_waitcnt vmcnt(" #n ")" ::: "memory")
; #define WAIT_L(n) asm volatile("s_waitcnt lgkmcnt(" #n ")" ::: "memory")
; #define BAR __builtin_amdgcn_s_barrier()
; #define SCHED __builtin_amdgcn_sched_barrier(0)
; template <int EPI>
; __device__ __forceinline__ void gemm_phase(const u16* __restrict__ A, const u16* __restrict__ Bt, const int K,
;                                            const int nN, char* shm, const EpiArgs& ea) {
;     ...
;       STAGE(SB(0, 1), rB, bcol + HALF, t + 2);
;       WAIT_V(10); BAR; MMA(1, 1, At, B1); BAR;
;       LDB(B0, 1, 0); SCHED; LDA(At, 1, 0); STAGE(SA(0, 1), rA, brow + HALF, t + 2);
;       WAIT_V(10); WAIT_L(8); BAR; WAIT_L(0); MMA(0, 0, At, B0); BAR; SCHED;
;       LDB(B1, 1, 1); STAGE(SB(1, 0), rB, bcol, t + 3);
;       WAIT_V(10); BAR; WAIT_L(0); MMA(0, 1, At, B1); BAR;
;       LDA(At, 1, 1); STAGE(SA(1, 0), rA, brow, t + 3);
;       BAR; WAIT_L(0); MMA(1, 0, At, B0); BAR; SCHED;
	s_add_i32 s57, s49, s53
	s_mov_b32 m0, s29
	s_add_i32 s58, s57, 0x8000
	buffer_load_dwordx4 v138, s[4:7], s58 offen lds
	s_add_i32 s58, s57, 0xa000
	s_mov_b32 m0, s30
	s_nop 0
	buffer_load_dwordx4 v138, s[4:7], s58 offen lds
	s_waitcnt vmcnt(10)
	s_barrier
	s_setprio 1
	v_mfma_f32_16x16x32_bf16 v[28:31], v[192:195], v[158:161], v[28:31]
	v_mfma_f32_16x16x32_bf16 v[24:27], v[200:203], v[158:161], v[24:27]
	v_mfma_f32_16x16x32_bf16 v[20:23], v[192:195], v[166:169], v[20:23]
	v_mfma_f32_16x16x32_bf16 v[16:19], v[200:203], v[166:169], v[16:19]
	v_mfma_f32_16x16x32_bf16 v[12:15], v[192:195], v[176:179], v[12:15]
	v_mfma_f32_16x16x32_bf16 v[8:11], v[200:203], v[176:179], v[8:11]
	v_mfma_f32_16x16x32_bf16 v[4:7], v[192:195], v[184:187], v[4:7]
	v_mfma_f32_16x16x32_bf16 v[0:3], v[200:203], v[184:187], v[0:3]
	v_mfma_f32_16x16x32_bf16 v[28:31], v[196:199], v[162:165], v[28:31]
	v_mfma_f32_16x16x32_bf16 v[24:27], v[204:207], v[162:165], v[24:27]
	v_mfma_f32_16x16x32_bf16 v[20:23], v[196:199], v[170:173], v[20:23]
	v_mfma_f32_16x16x32_bf16 v[16:19], v[204:207], v[170:173], v[16:19]
	v_mfma_f32_16x16x32_bf16 v[12:15], v[196:199], v[180:183], v[12:15]
	v_mfma_f32_16x16x32_bf16 v[8:11], v[204:207], v[180:183], v[8:11]
	v_mfma_f32_16x16x32_bf16 v[4:7], v[196:199], v[188:191], v[4:7]
	v_mfma_f32_16x16x32_bf16 v[0:3], v[204:207], v[188:191], v[0:3]
	s_setprio 0
	s_barrier
	ds_read_b128 v[130:133], v147
	ds_read_b128 v[134:137], v147 offset:1024
	ds_read_b128 v[150:153], v147 offset:2048
	ds_read_b128 v[154:157], v147 offset:3072
	s_mov_b32 m0, s31
	s_add_i32 s58, s54, 0x8000
	ds_read_b128 v[158:161], v142 offset:32768
	ds_read_b128 v[162:165], v142 offset:33792
	ds_read_b128 v[166:169], v143 offset:32768
	ds_read_b128 v[170:173], v143 offset:33792
	ds_read_b128 v[176:179], v144 offset:32768
	ds_read_b128 v[180:183], v144 offset:33792
	ds_read_b128 v[184:187], v145 offset:32768
	ds_read_b128 v[188:191], v145 offset:33792
	buffer_load_dwordx4 v138, s[0:3], s58 offen lds
	s_add_i32 s54, s54, 0xa000
	s_mov_b32 m0, s34
	s_nop 0
	buffer_load_dwordx4 v138, s[0:3], s54 offen lds
	s_waitcnt vmcnt(10)
	s_waitcnt lgkmcnt(8)
	s_barrier
	s_setprio 1
	s_waitcnt lgkmcnt(7)
	v_mfma_f32_16x16x32_bf16 v[124:127], v[130:133], v[158:161], v[124:127]
	v_mfma_f32_16x16x32_bf16 v[120:123], v[150:153], v[158:161], v[120:123]
	s_waitcnt lgkmcnt(5)
	v_mfma_f32_16x16x32_bf16 v[116:119], v[130:133], v[166:169], v[116:119]
	v_mfma_f32_16x16x32_bf16 v[112:115], v[150:153], v[166:169], v[112:115]
	s_waitcnt lgkmcnt(3)
	v_mfma_f32_16x16x32_bf16 v[108:111], v[130:133], v[176:179], v[108:111]
	v_mfma_f32_16x16x32_bf16 v[104:107], v[150:153], v[176:179], v[104:107]
	s_waitcnt lgkmcnt(1)
	v_mfma_f32_16x16x32_bf16 v[100:103], v[130:133], v[184:187], v[100:103]
	v_mfma_f32_16x16x32_bf16 v[96:99], v[150:153], v[184:187], v[96:99]
	v_mfma_f32_16x16x32_bf16 v[124:127], v[134:137], v[162:165], v[124:127]
	v_mfma_f32_16x16x32_bf16 v[120:123], v[154:157], v[162:165], v[120:123]
	v_mfma_f32_16x16x32_bf16 v[116:119], v[134:137], v[170:173], v[116:119]
	v_mfma_f32_16x16x32_bf16 v[112:115], v[154:157], v[170:173], v[112:115]
	v_mfma_f32_16x16x32_bf16 v[108:111], v[134:137], v[180:183], v[108:111]
	v_mfma_f32_16x16x32_bf16 v[104:107], v[154:157], v[180:183], v[104:107]
	s_waitcnt lgkmcnt(0)
	v_mfma_f32_16x16x32_bf16 v[100:103], v[134:137], v[188:191], v[100:103]
	v_mfma_f32_16x16x32_bf16 v[96:99], v[154:157], v[188:191], v[96:99]
	s_setprio 0
	s_barrier
	s_mov_b32 m0, s35
	s_add_i32 s54, s55, 0xc000
	ds_read_b128 v[192:195], v148
	ds_read_b128 v[196:199], v148 offset:1024
	ds_read_b128 v[200:203], v148 offset:2048
	ds_read_b128 v[204:207], v148 offset:3072
	buffer_load_dwordx4 v138, s[4:7], s54 offen lds
	s_add_i32 s55, s55, 0xe000
	s_mov_b32 m0, s36
	s_nop 0
	buffer_load_dwordx4 v138, s[4:7], s55 offen lds
	s_waitcnt vmcnt(10)
	s_barrier
	s_setprio 1
	s_waitcnt lgkmcnt(3)
	v_mfma_f32_16x16x32_bf16 v[92:95], v[192:195], v[158:161], v[92:95]
	s_waitcnt lgkmcnt(1)
	v_mfma_f32_16x16x32_bf16 v[88:91], v[200:203], v[158:161], v[88:91]
	v_mfma_f32_16x16x32_bf16 v[84:87], v[192:195], v[166:169], v[84:87]
	v_mfma_f32_16x16x32_bf16 v[80:83], v[200:203], v[166:169], v[80:83]
	v_mfma_f32_16x16x32_bf16 v[76:79], v[192:195], v[176:179], v[76:79]
	v_mfma_f32_16x16x32_bf16 v[72:75], v[200:203], v[176:179], v[72:75]
	v_mfma_f32_16x16x32_bf16 v[68:71], v[192:195], v[184:187], v[68:71]
	v_mfma_f32_16x16x32_bf16 v[64:67], v[200:203], v[184:187], v[64:67]
	v_mfma_f32_16x16x32_bf16 v[92:95], v[196:199], v[162:165], v[92:95]
	s_waitcnt lgkmcnt(0)
	v_mfma_f32_16x16x32_bf16 v[88:91], v[204:207], v[162:165], v[88:91]
	v_mfma_f32_16x16x32_bf16 v[84:87], v[196:199], v[170:173], v[84:87]
	v_mfma_f32_16x16x32_bf16 v[80:83], v[204:207], v[170:173], v[80:83]
	v_mfma_f32_16x16x32_bf16 v[76:79], v[196:199], v[180:183], v[76:79]
	v_mfma_f32_16x16x32_bf16 v[72:75], v[204:207], v[180:183], v[72:75]
	v_mfma_f32_16x16x32_bf16 v[68:71], v[196:199], v[188:191], v[68:71]
	v_mfma_f32_16x16x32_bf16 v[64:67], v[204:207], v[188:191], v[64:67]
	s_setprio 0
	s_mov_b32 m0, s37
	s_add_i32 s54, s56, 0xc000
	s_barrier
	ds_read_b128 v[158:161], v142 offset:49152
	ds_read_b128 v[162:165], v142 offset:50176
	ds_read_b128 v[166:169], v143 offset:49152
	ds_read_b128 v[170:173], v143 offset:50176
	ds_read_b128 v[176:179], v144 offset:49152
	ds_read_b128 v[180:183], v144 offset:50176
	ds_read_b128 v[184:187], v145 offset:49152
	ds_read_b128 v[188:191], v145 offset:50176
	buffer_load_dwordx4 v138, s[0:3], s54 offen lds
	s_add_i32 s56, s56, 0xe000
	s_mov_b32 m0, s38
	s_nop 0
	buffer_load_dwordx4 v138, s[0:3], s56 offen lds
	s_barrier
; #define LDA(dst, b, h)                                                                                               \
;   _Pragma("unroll") for (int m = 0; m < 4; ++m) _Pragma("unroll") for (int k = 0; k < 2; ++k) dst[m][k] =            \
;       *reinterpret_cast<const bf16x8*>(SA(b, h) + lds_byte(wr * 64 + m * 16 + fr, k * 32 + fq * 8))
; #define LDB(dst, b, h)                                                                                               \
;   _Pragma("unroll") for (int n = 0; n < 2; ++n) _Pragma("unroll") for (int k = 0; k < 2; ++k) dst[n][k] =            \
;       *reinterpret_cast<const bf16x8*>(SB(b, h) + lds_byte(wc * 32 + n * 16 + fr, k * 32 + fq * 8))
; #define WAIT_V(n) asm volatile("s_waitcnt vmcnt(" #n ")" ::: "memory")
; #define WAIT_L(n) asm volatile("s_waitcnt lgkmcnt(" #n ")" ::: "memory")
; #define BAR __builtin_amdgcn_s_barrier()
; #define SCHED __builtin_amdgcn_sched_barrier(0)
; template <int EPI>
; __device__ __forceinline__ void gemm_phase(const u16* __restrict__ A, const u16* __restrict__ Bt, const int K,
;                                            const int nN, char* shm, const EpiArgs& ea) {
;     ...
;       BAR; WAIT_L(0); MMA(1, 0, At, B0); BAR; SCHED;
;       STAGE(SB(1, 1), rB, bcol + HALF, t + 3);
;       WAIT_V(10); BAR; MMA(1, 1, At, B1); BAR;
;     }
;     float eC = 0.f, eB = 0.f;
;     float2 eS = make_float2(0.f, 0.f);
;     if (EPI == EPI_IN || EPI == EPI_SWIGLU_LN) {
;       if (wr == 0) {
;         eC = ea.c1[bcol + tid];
;         eS = *(const float2*)(ea.st_in + (size_t)(brow + tid) * 2);
;       } else {
;         eC = ea.c2[bcol + tid - 256];
;         if (EPI == EPI_IN) eB = ea.bias[bcol + tid - 256];
;       }
;     }
;     {
;       LDB(B0, 0, 0); LDA(At, 0, 0); STAGE(SA(1, 1), rA, brow + HALF, nt - 1);
;       WAIT_V(10); BAR; WAIT_L(0); MMA(0, 0, At, B0); BAR;
;       LDB(B1, 0, 1); WAIT_V(8); BAR; WAIT_L(0); MMA(0, 1, At, B1); BAR;
;       LDA(At, 0, 1); WAIT_V(4); BAR; WAIT_L(0); MMA(1, 0, At, B0); MMA(1, 1, At, B1); BAR;
	s_setprio 1
	s_waitcnt lgkmcnt(7)
	v_mfma_f32_16x16x32_bf16 v[60:63], v[130:133], v[158:161], v[60:63]
	v_mfma_f32_16x16x32_bf16 v[56:59], v[150:153], v[158:161], v[56:59]
	s_waitcnt lgkmcnt(5)
	v_mfma_f32_16x16x32_bf16 v[52:55], v[130:133], v[166:169], v[52:55]
	v_mfma_f32_16x16x32_bf16 v[48:51], v[150:153], v[166:169], v[48:51]
	s_waitcnt lgkmcnt(3)
	v_mfma_f32_16x16x32_bf16 v[44:47], v[130:133], v[176:179], v[44:47]
	v_mfma_f32_16x16x32_bf16 v[40:43], v[150:153], v[176:179], v[40:43]
	s_waitcnt lgkmcnt(1)
	v_mfma_f32_16x16x32_bf16 v[36:39], v[130:133], v[184:187], v[36:39]
	v_mfma_f32_16x16x32_bf16 v[32:35], v[150:153], v[184:187], v[32:35]
	v_mfma_f32_16x16x32_bf16 v[60:63], v[134:137], v[162:165], v[60:63]
	v_mfma_f32_16x16x32_bf16 v[56:59], v[154:157], v[162:165], v[56:59]
	v_mfma_f32_16x16x32_bf16 v[52:55], v[134:137], v[170:173], v[52:55]
	v_mfma_f32_16x16x32_bf16 v[48:51], v[154:157], v[170:173], v[48:51]
	v_mfma_f32_16x16x32_bf16 v[44:47], v[134:137], v[180:183], v[44:47]
	v_mfma_f32_16x16x32_bf16 v[40:43], v[154:157], v[180:183], v[40:43]
	s_waitcnt lgkmcnt(0)
	v_mfma_f32_16x16x32_bf16 v[36:39], v[134:137], v[188:191], v[36:39]
	v_mfma_f32_16x16x32_bf16 v[32:35], v[154:157], v[188:191], v[32:35]
	s_setprio 0
	s_barrier
	s_mov_b32 m0, s39
	s_add_i32 s54, s57, 0xc000
	buffer_load_dwordx4 v138, s[4:7], s54 offen lds
	s_add_i32 s57, s57, 0xe000
	s_mov_b32 m0, s40
	s_nop 0
	buffer_load_dwordx4 v138, s[4:7], s57 offen lds
	s_waitcnt vmcnt(10)
	s_barrier
	s_setprio 1
	v_mfma_f32_16x16x32_bf16 v[28:31], v[192:195], v[158:161], v[28:31]
	v_mfma_f32_16x16x32_bf16 v[24:27], v[200:203], v[158:161], v[24:27]
	v_mfma_f32_16x16x32_bf16 v[20:23], v[192:195], v[166:169], v[20:23]
	v_mfma_f32_16x16x32_bf16 v[16:19], v[200:203], v[166:169], v[16:19]
	v_mfma_f32_16x16x32_bf16 v[12:15], v[192:195], v[176:179], v[12:15]
	v_mfma_f32_16x16x32_bf16 v[8:11], v[200:203], v[176:179], v[8:11]
	v_mfma_f32_16x16x32_bf16 v[4:7], v[192:195], v[184:187], v[4:7]
	v_mfma_f32_16x16x32_bf16 v[0:3], v[200:203], v[184:187], v[0:3]
	v_mfma_f32_16x16x32_bf16 v[28:31], v[196:199], v[162:165], v[28:31]
	v_mfma_f32_16x16x32_bf16 v[24:27], v[204:207], v[162:165], v[24:27]
	v_mfma_f32_16x16x32_bf16 v[20:23], v[196:199], v[170:173], v[20:23]
	v_mfma_f32_16x16x32_bf16 v[16:19], v[204:207], v[170:173], v[16:19]
	v_mfma_f32_16x16x32_bf16 v[12:15], v[196:199], v[180:183], v[12:15]
	v_mfma_f32_16x16x32_bf16 v[8:11], v[204:207], v[180:183], v[8:11]
	v_mfma_f32_16x16x32_bf16 v[4:7], v[196:199], v[188:191], v[4:7]
	v_mfma_f32_16x16x32_bf16 v[0:3], v[204:207], v[188:191], v[0:3]
	s_setprio 0
	s_add_i32 s52, s52, 2
	s_add_i32 s53, s53, 0x8000
	s_cmpk_lt_u32 s52, 0x54
	s_barrier
	s_cbranch_scc1 .LBB0_631
	s_mov_b32 m0, s41
	s_add_i32 s6, s48, 0x15c000
	ds_read_b128 v[130:133], v141
	ds_read_b128 v[134:137], v141 offset:1024
	ds_read_b128 v[150:153], v141 offset:2048
	ds_read_b128 v[154:157], v141 offset:3072
	ds_read_b128 v[158:161], v142
	ds_read_b128 v[162:165], v142 offset:1024
	ds_read_b128 v[166:169], v143
	ds_read_b128 v[170:173], v143 offset:1024
	ds_read_b128 v[176:179], v144
	ds_read_b128 v[180:183], v144 offset:1024
	ds_read_b128 v[184:187], v145
	ds_read_b128 v[188:191], v145 offset:1024
	buffer_load_dwordx4 v138, s[0:3], s6 offen lds
	s_add_i32 s48, s48, 0x15e000
	s_mov_b32 m0, s42
	s_nop 0
	buffer_load_dwordx4 v138, s[0:3], s48 offen lds
	s_waitcnt vmcnt(10)
	s_barrier
	s_setprio 1
	s_waitcnt lgkmcnt(7)
	v_mfma_f32_16x16x32_bf16 v[124:127], v[130:133], v[158:161], v[124:127]
	v_mfma_f32_16x16x32_bf16 v[120:123], v[150:153], v[158:161], v[120:123]
	s_waitcnt lgkmcnt(5)
	v_mfma_f32_16x16x32_bf16 v[116:119], v[130:133], v[166:169], v[116:119]
	v_mfma_f32_16x16x32_bf16 v[112:115], v[150:153], v[166:169], v[112:115]
	s_waitcnt lgkmcnt(1)
	v_mfma_f32_16x16x32_bf16 v[100:103], v[130:133], v[184:187], v[100:103]
	v_mfma_f32_16x16x32_bf16 v[96:99], v[150:153], v[184:187], v[96:99]
	v_mfma_f32_16x16x32_bf16 v[124:127], v[134:137], v[162:165], v[124:127]
	v_mfma_f32_16x16x32_bf16 v[120:123], v[154:157], v[162:165], v[120:123]
	v_mfma_f32_16x16x32_bf16 v[116:119], v[134:137], v[170:173], v[116:119]
	v_mfma_f32_16x16x32_bf16 v[112:115], v[154:157], v[170:173], v[112:115]
	v_mfma_f32_16x16x32_bf16 v[108:111], v[130:133], v[176:179], v[108:111]
	v_mfma_f32_16x16x32_bf16 v[104:107], v[150:153], v[176:179], v[104:107]
	s_waitcnt lgkmcnt(0)
	v_mfma_f32_16x16x32_bf16 v[100:103], v[134:137], v[188:191], v[100:103]
	v_mfma_f32_16x16x32_bf16 v[96:99], v[154:157], v[188:191], v[96:99]
	v_mfma_f32_16x16x32_bf16 v[192:195], v[134:137], v[180:183], v[108:111]
	v_mfma_f32_16x16x32_bf16 v[196:199], v[154:157], v[180:183], v[104:107]
	s_setprio 0
	s_barrier
	s_nop 0
	ds_read_b128 v[104:107], v146
	ds_read_b128 v[108:111], v146 offset:1024
	ds_read_b128 v[200:203], v146 offset:2048
	ds_read_b128 v[204:207], v146 offset:3072
	s_waitcnt vmcnt(8)
	s_barrier
	s_setprio 1
	s_waitcnt lgkmcnt(3)
	v_mfma_f32_16x16x32_bf16 v[84:87], v[104:107], v[166:169], v[84:87]
	s_waitcnt lgkmcnt(1)
	v_mfma_f32_16x16x32_bf16 v[80:83], v[200:203], v[166:169], v[80:83]
	v_mfma_f32_16x16x32_bf16 v[68:71], v[104:107], v[184:187], v[68:71]
	v_mfma_f32_16x16x32_bf16 v[64:67], v[200:203], v[184:187], v[64:67]
	v_mfma_f32_16x16x32_bf16 v[92:95], v[104:107], v[158:161], v[92:95]
	v_mfma_f32_16x16x32_bf16 v[88:91], v[200:203], v[158:161], v[88:91]
	v_mfma_f32_16x16x32_bf16 v[84:87], v[108:111], v[170:173], v[84:87]
	s_waitcnt lgkmcnt(0)
	v_mfma_f32_16x16x32_bf16 v[80:83], v[204:207], v[170:173], v[80:83]
	v_mfma_f32_16x16x32_bf16 v[76:79], v[104:107], v[176:179], v[76:79]
	v_mfma_f32_16x16x32_bf16 v[72:75], v[200:203], v[176:179], v[72:75]
	v_mfma_f32_16x16x32_bf16 v[68:71], v[108:111], v[188:191], v[68:71]
	v_mfma_f32_16x16x32_bf16 v[64:67], v[204:207], v[188:191], v[64:67]
	v_mfma_f32_16x16x32_bf16 v[208:211], v[108:111], v[162:165], v[92:95]
	v_mfma_f32_16x16x32_bf16 v[158:161], v[204:207], v[162:165], v[88:91]
	v_mfma_f32_16x16x32_bf16 v[162:165], v[108:111], v[180:183], v[76:79]
	v_mfma_f32_16x16x32_bf16 v[166:169], v[204:207], v[180:183], v[72:75]
	s_setprio 0
	s_barrier
; #define LDA(dst, b, h)                                                                                               \
;   _Pragma("unroll") for (int m = 0; m < 4; ++m) _Pragma("unroll") for (int k = 0; k < 2; ++k) dst[m][k] =            \
;       *reinterpret_cast<const bf16x8*>(SA(b, h) + lds_byte(wr * 64 + m * 16 + fr, k * 32 + fq * 8))
; #define LDB(dst, b, h)                                                                                               \
;   _Pragma("unroll") for (int n = 0; n < 2; ++n) _Pragma("unroll") for (int k = 0; k < 2; ++k) dst[n][k] =            \
;       *reinterpret_cast<const bf16x8*>(SB(b, h) + lds_byte(wc * 32 + n * 16 + fr, k * 32 + fq * 8))
; #define WAIT_V(n) asm volatile("s_waitcnt vmcnt(" #n ")" ::: "memory")
; #define WAIT_L(n) asm volatile("s_waitcnt lgkmcnt(" #n ")" ::: "memory")
; #define BAR __builtin_amdgcn_s_barrier()
; template <int EPI>
; __device__ __forceinline__ void gemm_phase(const u16* __restrict__ A, const u16* __restrict__ Bt, const int K,
;                                            const int nN, char* shm, const EpiArgs& ea) {
;     ...
;       LDA(At, 0, 1); WAIT_V(4); BAR; WAIT_L(0); MMA(1, 0, At, B0); MMA(1, 1, At, B1); BAR;
;     }
;     {
;       LDB(B0, 1, 0); LDA(At, 1, 0); WAIT_V(2); BAR; WAIT_L(0); MMA(0, 0, At, B0); BAR;
	s_nop 0
	ds_read_b128 v[72:75], v142 offset:16384
	ds_read_b128 v[76:79], v142 offset:17408
	ds_read_b128 v[88:91], v143 offset:16384
	ds_read_b128 v[92:95], v143 offset:17408
	ds_read_b128 v[170:173], v144 offset:16384
	ds_read_b128 v[176:179], v144 offset:17408
	ds_read_b128 v[180:183], v145 offset:16384
	ds_read_b128 v[184:187], v145 offset:17408
	s_waitcnt vmcnt(4)
	s_barrier
	s_setprio 1
	s_waitcnt lgkmcnt(7)
	v_mfma_f32_16x16x32_bf16 v[60:63], v[130:133], v[72:75], v[60:63]
	v_mfma_f32_16x16x32_bf16 v[56:59], v[150:153], v[72:75], v[56:59]
	s_waitcnt lgkmcnt(5)
	v_mfma_f32_16x16x32_bf16 v[52:55], v[130:133], v[88:91], v[52:55]
	v_mfma_f32_16x16x32_bf16 v[48:51], v[150:153], v[88:91], v[48:51]
	s_waitcnt lgkmcnt(1)
	v_mfma_f32_16x16x32_bf16 v[36:39], v[130:133], v[180:183], v[36:39]
	v_mfma_f32_16x16x32_bf16 v[32:35], v[150:153], v[180:183], v[32:35]
	v_mfma_f32_16x16x32_bf16 v[60:63], v[134:137], v[76:79], v[60:63]
	v_mfma_f32_16x16x32_bf16 v[56:59], v[154:157], v[76:79], v[56:59]
	v_mfma_f32_16x16x32_bf16 v[52:55], v[134:137], v[92:95], v[52:55]
	v_mfma_f32_16x16x32_bf16 v[48:51], v[154:157], v[92:95], v[48:51]
	v_mfma_f32_16x16x32_bf16 v[44:47], v[130:133], v[170:173], v[44:47]
	v_mfma_f32_16x16x32_bf16 v[40:43], v[150:153], v[170:173], v[40:43]
	s_waitcnt lgkmcnt(0)
	v_mfma_f32_16x16x32_bf16 v[36:39], v[134:137], v[184:187], v[36:39]
	v_mfma_f32_16x16x32_bf16 v[32:35], v[154:157], v[184:187], v[32:35]
	v_mfma_f32_16x16x32_bf16 v[188:191], v[134:137], v[176:179], v[44:47]
	v_mfma_f32_16x16x32_bf16 v[212:215], v[154:157], v[176:179], v[40:43]
	s_setprio 0
	s_setprio 1
	v_mfma_f32_16x16x32_bf16 v[20:23], v[104:107], v[88:91], v[20:23]
	v_mfma_f32_16x16x32_bf16 v[16:19], v[200:203], v[88:91], v[16:19]
	v_mfma_f32_16x16x32_bf16 v[4:7], v[104:107], v[180:183], v[4:7]
	v_mfma_f32_16x16x32_bf16 v[0:3], v[200:203], v[180:183], v[0:3]
	v_mfma_f32_16x16x32_bf16 v[28:31], v[104:107], v[72:75], v[28:31]
	v_mfma_f32_16x16x32_bf16 v[24:27], v[200:203], v[72:75], v[24:27]
	v_mfma_f32_16x16x32_bf16 v[20:23], v[108:111], v[92:95], v[20:23]
	v_mfma_f32_16x16x32_bf16 v[16:19], v[204:207], v[92:95], v[16:19]
	v_mfma_f32_16x16x32_bf16 v[12:15], v[104:107], v[170:173], v[12:15]
	v_mfma_f32_16x16x32_bf16 v[8:11], v[200:203], v[170:173], v[8:11]
	v_mfma_f32_16x16x32_bf16 v[4:7], v[108:111], v[184:187], v[4:7]
	v_mfma_f32_16x16x32_bf16 v[0:3], v[204:207], v[184:187], v[0:3]
	v_mfma_f32_16x16x32_bf16 v[130:133], v[108:111], v[76:79], v[28:31]
	v_mfma_f32_16x16x32_bf16 v[134:137], v[204:207], v[76:79], v[24:27]
	v_mfma_f32_16x16x32_bf16 v[150:153], v[108:111], v[176:179], v[12:15]
	v_mfma_f32_16x16x32_bf16 v[154:157], v[204:207], v[176:179], v[8:11]
	s_setprio 0
	s_barrier
	s_nop 0
	ds_read_b128 v[8:11], v147
	ds_read_b128 v[12:15], v147 offset:1024
	ds_read_b128 v[170:173], v147 offset:2048
	ds_read_b128 v[176:179], v147 offset:3072
	ds_read_b128 v[24:27], v142 offset:32768
	ds_read_b128 v[28:31], v142 offset:33792
	ds_read_b128 v[40:43], v143 offset:32768
	ds_read_b128 v[44:47], v143 offset:33792
	ds_read_b128 v[180:183], v144 offset:32768
	ds_read_b128 v[184:187], v144 offset:33792
	ds_read_b128 v[200:203], v145 offset:32768
	ds_read_b128 v[204:207], v145 offset:33792
	s_waitcnt vmcnt(2)
	s_barrier
	s_setprio 1
	s_waitcnt lgkmcnt(7)
	v_mfma_f32_16x16x32_bf16 v[72:75], v[8:11], v[24:27], v[124:127]
	s_waitcnt lgkmcnt(6)
	v_mfma_f32_16x16x32_bf16 v[124:127], v[12:15], v[28:31], v[72:75]
	v_mfma_f32_16x16x32_bf16 v[72:75], v[170:173], v[24:27], v[120:123]
	v_mfma_f32_16x16x32_bf16 v[120:123], v[176:179], v[28:31], v[72:75]
	s_waitcnt lgkmcnt(5)
	v_mfma_f32_16x16x32_bf16 v[72:75], v[8:11], v[40:43], v[116:119]
	s_waitcnt lgkmcnt(4)
	v_mfma_f32_16x16x32_bf16 v[108:111], v[12:15], v[44:47], v[72:75]
	v_mfma_f32_16x16x32_bf16 v[72:75], v[170:173], v[40:43], v[112:115]
	v_mfma_f32_16x16x32_bf16 v[104:107], v[176:179], v[44:47], v[72:75]
	s_waitcnt lgkmcnt(3)
	v_mfma_f32_16x16x32_bf16 v[72:75], v[8:11], v[180:183], v[192:195]
	s_waitcnt lgkmcnt(2)
	v_mfma_f32_16x16x32_bf16 v[92:95], v[12:15], v[184:187], v[72:75]
	v_mfma_f32_16x16x32_bf16 v[72:75], v[170:173], v[180:183], v[196:199]
	v_mfma_f32_16x16x32_bf16 v[88:91], v[176:179], v[184:187], v[72:75]
	s_waitcnt lgkmcnt(1)
	v_mfma_f32_16x16x32_bf16 v[72:75], v[8:11], v[200:203], v[100:103]
	s_waitcnt lgkmcnt(0)
	v_mfma_f32_16x16x32_bf16 v[76:79], v[12:15], v[204:207], v[72:75]
	v_mfma_f32_16x16x32_bf16 v[72:75], v[170:173], v[200:203], v[96:99]
	v_mfma_f32_16x16x32_bf16 v[72:75], v[176:179], v[204:207], v[72:75]
	s_setprio 0
	s_barrier
; #define LDA(dst, b, h)                                                                                               \
;   _Pragma("unroll") for (int m = 0; m < 4; ++m) _Pragma("unroll") for (int k = 0; k < 2; ++k) dst[m][k] =            \
;       *reinterpret_cast<const bf16x8*>(SA(b, h) + lds_byte(wr * 64 + m * 16 + fr, k * 32 + fq * 8))
; #define LDB(dst, b, h)                                                                                               \
;   _Pragma("unroll") for (int n = 0; n < 2; ++n) _Pragma("unroll") for (int k = 0; k < 2; ++k) dst[n][k] =            \
;       *reinterpret_cast<const bf16x8*>(SB(b, h) + lds_byte(wc * 32 + n * 16 + fr, k * 32 + fq * 8))
; #define WAIT_V(n) asm volatile("s_waitcnt vmcnt(" #n ")" ::: "memory")
; #define WAIT_L(n) asm volatile("s_waitcnt lgkmcnt(" #n ")" ::: "memory")
; #define BAR __builtin_amdgcn_s_barrier()
; template <int EPI>
; __device__ __forceinline__ void gemm_phase(const u16* __restrict__ A, const u16* __restrict__ Bt, const int K,
;                                            const int nN, char* shm, const EpiArgs& ea) {
;     ...
;       LDB(B0, 1, 0); LDA(At, 1, 0); WAIT_V(2); BAR; WAIT_L(0); MMA(0, 0, At, B0); BAR;
;       LDB(B1, 1, 1); WAIT_V(0); BAR; WAIT_L(0); MMA(0, 1, At, B1); BAR;
;       LDA(At, 1, 1); BAR; WAIT_L(0); MMA(1, 0, At, B0); MMA(1, 1, At, B1); BAR;
;     }
;     if (wr == 0) BAR;
	ds_read_b128 v[192:195], v148
	ds_read_b128 v[196:199], v148 offset:1024
	ds_read_b128 v[216:219], v148 offset:2048
	ds_read_b128 v[220:223], v148 offset:3072
	s_waitcnt vmcnt(0)
	s_barrier
	s_setprio 1
	s_waitcnt lgkmcnt(3)
	v_mfma_f32_16x16x32_bf16 v[96:99], v[192:195], v[24:27], v[208:211]
	s_waitcnt lgkmcnt(1)
	v_mfma_f32_16x16x32_bf16 v[24:27], v[216:219], v[24:27], v[158:161]
	s_waitcnt lgkmcnt(0)
	v_mfma_f32_16x16x32_bf16 v[112:115], v[220:223], v[28:31], v[24:27]
	v_mfma_f32_16x16x32_bf16 v[24:27], v[192:195], v[40:43], v[84:87]
	v_mfma_f32_16x16x32_bf16 v[100:103], v[196:199], v[44:47], v[24:27]
	v_mfma_f32_16x16x32_bf16 v[24:27], v[216:219], v[40:43], v[80:83]
	v_mfma_f32_16x16x32_bf16 v[116:119], v[196:199], v[28:31], v[96:99]
	v_mfma_f32_16x16x32_bf16 v[96:99], v[220:223], v[44:47], v[24:27]
	v_mfma_f32_16x16x32_bf16 v[24:27], v[192:195], v[180:183], v[162:165]
	v_mfma_f32_16x16x32_bf16 v[84:87], v[196:199], v[184:187], v[24:27]
	v_mfma_f32_16x16x32_bf16 v[24:27], v[216:219], v[180:183], v[166:169]
	v_mfma_f32_16x16x32_bf16 v[80:83], v[220:223], v[184:187], v[24:27]
	v_mfma_f32_16x16x32_bf16 v[24:27], v[192:195], v[200:203], v[68:71]
	v_mfma_f32_16x16x32_bf16 v[68:71], v[196:199], v[204:207], v[24:27]
	v_mfma_f32_16x16x32_bf16 v[24:27], v[216:219], v[200:203], v[64:67]
	v_mfma_f32_16x16x32_bf16 v[64:67], v[220:223], v[204:207], v[24:27]
	s_setprio 0
	s_barrier
	ds_read_b128 v[158:161], v142 offset:49152
	ds_read_b128 v[162:165], v142 offset:50176
	ds_read_b128 v[166:169], v143 offset:49152
	ds_read_b128 v[180:183], v143 offset:50176
	ds_read_b128 v[184:187], v144 offset:49152
	ds_read_b128 v[200:203], v144 offset:50176
	ds_read_b128 v[204:207], v145 offset:49152
	ds_read_b128 v[208:211], v145 offset:50176
	s_barrier
	s_setprio 1
	s_waitcnt lgkmcnt(7)
	v_mfma_f32_16x16x32_bf16 v[24:27], v[8:11], v[158:161], v[60:63]
	s_waitcnt lgkmcnt(6)
	v_mfma_f32_16x16x32_bf16 v[60:63], v[12:15], v[162:165], v[24:27]
	v_mfma_f32_16x16x32_bf16 v[24:27], v[170:173], v[158:161], v[56:59]
	v_mfma_f32_16x16x32_bf16 v[56:59], v[176:179], v[162:165], v[24:27]
	s_waitcnt lgkmcnt(5)
	v_mfma_f32_16x16x32_bf16 v[24:27], v[8:11], v[166:169], v[52:55]
	s_waitcnt lgkmcnt(4)
	v_mfma_f32_16x16x32_bf16 v[44:47], v[12:15], v[180:183], v[24:27]
	v_mfma_f32_16x16x32_bf16 v[24:27], v[170:173], v[166:169], v[48:51]
	v_mfma_f32_16x16x32_bf16 v[40:43], v[176:179], v[180:183], v[24:27]
	s_waitcnt lgkmcnt(3)
	v_mfma_f32_16x16x32_bf16 v[24:27], v[8:11], v[184:187], v[188:191]
	s_waitcnt lgkmcnt(1)
	v_mfma_f32_16x16x32_bf16 v[8:11], v[8:11], v[204:207], v[36:39]
	v_mfma_f32_16x16x32_bf16 v[28:31], v[12:15], v[200:203], v[24:27]
	v_mfma_f32_16x16x32_bf16 v[24:27], v[170:173], v[184:187], v[212:215]
	s_waitcnt lgkmcnt(0)
	v_mfma_f32_16x16x32_bf16 v[12:15], v[12:15], v[208:211], v[8:11]
	v_mfma_f32_16x16x32_bf16 v[8:11], v[170:173], v[204:207], v[32:35]
	v_mfma_f32_16x16x32_bf16 v[24:27], v[176:179], v[200:203], v[24:27]
	v_mfma_f32_16x16x32_bf16 v[8:11], v[176:179], v[208:211], v[8:11]
	s_setprio 0
	s_setprio 1
	v_mfma_f32_16x16x32_bf16 v[32:35], v[192:195], v[158:161], v[130:133]
	v_mfma_f32_16x16x32_bf16 v[52:55], v[196:199], v[162:165], v[32:35]
	v_mfma_f32_16x16x32_bf16 v[32:35], v[216:219], v[158:161], v[134:137]
	v_mfma_f32_16x16x32_bf16 v[16:19], v[216:219], v[166:169], v[16:19]
	v_mfma_f32_16x16x32_bf16 v[48:51], v[220:223], v[162:165], v[32:35]
	v_mfma_f32_16x16x32_bf16 v[20:23], v[192:195], v[166:169], v[20:23]
	v_mfma_f32_16x16x32_bf16 v[32:35], v[220:223], v[180:183], v[16:19]
	v_mfma_f32_16x16x32_bf16 v[16:19], v[192:195], v[184:187], v[150:153]
	v_mfma_f32_16x16x32_bf16 v[36:39], v[196:199], v[180:183], v[20:23]
	v_mfma_f32_16x16x32_bf16 v[20:23], v[196:199], v[200:203], v[16:19]
	v_mfma_f32_16x16x32_bf16 v[16:19], v[216:219], v[184:187], v[154:157]
	v_mfma_f32_16x16x32_bf16 v[4:7], v[192:195], v[204:207], v[4:7]
	v_mfma_f32_16x16x32_bf16 v[0:3], v[216:219], v[204:207], v[0:3]
	v_mfma_f32_16x16x32_bf16 v[16:19], v[220:223], v[200:203], v[16:19]
	v_mfma_f32_16x16x32_bf16 v[4:7], v[196:199], v[208:211], v[4:7]
	v_mfma_f32_16x16x32_bf16 v[0:3], v[220:223], v[208:211], v[0:3]
	s_setprio 0
	s_andn2_b64 vcc, exec, s[14:15]
	s_barrier
	s_cbranch_vccnz .LBB0_634
	s_barrier
